# weight transposes' f32 row loads and bf16 stores marked non-temporal (read-once / consumed phases later)
# baseline (speedup 1.0000x reference)
; #define LAS __attribute__((address_space(3)))
; __device__ __forceinline__ void transpose_item(const float* W, int ldw, int K, bf16_t* WT, int nblk, LAS float* scr, int item, int lane) {
;     const int kb = item / nblk, nb = item % nblk, k0 = 64 * kb, n0 = 64 * nb;
;     f32x4 v[16];
; #pragma unroll
;     for (int i = 0; i < 16; ++i) v[i] = *(const f32x4*)(W + (size_t)(k0 + (lane >> 4) + 4 * i) * ldw + n0 + (lane & 15) * 4);
; #pragma unroll
;     for (int i = 0; i < 16; ++i) { LAS float* d = scr + ((lane >> 4) + 4 * i) * 65 + (lane & 15) * 4; d[0] = v[i][0]; d[1] = v[i][1]; d[2] = v[i][2]; d[3] = v[i][3]; }
; __device__ __forceinline__ void transpose_range(const Params& p, LAS unsigned char* lds, int l, int lo, int hi, int gw, int NGW, int wave, int lane) {
;     ...
;         transpose_item(p.ffn_down + (size_t)l * DFF * DM, DM, DFF, (bf16_t*)(ws + WS_WDN + l * SZ_WDN), DM / 64, scr, r, lane);
.LBB0_462:
	v_cmp_lt_i32_e32 vcc, s29, v20
	s_and_saveexec_b64 s[6:7], vcc
	s_xor_b64 s[6:7], exec, s[6:7]
	s_cbranch_execz .LBB0_472
	v_cmp_lt_u32_e32 vcc, s25, v20
	s_and_saveexec_b64 s[8:9], vcc
	s_xor_b64 s[12:13], exec, s[8:9]
	s_cbranch_execz .LBB0_469
	v_cmp_lt_u32_e32 vcc, s31, v20
	s_and_saveexec_b64 s[8:9], vcc
	s_xor_b64 s[14:15], exec, s[8:9]
	s_cbranch_execz .LBB0_466
	v_and_b32_e32 v16, 0x7fffffc0, v33
	v_add_u32_e32 v16, 0xffffbc00, v16
	v_and_b32_e32 v18, 0x7c0, v32
	v_or_b32_e32 v94, v16, v21
	v_lshlrev_b32_e32 v182, 2, v18
	v_lshl_add_u64 v[96:97], v[8:9], 0, v[182:183]
	v_mov_b32_e32 v95, v183
	v_or_b32_e32 v182, 4, v94
	v_lshlrev_b64 v[34:35], 13, v[94:95]
	v_lshlrev_b64 v[38:39], 13, v[182:183]
	v_lshl_add_u64 v[34:35], v[96:97], 0, v[34:35]
	v_lshl_add_u64 v[38:39], v[96:97], 0, v[38:39]
	v_or_b32_e32 v182, 8, v94
	global_load_dwordx4 v[34:37], v[34:35], off nt
	v_lshlrev_b64 v[42:43], 13, v[182:183]
	global_load_dwordx4 v[38:41], v[38:39], off nt
	v_lshl_add_u64 v[42:43], v[96:97], 0, v[42:43]
	v_or_b32_e32 v182, 12, v94
	global_load_dwordx4 v[42:45], v[42:43], off nt
	v_lshlrev_b64 v[46:47], 13, v[182:183]
	v_lshl_add_u64 v[46:47], v[96:97], 0, v[46:47]
	v_or_b32_e32 v182, 16, v94
	global_load_dwordx4 v[46:49], v[46:47], off nt
	v_lshlrev_b64 v[50:51], 13, v[182:183]
	v_lshl_add_u64 v[50:51], v[96:97], 0, v[50:51]
	v_or_b32_e32 v182, 20, v94
	global_load_dwordx4 v[50:53], v[50:51], off nt
	v_lshlrev_b64 v[54:55], 13, v[182:183]
	v_lshl_add_u64 v[54:55], v[96:97], 0, v[54:55]
	v_or_b32_e32 v182, 24, v94
	global_load_dwordx4 v[54:57], v[54:55], off nt
	v_lshlrev_b64 v[58:59], 13, v[182:183]
	v_lshl_add_u64 v[58:59], v[96:97], 0, v[58:59]
	v_or_b32_e32 v182, 28, v94
	global_load_dwordx4 v[58:61], v[58:59], off nt
	v_lshlrev_b64 v[62:63], 13, v[182:183]
	v_lshl_add_u64 v[62:63], v[96:97], 0, v[62:63]
	v_or_b32_e32 v182, 32, v94
	global_load_dwordx4 v[62:65], v[62:63], off nt
	v_lshlrev_b64 v[66:67], 13, v[182:183]
	v_lshl_add_u64 v[66:67], v[96:97], 0, v[66:67]
	v_or_b32_e32 v182, 36, v94
	global_load_dwordx4 v[66:69], v[66:67], off nt
	v_lshlrev_b64 v[70:71], 13, v[182:183]
	v_lshl_add_u64 v[70:71], v[96:97], 0, v[70:71]
	v_or_b32_e32 v182, 40, v94
	global_load_dwordx4 v[70:73], v[70:71], off nt
	v_lshlrev_b64 v[74:75], 13, v[182:183]
	v_lshl_add_u64 v[74:75], v[96:97], 0, v[74:75]
	v_or_b32_e32 v182, 44, v94
	global_load_dwordx4 v[74:77], v[74:75], off nt
	v_lshlrev_b64 v[78:79], 13, v[182:183]
	v_lshl_add_u64 v[78:79], v[96:97], 0, v[78:79]
	v_or_b32_e32 v182, 48, v94
	global_load_dwordx4 v[78:81], v[78:79], off nt
	v_lshlrev_b64 v[82:83], 13, v[182:183]
	v_lshl_add_u64 v[82:83], v[96:97], 0, v[82:83]
	v_or_b32_e32 v182, 52, v94
	global_load_dwordx4 v[82:85], v[82:83], off nt
	v_lshlrev_b64 v[86:87], 13, v[182:183]
	v_lshl_add_u64 v[86:87], v[96:97], 0, v[86:87]
	v_or_b32_e32 v182, 56, v94
	global_load_dwordx4 v[86:89], v[86:87], off nt
	v_lshlrev_b64 v[90:91], 13, v[182:183]
	v_lshl_add_u64 v[90:91], v[96:97], 0, v[90:91]
	v_or_b32_e32 v182, 60, v94
	global_load_dwordx4 v[90:93], v[90:91], off nt
	v_lshlrev_b64 v[94:95], 13, v[182:183]
	v_lshl_add_u64 v[94:95], v[96:97], 0, v[94:95]
	global_load_dwordx4 v[94:97], v[94:95], off nt
	v_add_u32_e32 v17, 0x410, v22
	v_add_u32_e32 v19, 0x400, v24
	s_waitcnt vmcnt(15)
	ds_write2_b32 v22, v34, v35 offset1:1
	ds_write2_b32 v22, v36, v37 offset0:2 offset1:3
	s_waitcnt vmcnt(14)
	ds_write2_b32 v17, v38, v39 offset1:1
	v_add_u32_e32 v17, 0x418, v22
	ds_write2_b32 v17, v40, v41 offset1:1
	v_add_u32_e32 v17, 0x820, v22
	s_waitcnt vmcnt(13)
	ds_write2_b32 v17, v42, v43 offset1:1
	v_add_u32_e32 v17, 0x828, v22
	ds_write2_b32 v17, v44, v45 offset1:1
	v_add_u32_e32 v17, 0xc30, v22
	s_waitcnt vmcnt(12)
	ds_write2_b32 v17, v46, v47 offset1:1
	v_add_u32_e32 v17, 0xc38, v22
	ds_write2_b32 v17, v48, v49 offset1:1
	v_add_u32_e32 v17, 0x1040, v22
	s_waitcnt vmcnt(11)
	ds_write2_b32 v17, v50, v51 offset1:1
	v_add_u32_e32 v17, 0x1048, v22
	ds_write2_b32 v17, v52, v53 offset1:1
	v_add_u32_e32 v17, 0x1450, v22
	s_waitcnt vmcnt(10)
	ds_write2_b32 v17, v54, v55 offset1:1
	v_add_u32_e32 v17, 0x1458, v22
	ds_write2_b32 v17, v56, v57 offset1:1
	v_add_u32_e32 v17, 0x1860, v22
	s_waitcnt vmcnt(9)
	ds_write2_b32 v17, v58, v59 offset1:1
	v_add_u32_e32 v17, 0x1868, v22
	ds_write2_b32 v17, v60, v61 offset1:1
	v_add_u32_e32 v17, 0x1c70, v22
	s_waitcnt vmcnt(8)
	ds_write2_b32 v17, v62, v63 offset1:1
	v_add_u32_e32 v17, 0x1c78, v22
	ds_write2_b32 v17, v64, v65 offset1:1
	v_add_u32_e32 v17, 0x2080, v22
	s_waitcnt vmcnt(7)
	ds_write2_b32 v17, v66, v67 offset1:1
	v_add_u32_e32 v17, 0x2088, v22
	ds_write2_b32 v17, v68, v69 offset1:1
	v_add_u32_e32 v17, 0x2490, v22
	s_waitcnt vmcnt(6)
	ds_write2_b32 v17, v70, v71 offset1:1
	v_add_u32_e32 v17, 0x2498, v22
	ds_write2_b32 v17, v72, v73 offset1:1
	v_add_u32_e32 v17, 0x28a0, v22
	s_waitcnt vmcnt(5)
	ds_write2_b32 v17, v74, v75 offset1:1
	v_add_u32_e32 v17, 0x28a8, v22
	ds_write2_b32 v17, v76, v77 offset1:1
	v_add_u32_e32 v17, 0x2cb0, v22
	s_waitcnt vmcnt(4)
	ds_write2_b32 v17, v78, v79 offset1:1
	v_add_u32_e32 v17, 0x2cb8, v22
	ds_write2_b32 v17, v80, v81 offset1:1
	v_add_u32_e32 v17, 0x30c0, v22
	s_waitcnt vmcnt(3)
	ds_write2_b32 v17, v82, v83 offset1:1
	v_add_u32_e32 v17, 0x30c8, v22
	ds_write2_b32 v17, v84, v85 offset1:1
	v_add_u32_e32 v17, 0x34d0, v22
	s_waitcnt vmcnt(2)
	ds_write2_b32 v17, v86, v87 offset1:1
	v_add_u32_e32 v17, 0x34d8, v22
	ds_write2_b32 v17, v88, v89 offset1:1
	v_add_u32_e32 v17, 0x38e0, v22
	s_waitcnt vmcnt(1)
	ds_write2_b32 v17, v90, v91 offset1:1
	v_add_u32_e32 v17, 0x38e8, v22
	ds_write2_b32 v17, v92, v93 offset1:1
	v_add_u32_e32 v17, 0x3cf0, v22
	s_waitcnt vmcnt(0)
; #define LAS __attribute__((address_space(3)))
; __device__ __forceinline__ unsigned pk2(float lo, float hi) { const f32x2 v = {lo, hi}; const hwbf16x2 b = __builtin_convertvector(v, hwbf16x2); return __builtin_bit_cast(unsigned, b); }
; #define LDS_WAIT() asm volatile("s_waitcnt lgkmcnt(0)" ::: "memory")
; __device__ __forceinline__ void transpose_item(const float* W, int ldw, int K, bf16_t* WT, int nblk, LAS float* scr, int item, int lane) {
;     ...
;     for (int i = 0; i < 16; ++i) { LAS float* d = scr + ((lane >> 4) + 4 * i) * 65 + (lane & 15) * 4; d[0] = v[i][0]; d[1] = v[i][1]; d[2] = v[i][2]; d[3] = v[i][3]; }
;     LDS_WAIT();
;     const int c = lane & 7;
; #pragma unroll
;     for (int j = 0; j < 8; ++j) { const int n = (lane >> 3) + 8 * j; const LAS float* s = scr + (8 * c) * 65 + n;
;         u32x4 o; o.x = pk2(s[0 * 65], s[1 * 65]); o.y = pk2(s[2 * 65], s[3 * 65]); o.z = pk2(s[4 * 65], s[5 * 65]); o.w = pk2(s[6 * 65], s[7 * 65]);
;         *(u32x4*)(WT + (size_t)(n0 + n) * K + k0 + 8 * c) = o; }
;     LDS_WAIT();
	ds_write2_b32 v17, v94, v95 offset1:1
	v_add_u32_e32 v17, 0x3cf8, v22
	ds_write2_b32 v17, v96, v97 offset1:1
	s_waitcnt lgkmcnt(0)
	ds_read2_b32 v[38:39], v24 offset0:65 offset1:73
	ds_read2_b32 v[40:41], v24 offset1:8
	ds_read2_b32 v[42:43], v24 offset0:130 offset1:138
	ds_read2_b32 v[44:45], v24 offset0:195 offset1:203
	ds_read2_b32 v[46:47], v19 offset0:4 offset1:12
	ds_read2_b32 v[48:49], v19 offset0:69 offset1:77
	ds_read2_b32 v[50:51], v19 offset0:134 offset1:142
	ds_read2_b32 v[52:53], v19 offset0:199 offset1:207
	v_mov_b32_e32 v17, v183
	s_waitcnt lgkmcnt(6)
	v_cvt_pk_bf16_f32 v34, v40, v38
	v_or_b32_e32 v38, v18, v23
	v_mul_u32_u24_e32 v38, 0x1600, v38
	v_lshlrev_b32_e32 v182, 1, v38
	v_or_b32_e32 v38, v18, v25
	v_lshl_add_u64 v[16:17], v[16:17], 1, v[0:1]
	v_mul_u32_u24_e32 v38, 0x1600, v38
	s_waitcnt lgkmcnt(4)
	v_cvt_pk_bf16_f32 v35, v42, v44
	s_waitcnt lgkmcnt(2)
	v_cvt_pk_bf16_f32 v36, v46, v48
	s_waitcnt lgkmcnt(0)
	v_cvt_pk_bf16_f32 v37, v50, v52
	v_lshl_add_u64 v[54:55], v[16:17], 0, v[182:183]
	v_lshlrev_b32_e32 v182, 1, v38
	global_store_dwordx4 v[54:55], v[34:37], off nt
	s_nop 1
	v_cvt_pk_bf16_f32 v34, v41, v39
	v_cvt_pk_bf16_f32 v35, v43, v45
	v_cvt_pk_bf16_f32 v36, v47, v49
	v_cvt_pk_bf16_f32 v37, v51, v53
	v_lshl_add_u64 v[38:39], v[16:17], 0, v[182:183]
	global_store_dwordx4 v[38:39], v[34:37], off nt
	ds_read2_b32 v[38:39], v24 offset0:16 offset1:24
	ds_read2_b32 v[40:41], v24 offset0:81 offset1:89
	ds_read2_b32 v[42:43], v24 offset0:146 offset1:154
	ds_read2_b32 v[44:45], v24 offset0:211 offset1:219
	ds_read2_b32 v[46:47], v19 offset0:20 offset1:28
	ds_read2_b32 v[48:49], v19 offset0:85 offset1:93
	ds_read2_b32 v[50:51], v19 offset0:150 offset1:158
	ds_read2_b32 v[52:53], v19 offset0:215 offset1:223
	s_waitcnt lgkmcnt(6)
	v_cvt_pk_bf16_f32 v34, v38, v40
	v_or_b32_e32 v38, v18, v26
	v_mul_u32_u24_e32 v38, 0x1600, v38
	v_lshlrev_b32_e32 v182, 1, v38
	v_or_b32_e32 v38, v18, v27
	v_mul_u32_u24_e32 v38, 0x1600, v38
	s_waitcnt lgkmcnt(4)
	v_cvt_pk_bf16_f32 v35, v42, v44
	s_waitcnt lgkmcnt(2)
	v_cvt_pk_bf16_f32 v36, v46, v48
	s_waitcnt lgkmcnt(0)
	v_cvt_pk_bf16_f32 v37, v50, v52
	v_lshl_add_u64 v[54:55], v[16:17], 0, v[182:183]
	v_lshlrev_b32_e32 v182, 1, v38
	global_store_dwordx4 v[54:55], v[34:37], off nt
	s_nop 1
	v_cvt_pk_bf16_f32 v34, v39, v41
	v_cvt_pk_bf16_f32 v35, v43, v45
	v_cvt_pk_bf16_f32 v36, v47, v49
	v_cvt_pk_bf16_f32 v37, v51, v53
	v_lshl_add_u64 v[38:39], v[16:17], 0, v[182:183]
	global_store_dwordx4 v[38:39], v[34:37], off nt
	ds_read2_b32 v[38:39], v24 offset0:32 offset1:40
	ds_read2_b32 v[40:41], v24 offset0:97 offset1:105
	ds_read2_b32 v[42:43], v24 offset0:162 offset1:170
	ds_read2_b32 v[44:45], v24 offset0:227 offset1:235
	ds_read2_b32 v[46:47], v19 offset0:36 offset1:44
	ds_read2_b32 v[48:49], v19 offset0:101 offset1:109
	ds_read2_b32 v[50:51], v19 offset0:166 offset1:174
	ds_read2_b32 v[52:53], v19 offset0:231 offset1:239
	s_waitcnt lgkmcnt(6)
	v_cvt_pk_bf16_f32 v34, v38, v40
	v_or_b32_e32 v38, v18, v28
	v_mul_u32_u24_e32 v38, 0x1600, v38
	v_lshlrev_b32_e32 v182, 1, v38
	v_or_b32_e32 v38, v18, v29
	v_mul_u32_u24_e32 v38, 0x1600, v38
	s_waitcnt lgkmcnt(4)
	v_cvt_pk_bf16_f32 v35, v42, v44
	s_waitcnt lgkmcnt(2)
	v_cvt_pk_bf16_f32 v36, v46, v48
	s_waitcnt lgkmcnt(0)
	v_cvt_pk_bf16_f32 v37, v50, v52
	v_lshl_add_u64 v[54:55], v[16:17], 0, v[182:183]
	v_lshlrev_b32_e32 v182, 1, v38
	global_store_dwordx4 v[54:55], v[34:37], off nt
	s_nop 1
	v_cvt_pk_bf16_f32 v34, v39, v41
	v_cvt_pk_bf16_f32 v35, v43, v45
	v_cvt_pk_bf16_f32 v36, v47, v49
	v_cvt_pk_bf16_f32 v37, v51, v53
	v_lshl_add_u64 v[38:39], v[16:17], 0, v[182:183]
	global_store_dwordx4 v[38:39], v[34:37], off nt
	ds_read2_b32 v[38:39], v24 offset0:48 offset1:56
	ds_read2_b32 v[40:41], v24 offset0:113 offset1:121
	ds_read2_b32 v[42:43], v24 offset0:178 offset1:186
	ds_read2_b32 v[44:45], v24 offset0:243 offset1:251
	ds_read2_b32 v[46:47], v19 offset0:52 offset1:60
	ds_read2_b32 v[48:49], v19 offset0:117 offset1:125
	ds_read2_b32 v[50:51], v19 offset0:182 offset1:190
	ds_read2_b32 v[52:53], v19 offset0:247 offset1:255
	v_or_b32_e32 v19, v18, v30
	v_mul_u32_u24_e32 v19, 0x1600, v19
	v_or_b32_e32 v18, v18, v31
	v_lshlrev_b32_e32 v182, 1, v19
	v_mul_u32_u24_e32 v18, 0x1600, v18
	s_waitcnt lgkmcnt(6)
	v_cvt_pk_bf16_f32 v34, v38, v40
	s_waitcnt lgkmcnt(4)
	v_cvt_pk_bf16_f32 v35, v42, v44
	s_waitcnt lgkmcnt(2)
	v_cvt_pk_bf16_f32 v36, v46, v48
	s_waitcnt lgkmcnt(0)
	v_cvt_pk_bf16_f32 v37, v50, v52
	v_lshl_add_u64 v[54:55], v[16:17], 0, v[182:183]
	v_lshlrev_b32_e32 v182, 1, v18
	global_store_dwordx4 v[54:55], v[34:37], off nt
	v_lshl_add_u64 v[16:17], v[16:17], 0, v[182:183]
	s_nop 0
	v_cvt_pk_bf16_f32 v34, v39, v41
	v_cvt_pk_bf16_f32 v35, v43, v45
	v_cvt_pk_bf16_f32 v36, v47, v49
	v_cvt_pk_bf16_f32 v37, v51, v53
	global_store_dwordx4 v[16:17], v[34:37], off nt
	s_waitcnt lgkmcnt(0)
; #define LAS __attribute__((address_space(3)))
; __device__ __forceinline__ void transpose_item(const float* W, int ldw, int K, bf16_t* WT, int nblk, LAS float* scr, int item, int lane) {
;     ...
;     for (int i = 0; i < 16; ++i) v[i] = *(const f32x4*)(W + (size_t)(k0 + (lane >> 4) + 4 * i) * ldw + n0 + (lane & 15) * 4);
; #pragma unroll
;     for (int i = 0; i < 16; ++i) { LAS float* d = scr + ((lane >> 4) + 4 * i) * 65 + (lane & 15) * 4; d[0] = v[i][0]; d[1] = v[i][1]; d[2] = v[i][2]; d[3] = v[i][3]; }
.LBB0_466:
	s_andn2_saveexec_b64 s[8:9], s[14:15]
	s_cbranch_execz .LBB0_468
	v_add_u16_e32 v16, 0xf400, v20
	v_mul_u32_u24_e32 v17, 0xba2f, v16
	v_lshrrev_b32_e32 v17, 23, v17
	v_mul_lo_u16_e32 v18, 0xb0, v17
	v_sub_u16_e32 v16, v16, v18
	v_lshlrev_b16_e32 v94, 6, v17
	v_lshlrev_b16_e32 v95, 6, v16
	v_or_b32_e32 v18, v21, v94
	v_lshlrev_b32_e32 v182, 2, v95
	v_mul_u32_u24_e32 v18, 0x2c00, v18
	v_lshl_add_u64 v[16:17], v[10:11], 0, v[182:183]
	v_lshlrev_b32_e32 v182, 2, v18
	v_lshl_add_u64 v[90:91], v[16:17], 0, v[182:183]
	v_add_co_u32_e32 v34, vcc, s58, v90
	s_mov_b32 s10, 0x18c000
	s_nop 0
	v_addc_co_u32_e32 v35, vcc, 0, v91, vcc
	v_add_co_u32_e32 v38, vcc, s28, v90
	global_load_dwordx4 v[16:19], v[90:91], off nt
	s_nop 0
	global_load_dwordx4 v[34:37], v[34:35], off nt
	v_addc_co_u32_e32 v39, vcc, 0, v91, vcc
	v_add_co_u32_e32 v42, vcc, s59, v90
	v_lshlrev_b32_e32 v182, 1, v94
	s_nop 0
	v_addc_co_u32_e32 v43, vcc, 0, v91, vcc
	global_load_dwordx4 v[38:41], v[38:39], off nt
	s_nop 0
	global_load_dwordx4 v[42:45], v[42:43], off nt
	v_add_co_u32_e32 v46, vcc, s64, v90
	s_nop 1
	v_addc_co_u32_e32 v47, vcc, 0, v91, vcc
	v_add_co_u32_e32 v50, vcc, s65, v90
	s_nop 1
	v_addc_co_u32_e32 v51, vcc, 0, v91, vcc
	global_load_dwordx4 v[46:49], v[46:47], off nt
	s_nop 0
	global_load_dwordx4 v[50:53], v[50:51], off nt
	v_add_co_u32_e32 v54, vcc, s66, v90
	s_nop 1
	v_addc_co_u32_e32 v55, vcc, 0, v91, vcc
	v_add_co_u32_e32 v58, vcc, s68, v90
	s_nop 1
	v_addc_co_u32_e32 v59, vcc, 0, v91, vcc
	global_load_dwordx4 v[54:57], v[54:55], off nt
	s_nop 0
	global_load_dwordx4 v[58:61], v[58:59], off nt
	v_add_co_u32_e32 v62, vcc, s69, v90
	s_nop 1
	v_addc_co_u32_e32 v63, vcc, 0, v91, vcc
	v_add_co_u32_e32 v66, vcc, s10, v90
	s_mov_b32 s10, 0x1b8000
	s_nop 0
	v_addc_co_u32_e32 v67, vcc, 0, v91, vcc
	global_load_dwordx4 v[62:65], v[62:63], off nt
	s_nop 0
	global_load_dwordx4 v[66:69], v[66:67], off nt
	v_add_co_u32_e32 v70, vcc, s10, v90
	s_mov_b32 s10, 0x1e4000
	s_nop 0
	v_addc_co_u32_e32 v71, vcc, 0, v91, vcc
	v_add_co_u32_e32 v74, vcc, s10, v90
	s_mov_b32 s10, 0x210000
	s_nop 0
	v_addc_co_u32_e32 v75, vcc, 0, v91, vcc
	global_load_dwordx4 v[70:73], v[70:71], off nt
	s_nop 0
	global_load_dwordx4 v[74:77], v[74:75], off nt
	v_add_co_u32_e32 v78, vcc, s10, v90
	s_mov_b32 s10, 0x23c000
	s_nop 0
	v_addc_co_u32_e32 v79, vcc, 0, v91, vcc
	v_add_co_u32_e32 v82, vcc, s10, v90
	s_mov_b32 s10, 0x268000
	s_nop 0
	v_addc_co_u32_e32 v83, vcc, 0, v91, vcc
	global_load_dwordx4 v[78:81], v[78:79], off nt
	s_nop 0
	global_load_dwordx4 v[82:85], v[82:83], off nt
	v_add_co_u32_e32 v86, vcc, s10, v90
	s_mov_b32 s10, 0x294000
	s_nop 0
	v_addc_co_u32_e32 v87, vcc, 0, v91, vcc
	global_load_dwordx4 v[86:89], v[86:87], off nt
	v_add_co_u32_e32 v90, vcc, s10, v90
	s_nop 1
	v_addc_co_u32_e32 v91, vcc, 0, v91, vcc
	global_load_dwordx4 v[90:93], v[90:91], off nt
	s_waitcnt vmcnt(15)
	ds_write2_b32 v22, v16, v17 offset1:1
	ds_write2_b32 v22, v18, v19 offset0:2 offset1:3
	v_add_u32_e32 v16, 0x410, v22
	s_waitcnt vmcnt(14)
	ds_write2_b32 v16, v34, v35 offset1:1
	v_add_u32_e32 v16, 0x418, v22
	ds_write2_b32 v16, v36, v37 offset1:1
	v_add_u32_e32 v16, 0x820, v22
	s_waitcnt vmcnt(13)
	ds_write2_b32 v16, v38, v39 offset1:1
	v_add_u32_e32 v16, 0x828, v22
	ds_write2_b32 v16, v40, v41 offset1:1
	v_add_u32_e32 v16, 0xc30, v22
	s_waitcnt vmcnt(12)
	ds_write2_b32 v16, v42, v43 offset1:1
	v_add_u32_e32 v16, 0xc38, v22
	ds_write2_b32 v16, v44, v45 offset1:1
	v_add_u32_e32 v16, 0x1040, v22
	s_waitcnt vmcnt(11)
	ds_write2_b32 v16, v46, v47 offset1:1
	v_add_u32_e32 v16, 0x1048, v22
	ds_write2_b32 v16, v48, v49 offset1:1
	v_add_u32_e32 v16, 0x1450, v22
	s_waitcnt vmcnt(10)
	ds_write2_b32 v16, v50, v51 offset1:1
	v_add_u32_e32 v16, 0x1458, v22
	ds_write2_b32 v16, v52, v53 offset1:1
	v_add_u32_e32 v16, 0x1860, v22
	v_lshl_add_u64 v[50:51], v[2:3], 0, v[182:183]
	s_waitcnt vmcnt(9)
	ds_write2_b32 v16, v54, v55 offset1:1
	v_add_u32_e32 v16, 0x1868, v22
	ds_write2_b32 v16, v56, v57 offset1:1
	v_add_u32_e32 v16, 0x1c70, v22
	s_waitcnt vmcnt(8)
	ds_write2_b32 v16, v58, v59 offset1:1
	v_add_u32_e32 v16, 0x1c78, v22
	ds_write2_b32 v16, v60, v61 offset1:1
	v_add_u32_e32 v16, 0x2080, v22
	v_add_u32_e32 v54, 0x400, v24
	s_waitcnt vmcnt(7)
	ds_write2_b32 v16, v62, v63 offset1:1
	v_add_u32_e32 v16, 0x2088, v22
	ds_write2_b32 v16, v64, v65 offset1:1
	v_add_u32_e32 v16, 0x2490, v22
	s_waitcnt vmcnt(6)
	ds_write2_b32 v16, v66, v67 offset1:1
	v_add_u32_e32 v16, 0x2498, v22
	ds_write2_b32 v16, v68, v69 offset1:1
	v_add_u32_e32 v16, 0x28a0, v22
	s_waitcnt vmcnt(5)
	ds_write2_b32 v16, v70, v71 offset1:1
	v_add_u32_e32 v16, 0x28a8, v22
	ds_write2_b32 v16, v72, v73 offset1:1
	v_add_u32_e32 v16, 0x2cb0, v22
	s_waitcnt vmcnt(4)
	ds_write2_b32 v16, v74, v75 offset1:1
	v_add_u32_e32 v16, 0x2cb8, v22
	ds_write2_b32 v16, v76, v77 offset1:1
	v_add_u32_e32 v16, 0x30c0, v22
	s_waitcnt vmcnt(3)
; #define LAS __attribute__((address_space(3)))
; __device__ __forceinline__ unsigned pk2(float lo, float hi) { const f32x2 v = {lo, hi}; const hwbf16x2 b = __builtin_convertvector(v, hwbf16x2); return __builtin_bit_cast(unsigned, b); }
; #define LDS_WAIT() asm volatile("s_waitcnt lgkmcnt(0)" ::: "memory")
; __device__ __forceinline__ void transpose_item(const float* W, int ldw, int K, bf16_t* WT, int nblk, LAS float* scr, int item, int lane) {
;     ...
;     for (int i = 0; i < 16; ++i) { LAS float* d = scr + ((lane >> 4) + 4 * i) * 65 + (lane & 15) * 4; d[0] = v[i][0]; d[1] = v[i][1]; d[2] = v[i][2]; d[3] = v[i][3]; }
;     LDS_WAIT();
;     const int c = lane & 7;
; #pragma unroll
;     for (int j = 0; j < 8; ++j) { const int n = (lane >> 3) + 8 * j; const LAS float* s = scr + (8 * c) * 65 + n;
;         u32x4 o; o.x = pk2(s[0 * 65], s[1 * 65]); o.y = pk2(s[2 * 65], s[3 * 65]); o.z = pk2(s[4 * 65], s[5 * 65]); o.w = pk2(s[6 * 65], s[7 * 65]);
;         *(u32x4*)(WT + (size_t)(n0 + n) * K + k0 + 8 * c) = o; }
;     LDS_WAIT();
	ds_write2_b32 v16, v78, v79 offset1:1
	v_add_u32_e32 v16, 0x30c8, v22
	ds_write2_b32 v16, v80, v81 offset1:1
	v_add_u32_e32 v16, 0x34d0, v22
	s_waitcnt vmcnt(2)
	ds_write2_b32 v16, v82, v83 offset1:1
	v_add_u32_e32 v16, 0x34d8, v22
	ds_write2_b32 v16, v84, v85 offset1:1
	v_add_u32_e32 v16, 0x38e0, v22
	s_waitcnt vmcnt(1)
	ds_write2_b32 v16, v86, v87 offset1:1
	v_add_u32_e32 v16, 0x38e8, v22
	ds_write2_b32 v16, v88, v89 offset1:1
	v_add_u32_e32 v16, 0x3cf0, v22
	s_waitcnt vmcnt(0)
	ds_write2_b32 v16, v90, v91 offset1:1
	v_add_u32_e32 v16, 0x3cf8, v22
	ds_write2_b32 v16, v92, v93 offset1:1
	s_waitcnt lgkmcnt(0)
	ds_read2_b32 v[34:35], v24 offset0:65 offset1:73
	ds_read2_b32 v[36:37], v24 offset1:8
	ds_read2_b32 v[38:39], v24 offset0:130 offset1:138
	ds_read2_b32 v[40:41], v24 offset0:195 offset1:203
	ds_read2_b32 v[42:43], v54 offset0:4 offset1:12
	ds_read2_b32 v[44:45], v54 offset0:69 offset1:77
	ds_read2_b32 v[46:47], v54 offset0:134 offset1:142
	ds_read2_b32 v[48:49], v54 offset0:199 offset1:207
	s_waitcnt lgkmcnt(6)
	v_cvt_pk_bf16_f32 v16, v36, v34
	v_or_b32_e32 v34, v23, v95
	v_lshlrev_b32_e32 v182, 12, v34
	s_waitcnt lgkmcnt(4)
	v_cvt_pk_bf16_f32 v17, v38, v40
	s_waitcnt lgkmcnt(2)
	v_cvt_pk_bf16_f32 v18, v42, v44
	s_waitcnt lgkmcnt(0)
	v_cvt_pk_bf16_f32 v19, v46, v48
	v_lshl_add_u64 v[52:53], v[50:51], 0, v[182:183]
	global_store_dwordx4 v[52:53], v[16:19], off nt
	v_or_b32_e32 v34, v25, v95
	v_lshlrev_b32_e32 v182, 12, v34
	v_cvt_pk_bf16_f32 v16, v37, v35
	v_cvt_pk_bf16_f32 v17, v39, v41
	v_cvt_pk_bf16_f32 v18, v43, v45
	v_cvt_pk_bf16_f32 v19, v47, v49
	ds_read2_b32 v[36:37], v24 offset0:81 offset1:89
	ds_read2_b32 v[38:39], v24 offset0:16 offset1:24
	ds_read2_b32 v[40:41], v24 offset0:146 offset1:154
	ds_read2_b32 v[42:43], v24 offset0:211 offset1:219
	ds_read2_b32 v[44:45], v54 offset0:20 offset1:28
	ds_read2_b32 v[46:47], v54 offset0:85 offset1:93
	ds_read2_b32 v[48:49], v54 offset0:150 offset1:158
	ds_read2_b32 v[52:53], v54 offset0:215 offset1:223
	v_lshl_add_u64 v[34:35], v[50:51], 0, v[182:183]
	global_store_dwordx4 v[34:35], v[16:19], off nt
	v_or_b32_e32 v34, v26, v95
	v_lshlrev_b32_e32 v182, 12, v34
	s_waitcnt lgkmcnt(6)
	v_cvt_pk_bf16_f32 v16, v38, v36
	s_waitcnt lgkmcnt(4)
	v_cvt_pk_bf16_f32 v17, v40, v42
	s_waitcnt lgkmcnt(2)
	v_cvt_pk_bf16_f32 v18, v44, v46
	s_waitcnt lgkmcnt(0)
	v_cvt_pk_bf16_f32 v19, v48, v52
	v_lshl_add_u64 v[34:35], v[50:51], 0, v[182:183]
	global_store_dwordx4 v[34:35], v[16:19], off nt
	v_or_b32_e32 v34, v27, v95
	v_lshlrev_b32_e32 v182, 12, v34
	v_cvt_pk_bf16_f32 v16, v39, v37
	v_cvt_pk_bf16_f32 v17, v41, v43
	v_cvt_pk_bf16_f32 v18, v45, v47
	v_cvt_pk_bf16_f32 v19, v49, v53
	ds_read2_b32 v[36:37], v24 offset0:32 offset1:40
	ds_read2_b32 v[38:39], v24 offset0:97 offset1:105
	ds_read2_b32 v[40:41], v24 offset0:162 offset1:170
	ds_read2_b32 v[42:43], v24 offset0:227 offset1:235
	ds_read2_b32 v[44:45], v54 offset0:36 offset1:44
	ds_read2_b32 v[46:47], v54 offset0:101 offset1:109
	ds_read2_b32 v[48:49], v54 offset0:166 offset1:174
	ds_read2_b32 v[52:53], v54 offset0:231 offset1:239
	v_lshl_add_u64 v[34:35], v[50:51], 0, v[182:183]
	global_store_dwordx4 v[34:35], v[16:19], off nt
	v_or_b32_e32 v34, v28, v95
	v_lshlrev_b32_e32 v182, 12, v34
	s_waitcnt lgkmcnt(6)
	v_cvt_pk_bf16_f32 v16, v36, v38
	s_waitcnt lgkmcnt(4)
	v_cvt_pk_bf16_f32 v17, v40, v42
	s_waitcnt lgkmcnt(2)
	v_cvt_pk_bf16_f32 v18, v44, v46
	s_waitcnt lgkmcnt(0)
	v_cvt_pk_bf16_f32 v19, v48, v52
	v_lshl_add_u64 v[34:35], v[50:51], 0, v[182:183]
	global_store_dwordx4 v[34:35], v[16:19], off nt
	v_or_b32_e32 v34, v29, v95
	v_lshlrev_b32_e32 v182, 12, v34
	v_cvt_pk_bf16_f32 v16, v37, v39
	v_cvt_pk_bf16_f32 v17, v41, v43
	v_cvt_pk_bf16_f32 v18, v45, v47
	v_cvt_pk_bf16_f32 v19, v49, v53
	ds_read2_b32 v[36:37], v24 offset0:48 offset1:56
	ds_read2_b32 v[38:39], v24 offset0:113 offset1:121
	ds_read2_b32 v[40:41], v24 offset0:178 offset1:186
	ds_read2_b32 v[42:43], v24 offset0:243 offset1:251
	ds_read2_b32 v[44:45], v54 offset0:52 offset1:60
	ds_read2_b32 v[46:47], v54 offset0:117 offset1:125
	ds_read2_b32 v[48:49], v54 offset0:182 offset1:190
	ds_read2_b32 v[52:53], v54 offset0:247 offset1:255
	v_lshl_add_u64 v[34:35], v[50:51], 0, v[182:183]
	global_store_dwordx4 v[34:35], v[16:19], off nt
	v_or_b32_e32 v34, v30, v95
	v_lshlrev_b32_e32 v182, 12, v34
	s_waitcnt lgkmcnt(6)
	v_cvt_pk_bf16_f32 v16, v36, v38
	s_waitcnt lgkmcnt(4)
	v_cvt_pk_bf16_f32 v17, v40, v42
	s_waitcnt lgkmcnt(2)
	v_cvt_pk_bf16_f32 v18, v44, v46
	s_waitcnt lgkmcnt(0)
	v_cvt_pk_bf16_f32 v19, v48, v52
	v_lshl_add_u64 v[34:35], v[50:51], 0, v[182:183]
	global_store_dwordx4 v[34:35], v[16:19], off nt
	v_or_b32_e32 v34, v31, v95
	v_lshlrev_b32_e32 v182, 12, v34
	v_cvt_pk_bf16_f32 v16, v37, v39
	v_cvt_pk_bf16_f32 v17, v41, v43
	v_cvt_pk_bf16_f32 v18, v45, v47
	v_cvt_pk_bf16_f32 v19, v49, v53
	v_lshl_add_u64 v[34:35], v[50:51], 0, v[182:183]
	global_store_dwordx4 v[34:35], v[16:19], off nt
	s_waitcnt lgkmcnt(0)

; #define LAS __attribute__((address_space(3)))
; __device__ __forceinline__ void transpose_item(const float* W, int ldw, int K, bf16_t* WT, int nblk, LAS float* scr, int item, int lane) {
;     ...
;     for (int i = 0; i < 16; ++i) v[i] = *(const f32x4*)(W + (size_t)(k0 + (lane >> 4) + 4 * i) * ldw + n0 + (lane & 15) * 4);
; #pragma unroll
;     for (int i = 0; i < 16; ++i) { LAS float* d = scr + ((lane >> 4) + 4 * i) * 65 + (lane & 15) * 4; d[0] = v[i][0]; d[1] = v[i][1]; d[2] = v[i][2]; d[3] = v[i][3]; }
.LBB0_469:
	s_andn2_saveexec_b64 s[8:9], s[12:13]
	s_cbranch_execz .LBB0_471
	v_add_u32_e32 v16, 0x1f000, v33
	v_and_b32_e32 v94, 0x1ffc0, v16
	v_and_b32_e32 v95, 0x7c0, v32
	v_or_b32_e32 v18, v94, v21
	v_lshlrev_b32_e32 v182, 2, v95
	v_lshl_add_u64 v[16:17], v[12:13], 0, v[182:183]
	v_lshlrev_b32_e32 v182, 13, v18
	v_lshl_add_u64 v[90:91], v[16:17], 0, v[182:183]
	v_add_co_u32_e32 v34, vcc, 0x8000, v90
	v_lshlrev_b32_e32 v182, 1, v94
	s_nop 0
	v_addc_co_u32_e32 v35, vcc, 0, v91, vcc
	v_add_co_u32_e32 v38, vcc, s5, v90
	global_load_dwordx4 v[16:19], v[90:91], off nt
	s_nop 0
	global_load_dwordx4 v[34:37], v[34:35], off nt
	v_addc_co_u32_e32 v39, vcc, 0, v91, vcc
	v_add_co_u32_e32 v42, vcc, s61, v90
	s_nop 1
	v_addc_co_u32_e32 v43, vcc, 0, v91, vcc
	global_load_dwordx4 v[38:41], v[38:39], off nt
	s_nop 0
	global_load_dwordx4 v[42:45], v[42:43], off nt
	v_add_co_u32_e32 v46, vcc, 0x20000, v90
	s_nop 1
	v_addc_co_u32_e32 v47, vcc, 0, v91, vcc
	v_add_co_u32_e32 v50, vcc, 0x28000, v90
	s_nop 1
	v_addc_co_u32_e32 v51, vcc, 0, v91, vcc
	global_load_dwordx4 v[46:49], v[46:47], off nt
	s_nop 0
	global_load_dwordx4 v[50:53], v[50:51], off nt
	v_add_co_u32_e32 v54, vcc, 0x30000, v90
	s_nop 1
	v_addc_co_u32_e32 v55, vcc, 0, v91, vcc
	v_add_co_u32_e32 v58, vcc, 0x38000, v90
	s_nop 1
	v_addc_co_u32_e32 v59, vcc, 0, v91, vcc
	global_load_dwordx4 v[54:57], v[54:55], off nt
	s_nop 0
	global_load_dwordx4 v[58:61], v[58:59], off nt
	v_add_co_u32_e32 v62, vcc, 0x40000, v90
	s_nop 1
	v_addc_co_u32_e32 v63, vcc, 0, v91, vcc
	v_add_co_u32_e32 v66, vcc, 0x48000, v90
	s_nop 1
	v_addc_co_u32_e32 v67, vcc, 0, v91, vcc
	global_load_dwordx4 v[62:65], v[62:63], off nt
	s_nop 0
	global_load_dwordx4 v[66:69], v[66:67], off nt
	v_add_co_u32_e32 v70, vcc, 0x50000, v90
	s_nop 1
	v_addc_co_u32_e32 v71, vcc, 0, v91, vcc
	v_add_co_u32_e32 v74, vcc, s28, v90
	s_nop 1
	v_addc_co_u32_e32 v75, vcc, 0, v91, vcc
	global_load_dwordx4 v[70:73], v[70:71], off nt
	s_nop 0
	global_load_dwordx4 v[74:77], v[74:75], off nt
	v_add_co_u32_e32 v78, vcc, 0x60000, v90
	s_nop 1
	v_addc_co_u32_e32 v79, vcc, 0, v91, vcc
	v_add_co_u32_e32 v82, vcc, 0x68000, v90
	s_nop 1
	v_addc_co_u32_e32 v83, vcc, 0, v91, vcc
	global_load_dwordx4 v[78:81], v[78:79], off nt
	s_nop 0
	global_load_dwordx4 v[82:85], v[82:83], off nt
	v_add_co_u32_e32 v86, vcc, 0x70000, v90
	s_nop 1
	v_addc_co_u32_e32 v87, vcc, 0, v91, vcc
	global_load_dwordx4 v[86:89], v[86:87], off nt
	v_add_co_u32_e32 v90, vcc, 0x78000, v90
	s_nop 1
	v_addc_co_u32_e32 v91, vcc, 0, v91, vcc
	global_load_dwordx4 v[90:93], v[90:91], off nt
	s_waitcnt vmcnt(15)
	ds_write2_b32 v22, v16, v17 offset1:1
	ds_write2_b32 v22, v18, v19 offset0:2 offset1:3
	v_add_u32_e32 v16, 0x410, v22
	s_waitcnt vmcnt(14)
	ds_write2_b32 v16, v34, v35 offset1:1
	v_add_u32_e32 v16, 0x418, v22
	ds_write2_b32 v16, v36, v37 offset1:1
	v_add_u32_e32 v16, 0x820, v22
	s_waitcnt vmcnt(13)
	ds_write2_b32 v16, v38, v39 offset1:1
	v_add_u32_e32 v16, 0x828, v22
	ds_write2_b32 v16, v40, v41 offset1:1
	v_add_u32_e32 v16, 0xc30, v22
	s_waitcnt vmcnt(12)
	ds_write2_b32 v16, v42, v43 offset1:1
	v_add_u32_e32 v16, 0xc38, v22
	ds_write2_b32 v16, v44, v45 offset1:1
	v_add_u32_e32 v16, 0x1040, v22
	s_waitcnt vmcnt(11)
	ds_write2_b32 v16, v46, v47 offset1:1
	v_add_u32_e32 v16, 0x1048, v22
	ds_write2_b32 v16, v48, v49 offset1:1
	v_add_u32_e32 v16, 0x1450, v22
	s_waitcnt vmcnt(10)
	ds_write2_b32 v16, v50, v51 offset1:1
	v_add_u32_e32 v16, 0x1458, v22
	ds_write2_b32 v16, v52, v53 offset1:1
	v_add_u32_e32 v16, 0x1860, v22
	v_lshl_add_u64 v[50:51], v[4:5], 0, v[182:183]
	s_waitcnt vmcnt(9)
	ds_write2_b32 v16, v54, v55 offset1:1
	v_add_u32_e32 v16, 0x1868, v22
	ds_write2_b32 v16, v56, v57 offset1:1
	v_add_u32_e32 v16, 0x1c70, v22
	s_waitcnt vmcnt(8)
	ds_write2_b32 v16, v58, v59 offset1:1
	v_add_u32_e32 v16, 0x1c78, v22
	ds_write2_b32 v16, v60, v61 offset1:1
	v_add_u32_e32 v16, 0x2080, v22
	v_add_u32_e32 v54, 0x400, v24
	s_waitcnt vmcnt(7)
	ds_write2_b32 v16, v62, v63 offset1:1
	v_add_u32_e32 v16, 0x2088, v22
	ds_write2_b32 v16, v64, v65 offset1:1
	v_add_u32_e32 v16, 0x2490, v22
	s_waitcnt vmcnt(6)
	ds_write2_b32 v16, v66, v67 offset1:1
	v_add_u32_e32 v16, 0x2498, v22
	ds_write2_b32 v16, v68, v69 offset1:1
	v_add_u32_e32 v16, 0x28a0, v22
	s_waitcnt vmcnt(5)
	ds_write2_b32 v16, v70, v71 offset1:1
	v_add_u32_e32 v16, 0x28a8, v22
	ds_write2_b32 v16, v72, v73 offset1:1
	v_add_u32_e32 v16, 0x2cb0, v22
	s_waitcnt vmcnt(4)
	ds_write2_b32 v16, v74, v75 offset1:1
	v_add_u32_e32 v16, 0x2cb8, v22
	ds_write2_b32 v16, v76, v77 offset1:1
	v_add_u32_e32 v16, 0x30c0, v22
	s_waitcnt vmcnt(3)
	ds_write2_b32 v16, v78, v79 offset1:1
	v_add_u32_e32 v16, 0x30c8, v22
	ds_write2_b32 v16, v80, v81 offset1:1
	v_add_u32_e32 v16, 0x34d0, v22
	s_waitcnt vmcnt(2)
; #define LAS __attribute__((address_space(3)))
; __device__ __forceinline__ unsigned pk2(float lo, float hi) { const f32x2 v = {lo, hi}; const hwbf16x2 b = __builtin_convertvector(v, hwbf16x2); return __builtin_bit_cast(unsigned, b); }
; #define LDS_WAIT() asm volatile("s_waitcnt lgkmcnt(0)" ::: "memory")
; __device__ __forceinline__ void transpose_item(const float* W, int ldw, int K, bf16_t* WT, int nblk, LAS float* scr, int item, int lane) {
;     ...
;     for (int i = 0; i < 16; ++i) { LAS float* d = scr + ((lane >> 4) + 4 * i) * 65 + (lane & 15) * 4; d[0] = v[i][0]; d[1] = v[i][1]; d[2] = v[i][2]; d[3] = v[i][3]; }
;     LDS_WAIT();
;     const int c = lane & 7;
; #pragma unroll
;     for (int j = 0; j < 8; ++j) { const int n = (lane >> 3) + 8 * j; const LAS float* s = scr + (8 * c) * 65 + n;
;         u32x4 o; o.x = pk2(s[0 * 65], s[1 * 65]); o.y = pk2(s[2 * 65], s[3 * 65]); o.z = pk2(s[4 * 65], s[5 * 65]); o.w = pk2(s[6 * 65], s[7 * 65]);
;         *(u32x4*)(WT + (size_t)(n0 + n) * K + k0 + 8 * c) = o; }
;     LDS_WAIT();
	ds_write2_b32 v16, v82, v83 offset1:1
	v_add_u32_e32 v16, 0x34d8, v22
	ds_write2_b32 v16, v84, v85 offset1:1
	v_add_u32_e32 v16, 0x38e0, v22
	s_waitcnt vmcnt(1)
	ds_write2_b32 v16, v86, v87 offset1:1
	v_add_u32_e32 v16, 0x38e8, v22
	ds_write2_b32 v16, v88, v89 offset1:1
	v_add_u32_e32 v16, 0x3cf0, v22
	s_waitcnt vmcnt(0)
	ds_write2_b32 v16, v90, v91 offset1:1
	v_add_u32_e32 v16, 0x3cf8, v22
	ds_write2_b32 v16, v92, v93 offset1:1
	s_waitcnt lgkmcnt(0)
	ds_read2_b32 v[34:35], v24 offset0:65 offset1:73
	ds_read2_b32 v[36:37], v24 offset1:8
	ds_read2_b32 v[38:39], v24 offset0:130 offset1:138
	ds_read2_b32 v[40:41], v24 offset0:195 offset1:203
	ds_read2_b32 v[42:43], v54 offset0:4 offset1:12
	ds_read2_b32 v[44:45], v54 offset0:69 offset1:77
	ds_read2_b32 v[46:47], v54 offset0:134 offset1:142
	ds_read2_b32 v[48:49], v54 offset0:199 offset1:207
	s_waitcnt lgkmcnt(6)
	v_cvt_pk_bf16_f32 v16, v36, v34
	v_or_b32_e32 v34, v95, v23
	v_lshlrev_b32_e32 v182, 12, v34
	s_waitcnt lgkmcnt(4)
	v_cvt_pk_bf16_f32 v17, v38, v40
	s_waitcnt lgkmcnt(2)
	v_cvt_pk_bf16_f32 v18, v42, v44
	s_waitcnt lgkmcnt(0)
	v_cvt_pk_bf16_f32 v19, v46, v48
	v_lshl_add_u64 v[52:53], v[50:51], 0, v[182:183]
	global_store_dwordx4 v[52:53], v[16:19], off nt
	v_or_b32_e32 v34, v95, v25
	v_lshlrev_b32_e32 v182, 12, v34
	v_cvt_pk_bf16_f32 v16, v37, v35
	v_cvt_pk_bf16_f32 v17, v39, v41
	v_cvt_pk_bf16_f32 v18, v43, v45
	v_cvt_pk_bf16_f32 v19, v47, v49
	ds_read2_b32 v[36:37], v24 offset0:81 offset1:89
	ds_read2_b32 v[38:39], v24 offset0:16 offset1:24
	ds_read2_b32 v[40:41], v24 offset0:146 offset1:154
	ds_read2_b32 v[42:43], v24 offset0:211 offset1:219
	ds_read2_b32 v[44:45], v54 offset0:20 offset1:28
	ds_read2_b32 v[46:47], v54 offset0:85 offset1:93
	ds_read2_b32 v[48:49], v54 offset0:150 offset1:158
	ds_read2_b32 v[52:53], v54 offset0:215 offset1:223
	v_lshl_add_u64 v[34:35], v[50:51], 0, v[182:183]
	global_store_dwordx4 v[34:35], v[16:19], off nt
	v_or_b32_e32 v34, v95, v26
	v_lshlrev_b32_e32 v182, 12, v34
	s_waitcnt lgkmcnt(6)
	v_cvt_pk_bf16_f32 v16, v38, v36
	s_waitcnt lgkmcnt(4)
	v_cvt_pk_bf16_f32 v17, v40, v42
	s_waitcnt lgkmcnt(2)
	v_cvt_pk_bf16_f32 v18, v44, v46
	s_waitcnt lgkmcnt(0)
	v_cvt_pk_bf16_f32 v19, v48, v52
	v_lshl_add_u64 v[34:35], v[50:51], 0, v[182:183]
	global_store_dwordx4 v[34:35], v[16:19], off nt
	v_or_b32_e32 v34, v95, v27
	v_lshlrev_b32_e32 v182, 12, v34
	v_cvt_pk_bf16_f32 v16, v39, v37
	v_cvt_pk_bf16_f32 v17, v41, v43
	v_cvt_pk_bf16_f32 v18, v45, v47
	v_cvt_pk_bf16_f32 v19, v49, v53
	ds_read2_b32 v[36:37], v24 offset0:32 offset1:40
	ds_read2_b32 v[38:39], v24 offset0:97 offset1:105
	ds_read2_b32 v[40:41], v24 offset0:162 offset1:170
	ds_read2_b32 v[42:43], v24 offset0:227 offset1:235
	ds_read2_b32 v[44:45], v54 offset0:36 offset1:44
	ds_read2_b32 v[46:47], v54 offset0:101 offset1:109
	ds_read2_b32 v[48:49], v54 offset0:166 offset1:174
	ds_read2_b32 v[52:53], v54 offset0:231 offset1:239
	v_lshl_add_u64 v[34:35], v[50:51], 0, v[182:183]
	global_store_dwordx4 v[34:35], v[16:19], off nt
	v_or_b32_e32 v34, v95, v28
	v_lshlrev_b32_e32 v182, 12, v34
	s_waitcnt lgkmcnt(6)
	v_cvt_pk_bf16_f32 v16, v36, v38
	s_waitcnt lgkmcnt(4)
	v_cvt_pk_bf16_f32 v17, v40, v42
	s_waitcnt lgkmcnt(2)
	v_cvt_pk_bf16_f32 v18, v44, v46
	s_waitcnt lgkmcnt(0)
	v_cvt_pk_bf16_f32 v19, v48, v52
	v_lshl_add_u64 v[34:35], v[50:51], 0, v[182:183]
	global_store_dwordx4 v[34:35], v[16:19], off nt
	v_or_b32_e32 v34, v95, v29
	v_lshlrev_b32_e32 v182, 12, v34
	v_cvt_pk_bf16_f32 v16, v37, v39
	v_cvt_pk_bf16_f32 v17, v41, v43
	v_cvt_pk_bf16_f32 v18, v45, v47
	v_cvt_pk_bf16_f32 v19, v49, v53
	ds_read2_b32 v[36:37], v24 offset0:48 offset1:56
	ds_read2_b32 v[38:39], v24 offset0:113 offset1:121
	ds_read2_b32 v[40:41], v24 offset0:178 offset1:186
	ds_read2_b32 v[42:43], v24 offset0:243 offset1:251
	ds_read2_b32 v[44:45], v54 offset0:52 offset1:60
	ds_read2_b32 v[46:47], v54 offset0:117 offset1:125
	ds_read2_b32 v[48:49], v54 offset0:182 offset1:190
	ds_read2_b32 v[52:53], v54 offset0:247 offset1:255
	v_lshl_add_u64 v[34:35], v[50:51], 0, v[182:183]
	global_store_dwordx4 v[34:35], v[16:19], off nt
	v_or_b32_e32 v34, v95, v30
	v_lshlrev_b32_e32 v182, 12, v34
	s_waitcnt lgkmcnt(6)
	v_cvt_pk_bf16_f32 v16, v36, v38
	s_waitcnt lgkmcnt(4)
	v_cvt_pk_bf16_f32 v17, v40, v42
	s_waitcnt lgkmcnt(2)
	v_cvt_pk_bf16_f32 v18, v44, v46
	s_waitcnt lgkmcnt(0)
	v_cvt_pk_bf16_f32 v19, v48, v52
	v_lshl_add_u64 v[34:35], v[50:51], 0, v[182:183]
	global_store_dwordx4 v[34:35], v[16:19], off nt
	v_or_b32_e32 v34, v95, v31
	v_lshlrev_b32_e32 v182, 12, v34
	v_cvt_pk_bf16_f32 v16, v37, v39
	v_cvt_pk_bf16_f32 v17, v41, v43
	v_cvt_pk_bf16_f32 v18, v45, v47
	v_cvt_pk_bf16_f32 v19, v49, v53
	v_lshl_add_u64 v[34:35], v[50:51], 0, v[182:183]
	global_store_dwordx4 v[34:35], v[16:19], off nt
	s_waitcnt lgkmcnt(0)

; #define LAS __attribute__((address_space(3)))
; __device__ __forceinline__ void transpose_item(const float* W, int ldw, int K, bf16_t* WT, int nblk, LAS float* scr, int item, int lane) {
;     ...
;     for (int i = 0; i < 16; ++i) v[i] = *(const f32x4*)(W + (size_t)(k0 + (lane >> 4) + 4 * i) * ldw + n0 + (lane & 15) * 4);
; #pragma unroll
;     for (int i = 0; i < 16; ++i) { LAS float* d = scr + ((lane >> 4) + 4 * i) * 65 + (lane & 15) * 4; d[0] = v[i][0]; d[1] = v[i][1]; d[2] = v[i][2]; d[3] = v[i][3]; }
; __device__ __forceinline__ void transpose_range(const Params& p, LAS unsigned char* lds, int l, int lo, int hi, int gw, int NGW, int wave, int lane) {
;     ...
;         if (r < TI_IN) { transpose_item(p.w_in + (size_t)l * DM * INW, INW, DM, (bf16_t*)(ws + WS_WIN + l * SZ_WIN), ZW / 64, scr, r, lane); continue; } r -= TI_IN;
.LBB0_472:
	s_andn2_saveexec_b64 s[6:7], s[6:7]
	s_cbranch_execz .LBB0_461
	v_ashrrev_i32_e32 v16, 31, v20
	v_lshrrev_b32_e32 v16, 26, v16
	v_add_u32_e32 v17, v20, v16
	v_and_b32_e32 v16, 0xffffffc0, v17
	v_lshlrev_b32_e32 v17, 6, v17
	v_and_b32_e32 v17, 0xfffff000, v17
	v_sub_u32_e32 v18, v32, v17
	v_or_b32_e32 v17, v16, v21
	v_ashrrev_i32_e32 v19, 31, v18
	v_lshl_add_u64 v[94:95], v[18:19], 2, v[14:15]
	v_or_b32_e32 v19, 4, v17
	v_mad_i64_i32 v[34:35], s[8:9], v17, s21, v[94:95]
	v_mad_i64_i32 v[38:39], s[8:9], v19, s21, v[94:95]
	global_load_dwordx4 v[34:37], v[34:35], off nt
	v_or_b32_e32 v19, 8, v17
	global_load_dwordx4 v[38:41], v[38:39], off nt
	v_mad_i64_i32 v[42:43], s[8:9], v19, s21, v[94:95]
	global_load_dwordx4 v[42:45], v[42:43], off nt
	v_or_b32_e32 v19, 12, v17
	v_mad_i64_i32 v[46:47], s[8:9], v19, s21, v[94:95]
	global_load_dwordx4 v[46:49], v[46:47], off nt
	v_or_b32_e32 v19, 16, v17
	v_mad_i64_i32 v[50:51], s[8:9], v19, s21, v[94:95]
	global_load_dwordx4 v[50:53], v[50:51], off nt
	v_or_b32_e32 v19, 20, v17
	v_mad_i64_i32 v[54:55], s[8:9], v19, s21, v[94:95]
	global_load_dwordx4 v[54:57], v[54:55], off nt
	v_or_b32_e32 v19, 24, v17
	v_mad_i64_i32 v[58:59], s[8:9], v19, s21, v[94:95]
	global_load_dwordx4 v[58:61], v[58:59], off nt
	v_or_b32_e32 v19, 28, v17
	v_mad_i64_i32 v[62:63], s[8:9], v19, s21, v[94:95]
	global_load_dwordx4 v[62:65], v[62:63], off nt
	v_or_b32_e32 v19, 32, v17
	v_mad_i64_i32 v[66:67], s[8:9], v19, s21, v[94:95]
	global_load_dwordx4 v[66:69], v[66:67], off nt
	v_or_b32_e32 v19, 36, v17
	v_mad_i64_i32 v[70:71], s[8:9], v19, s21, v[94:95]
	global_load_dwordx4 v[70:73], v[70:71], off nt
	v_or_b32_e32 v19, 40, v17
	v_mad_i64_i32 v[74:75], s[8:9], v19, s21, v[94:95]
	global_load_dwordx4 v[74:77], v[74:75], off nt
	v_or_b32_e32 v19, 44, v17
	v_mad_i64_i32 v[78:79], s[8:9], v19, s21, v[94:95]
	global_load_dwordx4 v[78:81], v[78:79], off nt
	v_or_b32_e32 v19, 48, v17
	v_mad_i64_i32 v[82:83], s[8:9], v19, s21, v[94:95]
	global_load_dwordx4 v[82:85], v[82:83], off nt
	v_or_b32_e32 v19, 52, v17
	v_mad_i64_i32 v[86:87], s[8:9], v19, s21, v[94:95]
	global_load_dwordx4 v[86:89], v[86:87], off nt
	v_or_b32_e32 v19, 56, v17
	v_mad_i64_i32 v[90:91], s[8:9], v19, s21, v[94:95]
	global_load_dwordx4 v[90:93], v[90:91], off nt
	v_or_b32_e32 v17, 60, v17
	v_mad_i64_i32 v[94:95], s[8:9], v17, s21, v[94:95]
	global_load_dwordx4 v[94:97], v[94:95], off nt
	v_add_u32_e32 v17, 0x410, v22
	v_add_u32_e32 v18, v18, v23
	v_ashrrev_i32_e32 v19, 31, v18
	s_waitcnt vmcnt(15)
	ds_write2_b32 v22, v34, v35 offset1:1
	ds_write2_b32 v22, v36, v37 offset0:2 offset1:3
	s_waitcnt vmcnt(14)
	ds_write2_b32 v17, v38, v39 offset1:1
	v_add_u32_e32 v17, 0x418, v22
	ds_write2_b32 v17, v40, v41 offset1:1
	v_add_u32_e32 v17, 0x820, v22
	s_waitcnt vmcnt(13)
	ds_write2_b32 v17, v42, v43 offset1:1
	v_add_u32_e32 v17, 0x828, v22
	ds_write2_b32 v17, v44, v45 offset1:1
	v_add_u32_e32 v17, 0xc30, v22
	s_waitcnt vmcnt(12)
	ds_write2_b32 v17, v46, v47 offset1:1
	v_add_u32_e32 v17, 0xc38, v22
	ds_write2_b32 v17, v48, v49 offset1:1
	v_add_u32_e32 v17, 0x1040, v22
	s_waitcnt vmcnt(11)
	ds_write2_b32 v17, v50, v51 offset1:1
	v_add_u32_e32 v17, 0x1048, v22
	ds_write2_b32 v17, v52, v53 offset1:1
	v_add_u32_e32 v17, 0x1450, v22
	s_waitcnt vmcnt(10)
	ds_write2_b32 v17, v54, v55 offset1:1
	v_add_u32_e32 v17, 0x1458, v22
	ds_write2_b32 v17, v56, v57 offset1:1
	v_add_u32_e32 v17, 0x1860, v22
	s_waitcnt vmcnt(9)
	ds_write2_b32 v17, v58, v59 offset1:1
	v_add_u32_e32 v17, 0x1868, v22
	ds_write2_b32 v17, v60, v61 offset1:1
	v_add_u32_e32 v17, 0x1c70, v22
	s_waitcnt vmcnt(8)
	ds_write2_b32 v17, v62, v63 offset1:1
	v_add_u32_e32 v17, 0x1c78, v22
	ds_write2_b32 v17, v64, v65 offset1:1
	v_add_u32_e32 v17, 0x2080, v22
	s_waitcnt vmcnt(7)
	ds_write2_b32 v17, v66, v67 offset1:1
	v_add_u32_e32 v17, 0x2088, v22
	ds_write2_b32 v17, v68, v69 offset1:1
	v_add_u32_e32 v17, 0x2490, v22
	s_waitcnt vmcnt(6)
	ds_write2_b32 v17, v70, v71 offset1:1
	v_add_u32_e32 v17, 0x2498, v22
	ds_write2_b32 v17, v72, v73 offset1:1
	v_add_u32_e32 v17, 0x28a0, v22
	s_waitcnt vmcnt(5)
	ds_write2_b32 v17, v74, v75 offset1:1
	v_add_u32_e32 v17, 0x28a8, v22
	ds_write2_b32 v17, v76, v77 offset1:1
	v_add_u32_e32 v17, 0x2cb0, v22
	s_waitcnt vmcnt(4)
	ds_write2_b32 v17, v78, v79 offset1:1
	v_add_u32_e32 v17, 0x2cb8, v22
	ds_write2_b32 v17, v80, v81 offset1:1
	v_add_u32_e32 v17, 0x30c0, v22
	s_waitcnt vmcnt(3)
	ds_write2_b32 v17, v82, v83 offset1:1
	v_add_u32_e32 v17, 0x30c8, v22
	ds_write2_b32 v17, v84, v85 offset1:1
	v_add_u32_e32 v17, 0x34d0, v22
	s_waitcnt vmcnt(2)
	ds_write2_b32 v17, v86, v87 offset1:1
	v_add_u32_e32 v17, 0x34d8, v22
	ds_write2_b32 v17, v88, v89 offset1:1
	v_add_u32_e32 v17, 0x38e0, v22
	s_waitcnt vmcnt(1)
	ds_write2_b32 v17, v90, v91 offset1:1
	v_add_u32_e32 v17, 0x38e8, v22
	ds_write2_b32 v17, v92, v93 offset1:1
	v_add_u32_e32 v17, 0x3cf0, v22
	s_waitcnt vmcnt(0)
; #define LAS __attribute__((address_space(3)))
; __device__ __forceinline__ unsigned pk2(float lo, float hi) { const f32x2 v = {lo, hi}; const hwbf16x2 b = __builtin_convertvector(v, hwbf16x2); return __builtin_bit_cast(unsigned, b); }
; #define LDS_WAIT() asm volatile("s_waitcnt lgkmcnt(0)" ::: "memory")
; __device__ __forceinline__ void transpose_item(const float* W, int ldw, int K, bf16_t* WT, int nblk, LAS float* scr, int item, int lane) {
;     ...
;     for (int i = 0; i < 16; ++i) { LAS float* d = scr + ((lane >> 4) + 4 * i) * 65 + (lane & 15) * 4; d[0] = v[i][0]; d[1] = v[i][1]; d[2] = v[i][2]; d[3] = v[i][3]; }
;     LDS_WAIT();
;     const int c = lane & 7;
; #pragma unroll
;     for (int j = 0; j < 8; ++j) { const int n = (lane >> 3) + 8 * j; const LAS float* s = scr + (8 * c) * 65 + n;
;         u32x4 o; o.x = pk2(s[0 * 65], s[1 * 65]); o.y = pk2(s[2 * 65], s[3 * 65]); o.z = pk2(s[4 * 65], s[5 * 65]); o.w = pk2(s[6 * 65], s[7 * 65]);
;         *(u32x4*)(WT + (size_t)(n0 + n) * K + k0 + 8 * c) = o; }
;     LDS_WAIT();
	ds_write2_b32 v17, v94, v95 offset1:1
	v_add_u32_e32 v17, 0x3cf8, v22
	ds_write2_b32 v17, v96, v97 offset1:1
	s_waitcnt lgkmcnt(0)
	v_add_u32_e32 v56, 0x400, v24
	ds_read2_b32 v[38:39], v24 offset0:65 offset1:73
	ds_read2_b32 v[40:41], v24 offset1:8
	ds_read2_b32 v[42:43], v24 offset0:130 offset1:138
	ds_read2_b32 v[44:45], v24 offset0:195 offset1:203
	ds_read2_b32 v[46:47], v56 offset0:4 offset1:12
	ds_read2_b32 v[48:49], v56 offset0:69 offset1:77
	ds_read2_b32 v[50:51], v56 offset0:134 offset1:142
	ds_read2_b32 v[52:53], v56 offset0:199 offset1:207
	v_ashrrev_i32_e32 v17, 31, v16
	v_lshl_add_u64 v[16:17], v[16:17], 1, v[6:7]
	v_lshlrev_b64 v[54:55], 12, v[18:19]
	s_waitcnt lgkmcnt(6)
	v_cvt_pk_bf16_f32 v34, v40, v38
	s_waitcnt lgkmcnt(4)
	v_cvt_pk_bf16_f32 v35, v42, v44
	s_waitcnt lgkmcnt(2)
	v_cvt_pk_bf16_f32 v36, v46, v48
	s_waitcnt lgkmcnt(0)
	v_cvt_pk_bf16_f32 v37, v50, v52
	v_lshl_add_u64 v[54:55], v[16:17], 0, v[54:55]
	v_add_u32_e32 v38, 8, v18
	global_store_dwordx4 v[54:55], v[34:37], off nt
	v_add_u32_e32 v54, 16, v18
	v_ashrrev_i32_e32 v55, 31, v54
	v_cvt_pk_bf16_f32 v34, v41, v39
	v_ashrrev_i32_e32 v39, 31, v38
	v_lshlrev_b64 v[38:39], 12, v[38:39]
	v_cvt_pk_bf16_f32 v35, v43, v45
	v_cvt_pk_bf16_f32 v36, v47, v49
	v_cvt_pk_bf16_f32 v37, v51, v53
	v_lshl_add_u64 v[38:39], v[16:17], 0, v[38:39]
	global_store_dwordx4 v[38:39], v[34:37], off nt
	ds_read2_b32 v[38:39], v24 offset0:81 offset1:89
	ds_read2_b32 v[40:41], v24 offset0:16 offset1:24
	ds_read2_b32 v[42:43], v24 offset0:146 offset1:154
	ds_read2_b32 v[44:45], v24 offset0:211 offset1:219
	ds_read2_b32 v[46:47], v56 offset0:20 offset1:28
	ds_read2_b32 v[48:49], v56 offset0:85 offset1:93
	ds_read2_b32 v[50:51], v56 offset0:150 offset1:158
	ds_read2_b32 v[52:53], v56 offset0:215 offset1:223
	v_lshlrev_b64 v[54:55], 12, v[54:55]
	s_waitcnt lgkmcnt(6)
	v_cvt_pk_bf16_f32 v34, v40, v38
	s_waitcnt lgkmcnt(4)
	v_cvt_pk_bf16_f32 v35, v42, v44
	s_waitcnt lgkmcnt(2)
	v_cvt_pk_bf16_f32 v36, v46, v48
	s_waitcnt lgkmcnt(0)
	v_cvt_pk_bf16_f32 v37, v50, v52
	v_lshl_add_u64 v[54:55], v[16:17], 0, v[54:55]
	v_add_u32_e32 v38, 24, v18
	global_store_dwordx4 v[54:55], v[34:37], off nt
	v_add_u32_e32 v54, 32, v18
	v_ashrrev_i32_e32 v55, 31, v54
	v_cvt_pk_bf16_f32 v34, v41, v39
	v_ashrrev_i32_e32 v39, 31, v38
	v_lshlrev_b64 v[38:39], 12, v[38:39]
	v_cvt_pk_bf16_f32 v35, v43, v45
	v_cvt_pk_bf16_f32 v36, v47, v49
	v_cvt_pk_bf16_f32 v37, v51, v53
	v_lshl_add_u64 v[38:39], v[16:17], 0, v[38:39]
	global_store_dwordx4 v[38:39], v[34:37], off nt
	ds_read2_b32 v[38:39], v24 offset0:32 offset1:40
	ds_read2_b32 v[40:41], v24 offset0:97 offset1:105
	ds_read2_b32 v[42:43], v24 offset0:162 offset1:170
	ds_read2_b32 v[44:45], v24 offset0:227 offset1:235
	ds_read2_b32 v[46:47], v56 offset0:36 offset1:44
	ds_read2_b32 v[48:49], v56 offset0:101 offset1:109
	ds_read2_b32 v[50:51], v56 offset0:166 offset1:174
	ds_read2_b32 v[52:53], v56 offset0:231 offset1:239
	v_lshlrev_b64 v[54:55], 12, v[54:55]
	s_waitcnt lgkmcnt(6)
	v_cvt_pk_bf16_f32 v34, v38, v40
	s_waitcnt lgkmcnt(4)
	v_cvt_pk_bf16_f32 v35, v42, v44
	s_waitcnt lgkmcnt(2)
	v_cvt_pk_bf16_f32 v36, v46, v48
	s_waitcnt lgkmcnt(0)
	v_cvt_pk_bf16_f32 v37, v50, v52
	v_lshl_add_u64 v[54:55], v[16:17], 0, v[54:55]
	v_add_u32_e32 v38, 40, v18
	global_store_dwordx4 v[54:55], v[34:37], off nt
	v_add_u32_e32 v54, 48, v18
	v_ashrrev_i32_e32 v55, 31, v54
	v_cvt_pk_bf16_f32 v34, v39, v41
	v_ashrrev_i32_e32 v39, 31, v38
	v_lshlrev_b64 v[38:39], 12, v[38:39]
	v_cvt_pk_bf16_f32 v35, v43, v45
	v_cvt_pk_bf16_f32 v36, v47, v49
	v_cvt_pk_bf16_f32 v37, v51, v53
	v_lshl_add_u64 v[38:39], v[16:17], 0, v[38:39]
	global_store_dwordx4 v[38:39], v[34:37], off nt
	ds_read2_b32 v[38:39], v24 offset0:48 offset1:56
	ds_read2_b32 v[40:41], v24 offset0:113 offset1:121
	ds_read2_b32 v[42:43], v24 offset0:178 offset1:186
	ds_read2_b32 v[44:45], v24 offset0:243 offset1:251
	ds_read2_b32 v[46:47], v56 offset0:52 offset1:60
	ds_read2_b32 v[48:49], v56 offset0:117 offset1:125
	ds_read2_b32 v[50:51], v56 offset0:182 offset1:190
	ds_read2_b32 v[52:53], v56 offset0:247 offset1:255
	v_add_u32_e32 v18, 56, v18
	v_lshlrev_b64 v[54:55], 12, v[54:55]
	v_ashrrev_i32_e32 v19, 31, v18
	s_waitcnt lgkmcnt(6)
	v_cvt_pk_bf16_f32 v34, v38, v40
	s_waitcnt lgkmcnt(4)
	v_cvt_pk_bf16_f32 v35, v42, v44
	s_waitcnt lgkmcnt(2)
	v_cvt_pk_bf16_f32 v36, v46, v48
	s_waitcnt lgkmcnt(0)
	v_cvt_pk_bf16_f32 v37, v50, v52
	v_lshl_add_u64 v[54:55], v[16:17], 0, v[54:55]
	v_lshlrev_b64 v[18:19], 12, v[18:19]
	global_store_dwordx4 v[54:55], v[34:37], off nt
	v_lshl_add_u64 v[16:17], v[16:17], 0, v[18:19]
	s_nop 0
	v_cvt_pk_bf16_f32 v34, v39, v41
	v_cvt_pk_bf16_f32 v35, v43, v45
	v_cvt_pk_bf16_f32 v36, v47, v49
	v_cvt_pk_bf16_f32 v37, v51, v53
	global_store_dwordx4 v[16:17], v[34:37], off nt
	s_waitcnt lgkmcnt(0)
	s_branch .LBB0_461

; #define LAS __attribute__((address_space(3)))
; __device__ __forceinline__ void transpose_item(const float* W, int ldw, int K, bf16_t* WT, int nblk, LAS float* scr, int item, int lane) {
;     ...
;     for (int i = 0; i < 16; ++i) v[i] = *(const f32x4*)(W + (size_t)(k0 + (lane >> 4) + 4 * i) * ldw + n0 + (lane & 15) * 4);
; #pragma unroll
;     for (int i = 0; i < 16; ++i) { LAS float* d = scr + ((lane >> 4) + 4 * i) * 65 + (lane & 15) * 4; d[0] = v[i][0]; d[1] = v[i][1]; d[2] = v[i][2]; d[3] = v[i][3]; }
; __device__ __forceinline__ void transpose_range(const Params& p, LAS unsigned char* lds, int l, int lo, int hi, int gw, int NGW, int wave, int lane) {
;     ...
;         if (r < TI_UP) { transpose_item(p.ffn_up + (size_t)l * DM * DFF2, DFF2, DM, (bf16_t*)(ws + WS_WUP + l * SZ_WUP), DFF2 / 64, scr, r, lane); continue; } r -= TI_UP;
.LBB0_541:
	v_cmp_lt_i32_e32 vcc, s29, v22
	s_and_saveexec_b64 s[6:7], vcc
	s_xor_b64 s[6:7], exec, s[6:7]
	s_cbranch_execz .LBB0_547
	v_cmp_lt_u32_e32 vcc, s25, v22
	s_and_saveexec_b64 s[8:9], vcc
	s_xor_b64 s[8:9], exec, s[8:9]
	s_cbranch_execz .LBB0_544
	v_add_u16_e32 v14, 0xf400, v22
	v_mul_u32_u24_e32 v15, 0xba2f, v14
	v_lshrrev_b32_e32 v15, 23, v15
	v_mul_lo_u16_e32 v16, 0xb0, v15
	v_sub_u16_e32 v14, v14, v16
	v_lshlrev_b16_e32 v33, 6, v15
	v_lshlrev_b16_e32 v71, 6, v14
	v_or_b32_e32 v16, v68, v33
	v_lshlrev_b32_e32 v182, 2, v71
	v_mul_u32_u24_e32 v16, 0x2c00, v16
	v_lshl_add_u64 v[14:15], v[8:9], 0, v[182:183]
	v_lshlrev_b32_e32 v182, 2, v16
	v_lshl_add_u64 v[66:67], v[14:15], 0, v[182:183]
	v_add_co_u32_e32 v34, vcc, s58, v66
	s_mov_b32 s10, 0x18c000
	s_nop 0
	v_addc_co_u32_e32 v35, vcc, 0, v67, vcc
	v_add_co_u32_e32 v38, vcc, s28, v66
	global_load_dwordx4 v[14:17], v[66:67], off nt
	s_nop 0
	global_load_dwordx4 v[34:37], v[34:35], off nt
	v_addc_co_u32_e32 v39, vcc, 0, v67, vcc
	v_add_co_u32_e32 v42, vcc, s59, v66
	v_lshlrev_b32_e32 v182, 1, v33
	s_nop 0
	v_addc_co_u32_e32 v43, vcc, 0, v67, vcc
	global_load_dwordx4 v[38:41], v[38:39], off nt
	s_nop 0
	global_load_dwordx4 v[42:45], v[42:43], off nt
	v_add_co_u32_e32 v46, vcc, s64, v66
	v_add_u32_e32 v33, 0x400, v24
	s_nop 0
	v_addc_co_u32_e32 v47, vcc, 0, v67, vcc
	v_add_co_u32_e32 v50, vcc, s65, v66
	s_nop 1
	v_addc_co_u32_e32 v51, vcc, 0, v67, vcc
	global_load_dwordx4 v[46:49], v[46:47], off nt
	s_nop 0
	global_load_dwordx4 v[50:53], v[50:51], off nt
	v_add_co_u32_e32 v54, vcc, s66, v66
	s_nop 1
	v_addc_co_u32_e32 v55, vcc, 0, v67, vcc
	v_add_co_u32_e32 v58, vcc, s68, v66
	s_nop 1
	v_addc_co_u32_e32 v59, vcc, 0, v67, vcc
	global_load_dwordx4 v[54:57], v[54:55], off nt
	s_nop 0
	global_load_dwordx4 v[58:61], v[58:59], off nt
	v_add_co_u32_e32 v62, vcc, s69, v66
	s_nop 1
	v_addc_co_u32_e32 v63, vcc, 0, v67, vcc
	v_add_co_u32_e32 v72, vcc, s10, v66
	s_mov_b32 s10, 0x1b8000
	s_nop 0
	v_addc_co_u32_e32 v73, vcc, 0, v67, vcc
	global_load_dwordx4 v[62:65], v[62:63], off nt
	s_nop 0
	global_load_dwordx4 v[72:75], v[72:73], off nt
	v_add_co_u32_e32 v76, vcc, s10, v66
	s_mov_b32 s10, 0x1e4000
	s_nop 0
	v_addc_co_u32_e32 v77, vcc, 0, v67, vcc
	v_add_co_u32_e32 v80, vcc, s10, v66
	s_mov_b32 s10, 0x210000
	s_nop 0
	v_addc_co_u32_e32 v81, vcc, 0, v67, vcc
	global_load_dwordx4 v[76:79], v[76:77], off nt
	s_nop 0
	global_load_dwordx4 v[80:83], v[80:81], off nt
	v_add_co_u32_e32 v84, vcc, s10, v66
	s_mov_b32 s10, 0x23c000
	s_nop 0
	v_addc_co_u32_e32 v85, vcc, 0, v67, vcc
	v_add_co_u32_e32 v88, vcc, s10, v66
	s_mov_b32 s10, 0x268000
	s_nop 0
	v_addc_co_u32_e32 v89, vcc, 0, v67, vcc
	global_load_dwordx4 v[84:87], v[84:85], off nt
	s_nop 0
	global_load_dwordx4 v[88:91], v[88:89], off nt
	v_add_co_u32_e32 v92, vcc, s10, v66
	s_mov_b32 s10, 0x294000
	s_nop 0
	v_addc_co_u32_e32 v93, vcc, 0, v67, vcc
	global_load_dwordx4 v[92:95], v[92:93], off nt
	v_add_co_u32_e32 v66, vcc, s10, v66
	s_nop 1
	v_addc_co_u32_e32 v67, vcc, 0, v67, vcc
	global_load_dwordx4 v[96:99], v[66:67], off nt
	s_waitcnt vmcnt(15)
	ds_write2_b32 v23, v14, v15 offset1:1
	ds_write2_b32 v23, v16, v17 offset0:2 offset1:3
	v_add_u32_e32 v14, 0x410, v23
	s_waitcnt vmcnt(14)
	ds_write2_b32 v14, v34, v35 offset1:1
	v_add_u32_e32 v14, 0x418, v23
	ds_write2_b32 v14, v36, v37 offset1:1
	v_add_u32_e32 v14, 0x820, v23
	s_waitcnt vmcnt(13)
	ds_write2_b32 v14, v38, v39 offset1:1
	v_add_u32_e32 v14, 0x828, v23
	ds_write2_b32 v14, v40, v41 offset1:1
	v_add_u32_e32 v14, 0xc30, v23
	s_waitcnt vmcnt(12)
	ds_write2_b32 v14, v42, v43 offset1:1
	v_add_u32_e32 v14, 0xc38, v23
	ds_write2_b32 v14, v44, v45 offset1:1
	v_add_u32_e32 v14, 0x1040, v23
	s_waitcnt vmcnt(11)
	ds_write2_b32 v14, v46, v47 offset1:1
	v_add_u32_e32 v14, 0x1048, v23
	ds_write2_b32 v14, v48, v49 offset1:1
	v_add_u32_e32 v14, 0x1450, v23
	s_waitcnt vmcnt(10)
	ds_write2_b32 v14, v50, v51 offset1:1
	v_add_u32_e32 v14, 0x1458, v23
	ds_write2_b32 v14, v52, v53 offset1:1
	v_add_u32_e32 v14, 0x1860, v23
	v_lshl_add_u64 v[50:51], v[2:3], 0, v[182:183]
	s_waitcnt vmcnt(9)
	ds_write2_b32 v14, v54, v55 offset1:1
	v_add_u32_e32 v14, 0x1868, v23
	ds_write2_b32 v14, v56, v57 offset1:1
	v_add_u32_e32 v14, 0x1c70, v23
	s_waitcnt vmcnt(8)
	ds_write2_b32 v14, v58, v59 offset1:1
	v_add_u32_e32 v14, 0x1c78, v23
	ds_write2_b32 v14, v60, v61 offset1:1
	v_add_u32_e32 v14, 0x2080, v23
	s_waitcnt vmcnt(7)
	ds_write2_b32 v14, v62, v63 offset1:1
	v_add_u32_e32 v14, 0x2088, v23
	ds_write2_b32 v14, v64, v65 offset1:1
	v_add_u32_e32 v14, 0x2490, v23
	s_waitcnt vmcnt(6)
	ds_write2_b32 v14, v72, v73 offset1:1
	v_add_u32_e32 v14, 0x2498, v23
	ds_write2_b32 v14, v74, v75 offset1:1
	v_add_u32_e32 v14, 0x28a0, v23
	s_waitcnt vmcnt(5)
	ds_write2_b32 v14, v76, v77 offset1:1
	v_add_u32_e32 v14, 0x28a8, v23
	ds_write2_b32 v14, v78, v79 offset1:1
	v_add_u32_e32 v14, 0x2cb0, v23
	s_waitcnt vmcnt(4)
	ds_write2_b32 v14, v80, v81 offset1:1
	v_add_u32_e32 v14, 0x2cb8, v23
	ds_write2_b32 v14, v82, v83 offset1:1
	v_add_u32_e32 v14, 0x30c0, v23
	s_waitcnt vmcnt(3)
	ds_write2_b32 v14, v84, v85 offset1:1
	v_add_u32_e32 v14, 0x30c8, v23
	ds_write2_b32 v14, v86, v87 offset1:1
	v_add_u32_e32 v14, 0x34d0, v23
	s_waitcnt vmcnt(2)
	ds_write2_b32 v14, v88, v89 offset1:1
	v_add_u32_e32 v14, 0x34d8, v23
	ds_write2_b32 v14, v90, v91 offset1:1
	v_add_u32_e32 v14, 0x38e0, v23
	s_waitcnt vmcnt(1)
	ds_write2_b32 v14, v92, v93 offset1:1
	v_add_u32_e32 v14, 0x38e8, v23
	ds_write2_b32 v14, v94, v95 offset1:1
	v_add_u32_e32 v14, 0x3cf0, v23
	s_waitcnt vmcnt(0)
	ds_write2_b32 v14, v96, v97 offset1:1
	v_add_u32_e32 v14, 0x3cf8, v23
	ds_write2_b32 v14, v98, v99 offset1:1
	s_waitcnt lgkmcnt(0)
; #define LAS __attribute__((address_space(3)))
; __device__ __forceinline__ unsigned pk2(float lo, float hi) { const f32x2 v = {lo, hi}; const hwbf16x2 b = __builtin_convertvector(v, hwbf16x2); return __builtin_bit_cast(unsigned, b); }
; #define LDS_WAIT() asm volatile("s_waitcnt lgkmcnt(0)" ::: "memory")
; __device__ __forceinline__ void transpose_item(const float* W, int ldw, int K, bf16_t* WT, int nblk, LAS float* scr, int item, int lane) {
;     ...
;     LDS_WAIT();
;     const int c = lane & 7;
; #pragma unroll
;     for (int j = 0; j < 8; ++j) { const int n = (lane >> 3) + 8 * j; const LAS float* s = scr + (8 * c) * 65 + n;
;         u32x4 o; o.x = pk2(s[0 * 65], s[1 * 65]); o.y = pk2(s[2 * 65], s[3 * 65]); o.z = pk2(s[4 * 65], s[5 * 65]); o.w = pk2(s[6 * 65], s[7 * 65]);
;         *(u32x4*)(WT + (size_t)(n0 + n) * K + k0 + 8 * c) = o; }
;     LDS_WAIT();
	ds_read2_b32 v[34:35], v24 offset0:65 offset1:73
	ds_read2_b32 v[36:37], v24 offset1:8
	ds_read2_b32 v[38:39], v24 offset0:130 offset1:138
	ds_read2_b32 v[40:41], v24 offset0:195 offset1:203
	ds_read2_b32 v[42:43], v33 offset0:4 offset1:12
	ds_read2_b32 v[44:45], v33 offset0:69 offset1:77
	ds_read2_b32 v[46:47], v33 offset0:134 offset1:142
	ds_read2_b32 v[48:49], v33 offset0:199 offset1:207
	s_waitcnt lgkmcnt(6)
	v_cvt_pk_bf16_f32 v14, v36, v34
	v_or_b32_e32 v34, v69, v71
	v_lshlrev_b32_e32 v182, 12, v34
	s_waitcnt lgkmcnt(4)
	v_cvt_pk_bf16_f32 v15, v38, v40
	s_waitcnt lgkmcnt(2)
	v_cvt_pk_bf16_f32 v16, v42, v44
	s_waitcnt lgkmcnt(0)
	v_cvt_pk_bf16_f32 v17, v46, v48
	v_lshl_add_u64 v[52:53], v[50:51], 0, v[182:183]
	global_store_dwordx4 v[52:53], v[14:17], off nt
	v_or_b32_e32 v34, v25, v71
	v_lshlrev_b32_e32 v182, 12, v34
	v_cvt_pk_bf16_f32 v14, v37, v35
	v_cvt_pk_bf16_f32 v15, v39, v41
	v_cvt_pk_bf16_f32 v16, v43, v45
	v_cvt_pk_bf16_f32 v17, v47, v49
	ds_read2_b32 v[36:37], v24 offset0:81 offset1:89
	ds_read2_b32 v[38:39], v24 offset0:16 offset1:24
	ds_read2_b32 v[40:41], v24 offset0:146 offset1:154
	ds_read2_b32 v[42:43], v24 offset0:211 offset1:219
	ds_read2_b32 v[44:45], v33 offset0:20 offset1:28
	ds_read2_b32 v[46:47], v33 offset0:85 offset1:93
	ds_read2_b32 v[48:49], v33 offset0:150 offset1:158
	ds_read2_b32 v[52:53], v33 offset0:215 offset1:223
	v_lshl_add_u64 v[34:35], v[50:51], 0, v[182:183]
	global_store_dwordx4 v[34:35], v[14:17], off nt
	v_or_b32_e32 v34, v26, v71
	v_lshlrev_b32_e32 v182, 12, v34
	s_waitcnt lgkmcnt(6)
	v_cvt_pk_bf16_f32 v14, v38, v36
	s_waitcnt lgkmcnt(4)
	v_cvt_pk_bf16_f32 v15, v40, v42
	s_waitcnt lgkmcnt(2)
	v_cvt_pk_bf16_f32 v16, v44, v46
	s_waitcnt lgkmcnt(0)
	v_cvt_pk_bf16_f32 v17, v48, v52
	v_lshl_add_u64 v[34:35], v[50:51], 0, v[182:183]
	global_store_dwordx4 v[34:35], v[14:17], off nt
	v_or_b32_e32 v34, v27, v71
	v_lshlrev_b32_e32 v182, 12, v34
	v_cvt_pk_bf16_f32 v14, v39, v37
	v_cvt_pk_bf16_f32 v15, v41, v43
	v_cvt_pk_bf16_f32 v16, v45, v47
	v_cvt_pk_bf16_f32 v17, v49, v53
	ds_read2_b32 v[36:37], v24 offset0:32 offset1:40
	ds_read2_b32 v[38:39], v24 offset0:97 offset1:105
	ds_read2_b32 v[40:41], v24 offset0:162 offset1:170
	ds_read2_b32 v[42:43], v24 offset0:227 offset1:235
	ds_read2_b32 v[44:45], v33 offset0:36 offset1:44
	ds_read2_b32 v[46:47], v33 offset0:101 offset1:109
	ds_read2_b32 v[48:49], v33 offset0:166 offset1:174
	ds_read2_b32 v[52:53], v33 offset0:231 offset1:239
	v_lshl_add_u64 v[34:35], v[50:51], 0, v[182:183]
	global_store_dwordx4 v[34:35], v[14:17], off nt
	v_or_b32_e32 v34, v28, v71
	v_lshlrev_b32_e32 v182, 12, v34
	s_waitcnt lgkmcnt(6)
	v_cvt_pk_bf16_f32 v14, v36, v38
	s_waitcnt lgkmcnt(4)
	v_cvt_pk_bf16_f32 v15, v40, v42
	s_waitcnt lgkmcnt(2)
	v_cvt_pk_bf16_f32 v16, v44, v46
	s_waitcnt lgkmcnt(0)
	v_cvt_pk_bf16_f32 v17, v48, v52
	v_lshl_add_u64 v[34:35], v[50:51], 0, v[182:183]
	global_store_dwordx4 v[34:35], v[14:17], off nt
	v_or_b32_e32 v34, v29, v71
	v_lshlrev_b32_e32 v182, 12, v34
	v_cvt_pk_bf16_f32 v14, v37, v39
	v_cvt_pk_bf16_f32 v15, v41, v43
	v_cvt_pk_bf16_f32 v16, v45, v47
	v_cvt_pk_bf16_f32 v17, v49, v53
	ds_read2_b32 v[36:37], v24 offset0:48 offset1:56
	ds_read2_b32 v[38:39], v24 offset0:113 offset1:121
	ds_read2_b32 v[40:41], v24 offset0:178 offset1:186
	ds_read2_b32 v[42:43], v24 offset0:243 offset1:251
	ds_read2_b32 v[44:45], v33 offset0:52 offset1:60
	ds_read2_b32 v[46:47], v33 offset0:117 offset1:125
	ds_read2_b32 v[48:49], v33 offset0:182 offset1:190
	ds_read2_b32 v[52:53], v33 offset0:247 offset1:255
	v_or_b32_e32 v33, v30, v71
	v_lshl_add_u64 v[34:35], v[50:51], 0, v[182:183]
	v_lshlrev_b32_e32 v182, 12, v33
	v_or_b32_e32 v33, v31, v71
	global_store_dwordx4 v[34:35], v[14:17], off nt
	v_lshl_add_u64 v[34:35], v[50:51], 0, v[182:183]
	v_lshlrev_b32_e32 v182, 12, v33
	s_waitcnt lgkmcnt(6)
	v_cvt_pk_bf16_f32 v14, v36, v38
	s_waitcnt lgkmcnt(4)
	v_cvt_pk_bf16_f32 v15, v40, v42
	s_waitcnt lgkmcnt(2)
	v_cvt_pk_bf16_f32 v16, v44, v46
	s_waitcnt lgkmcnt(0)
	v_cvt_pk_bf16_f32 v17, v48, v52
	global_store_dwordx4 v[34:35], v[14:17], off nt
	v_lshl_add_u64 v[34:35], v[50:51], 0, v[182:183]
	s_nop 0
	v_cvt_pk_bf16_f32 v14, v37, v39
	v_cvt_pk_bf16_f32 v15, v41, v43
	v_cvt_pk_bf16_f32 v16, v45, v47
	v_cvt_pk_bf16_f32 v17, v49, v53
	global_store_dwordx4 v[34:35], v[14:17], off nt
	s_waitcnt lgkmcnt(0)
; #define LAS __attribute__((address_space(3)))
; __device__ __forceinline__ void transpose_item(const float* W, int ldw, int K, bf16_t* WT, int nblk, LAS float* scr, int item, int lane) {
;     ...
;     for (int i = 0; i < 16; ++i) v[i] = *(const f32x4*)(W + (size_t)(k0 + (lane >> 4) + 4 * i) * ldw + n0 + (lane & 15) * 4);
; #pragma unroll
;     for (int i = 0; i < 16; ++i) { LAS float* d = scr + ((lane >> 4) + 4 * i) * 65 + (lane & 15) * 4; d[0] = v[i][0]; d[1] = v[i][1]; d[2] = v[i][2]; d[3] = v[i][3]; }
; __device__ __forceinline__ void transpose_range(const Params& p, LAS unsigned char* lds, int l, int lo, int hi, int gw, int NGW, int wave, int lane) {
;     ...
;         if (r < TI_OUT) { transpose_item(p.w_out + (size_t)l * DM * DM, DM, DM, (bf16_t*)(ws + WS_WOUT + l * SZ_WOUT), DM / 64, scr, r, lane); continue; } r -= TI_OUT;
.LBB0_544:
	s_andn2_saveexec_b64 s[8:9], s[8:9]
	s_cbranch_execz .LBB0_546
	v_and_b32_e32 v33, 0x1ffc0, v32
	v_and_b32_e32 v71, 0x7c0, v1
	v_or_b32_e32 v16, v33, v68
	v_lshlrev_b32_e32 v182, 2, v71
	v_lshl_add_u64 v[14:15], v[10:11], 0, v[182:183]
	v_lshlrev_b32_e32 v182, 13, v16
	v_lshl_add_u64 v[66:67], v[14:15], 0, v[182:183]
	v_add_co_u32_e32 v34, vcc, 0x8000, v66
	v_lshlrev_b32_e32 v182, 1, v33
	s_nop 0
	v_addc_co_u32_e32 v35, vcc, 0, v67, vcc
	v_add_co_u32_e32 v38, vcc, s5, v66
	global_load_dwordx4 v[14:17], v[66:67], off nt
	s_nop 0
	global_load_dwordx4 v[34:37], v[34:35], off nt
	v_addc_co_u32_e32 v39, vcc, 0, v67, vcc
	v_add_co_u32_e32 v42, vcc, s61, v66
	v_add_u32_e32 v33, 0x400, v24
	s_nop 0
	v_addc_co_u32_e32 v43, vcc, 0, v67, vcc
	global_load_dwordx4 v[38:41], v[38:39], off nt
	s_nop 0
	global_load_dwordx4 v[42:45], v[42:43], off nt
	v_add_co_u32_e32 v46, vcc, 0x20000, v66
	s_nop 1
	v_addc_co_u32_e32 v47, vcc, 0, v67, vcc
	v_add_co_u32_e32 v50, vcc, 0x28000, v66
	s_nop 1
	v_addc_co_u32_e32 v51, vcc, 0, v67, vcc
	global_load_dwordx4 v[46:49], v[46:47], off nt
	s_nop 0
	global_load_dwordx4 v[50:53], v[50:51], off nt
	v_add_co_u32_e32 v54, vcc, 0x30000, v66
	s_nop 1
	v_addc_co_u32_e32 v55, vcc, 0, v67, vcc
	v_add_co_u32_e32 v58, vcc, 0x38000, v66
	s_nop 1
	v_addc_co_u32_e32 v59, vcc, 0, v67, vcc
	global_load_dwordx4 v[54:57], v[54:55], off nt
	s_nop 0
	global_load_dwordx4 v[58:61], v[58:59], off nt
	v_add_co_u32_e32 v62, vcc, 0x40000, v66
	s_nop 1
	v_addc_co_u32_e32 v63, vcc, 0, v67, vcc
	v_add_co_u32_e32 v72, vcc, 0x48000, v66
	s_nop 1
	v_addc_co_u32_e32 v73, vcc, 0, v67, vcc
	global_load_dwordx4 v[62:65], v[62:63], off nt
	s_nop 0
	global_load_dwordx4 v[72:75], v[72:73], off nt
	v_add_co_u32_e32 v76, vcc, 0x50000, v66
	s_nop 1
	v_addc_co_u32_e32 v77, vcc, 0, v67, vcc
	v_add_co_u32_e32 v80, vcc, s28, v66
	s_nop 1
	v_addc_co_u32_e32 v81, vcc, 0, v67, vcc
	global_load_dwordx4 v[76:79], v[76:77], off nt
	s_nop 0
	global_load_dwordx4 v[80:83], v[80:81], off nt
	v_add_co_u32_e32 v84, vcc, 0x60000, v66
	s_nop 1
	v_addc_co_u32_e32 v85, vcc, 0, v67, vcc
	v_add_co_u32_e32 v88, vcc, 0x68000, v66
	s_nop 1
	v_addc_co_u32_e32 v89, vcc, 0, v67, vcc
	global_load_dwordx4 v[84:87], v[84:85], off nt
	s_nop 0
	global_load_dwordx4 v[88:91], v[88:89], off nt
	v_add_co_u32_e32 v92, vcc, 0x70000, v66
	s_nop 1
	v_addc_co_u32_e32 v93, vcc, 0, v67, vcc
	global_load_dwordx4 v[92:95], v[92:93], off nt
	v_add_co_u32_e32 v66, vcc, 0x78000, v66
	s_nop 1
	v_addc_co_u32_e32 v67, vcc, 0, v67, vcc
	global_load_dwordx4 v[96:99], v[66:67], off nt
	s_waitcnt vmcnt(15)
	ds_write2_b32 v23, v14, v15 offset1:1
	ds_write2_b32 v23, v16, v17 offset0:2 offset1:3
	v_add_u32_e32 v14, 0x410, v23
	s_waitcnt vmcnt(14)
	ds_write2_b32 v14, v34, v35 offset1:1
	v_add_u32_e32 v14, 0x418, v23
	ds_write2_b32 v14, v36, v37 offset1:1
	v_add_u32_e32 v14, 0x820, v23
	s_waitcnt vmcnt(13)
	ds_write2_b32 v14, v38, v39 offset1:1
	v_add_u32_e32 v14, 0x828, v23
	ds_write2_b32 v14, v40, v41 offset1:1
	v_add_u32_e32 v14, 0xc30, v23
	s_waitcnt vmcnt(12)
	ds_write2_b32 v14, v42, v43 offset1:1
	v_add_u32_e32 v14, 0xc38, v23
	ds_write2_b32 v14, v44, v45 offset1:1
	v_add_u32_e32 v14, 0x1040, v23
	s_waitcnt vmcnt(11)
	ds_write2_b32 v14, v46, v47 offset1:1
	v_add_u32_e32 v14, 0x1048, v23
	ds_write2_b32 v14, v48, v49 offset1:1
	v_add_u32_e32 v14, 0x1450, v23
	s_waitcnt vmcnt(10)
	ds_write2_b32 v14, v50, v51 offset1:1
	v_add_u32_e32 v14, 0x1458, v23
	ds_write2_b32 v14, v52, v53 offset1:1
	v_add_u32_e32 v14, 0x1860, v23
	v_lshl_add_u64 v[50:51], v[4:5], 0, v[182:183]
	s_waitcnt vmcnt(9)
	ds_write2_b32 v14, v54, v55 offset1:1
	v_add_u32_e32 v14, 0x1868, v23
	ds_write2_b32 v14, v56, v57 offset1:1
	v_add_u32_e32 v14, 0x1c70, v23
	s_waitcnt vmcnt(8)
	ds_write2_b32 v14, v58, v59 offset1:1
	v_add_u32_e32 v14, 0x1c78, v23
	ds_write2_b32 v14, v60, v61 offset1:1
	v_add_u32_e32 v14, 0x2080, v23
	s_waitcnt vmcnt(7)
	ds_write2_b32 v14, v62, v63 offset1:1
	v_add_u32_e32 v14, 0x2088, v23
	ds_write2_b32 v14, v64, v65 offset1:1
	v_add_u32_e32 v14, 0x2490, v23
	s_waitcnt vmcnt(6)
	ds_write2_b32 v14, v72, v73 offset1:1
	v_add_u32_e32 v14, 0x2498, v23
	ds_write2_b32 v14, v74, v75 offset1:1
	v_add_u32_e32 v14, 0x28a0, v23
	s_waitcnt vmcnt(5)
	ds_write2_b32 v14, v76, v77 offset1:1
	v_add_u32_e32 v14, 0x28a8, v23
	ds_write2_b32 v14, v78, v79 offset1:1
	v_add_u32_e32 v14, 0x2cb0, v23
	s_waitcnt vmcnt(4)
	ds_write2_b32 v14, v80, v81 offset1:1
	v_add_u32_e32 v14, 0x2cb8, v23
	ds_write2_b32 v14, v82, v83 offset1:1
	v_add_u32_e32 v14, 0x30c0, v23
	s_waitcnt vmcnt(3)
	ds_write2_b32 v14, v84, v85 offset1:1
	v_add_u32_e32 v14, 0x30c8, v23
	ds_write2_b32 v14, v86, v87 offset1:1
	v_add_u32_e32 v14, 0x34d0, v23
	s_waitcnt vmcnt(2)
; #define LAS __attribute__((address_space(3)))
; __device__ __forceinline__ unsigned pk2(float lo, float hi) { const f32x2 v = {lo, hi}; const hwbf16x2 b = __builtin_convertvector(v, hwbf16x2); return __builtin_bit_cast(unsigned, b); }
; #define LDS_WAIT() asm volatile("s_waitcnt lgkmcnt(0)" ::: "memory")
; __device__ __forceinline__ void transpose_item(const float* W, int ldw, int K, bf16_t* WT, int nblk, LAS float* scr, int item, int lane) {
;     ...
;     LDS_WAIT();
;     const int c = lane & 7;
; #pragma unroll
;     for (int j = 0; j < 8; ++j) { const int n = (lane >> 3) + 8 * j; const LAS float* s = scr + (8 * c) * 65 + n;
;         u32x4 o; o.x = pk2(s[0 * 65], s[1 * 65]); o.y = pk2(s[2 * 65], s[3 * 65]); o.z = pk2(s[4 * 65], s[5 * 65]); o.w = pk2(s[6 * 65], s[7 * 65]);
;         *(u32x4*)(WT + (size_t)(n0 + n) * K + k0 + 8 * c) = o; }
;     LDS_WAIT();
	ds_write2_b32 v14, v88, v89 offset1:1
	v_add_u32_e32 v14, 0x34d8, v23
	ds_write2_b32 v14, v90, v91 offset1:1
	v_add_u32_e32 v14, 0x38e0, v23
	s_waitcnt vmcnt(1)
	ds_write2_b32 v14, v92, v93 offset1:1
	v_add_u32_e32 v14, 0x38e8, v23
	ds_write2_b32 v14, v94, v95 offset1:1
	v_add_u32_e32 v14, 0x3cf0, v23
	s_waitcnt vmcnt(0)
	ds_write2_b32 v14, v96, v97 offset1:1
	v_add_u32_e32 v14, 0x3cf8, v23
	ds_write2_b32 v14, v98, v99 offset1:1
	s_waitcnt lgkmcnt(0)
	ds_read2_b32 v[34:35], v24 offset0:65 offset1:73
	ds_read2_b32 v[36:37], v24 offset1:8
	ds_read2_b32 v[38:39], v24 offset0:130 offset1:138
	ds_read2_b32 v[40:41], v24 offset0:195 offset1:203
	ds_read2_b32 v[42:43], v33 offset0:4 offset1:12
	ds_read2_b32 v[44:45], v33 offset0:69 offset1:77
	ds_read2_b32 v[46:47], v33 offset0:134 offset1:142
	ds_read2_b32 v[48:49], v33 offset0:199 offset1:207
	s_waitcnt lgkmcnt(6)
	v_cvt_pk_bf16_f32 v14, v36, v34
	v_or_b32_e32 v34, v71, v69
	v_lshlrev_b32_e32 v182, 12, v34
	s_waitcnt lgkmcnt(4)
	v_cvt_pk_bf16_f32 v15, v38, v40
	s_waitcnt lgkmcnt(2)
	v_cvt_pk_bf16_f32 v16, v42, v44
	s_waitcnt lgkmcnt(0)
	v_cvt_pk_bf16_f32 v17, v46, v48
	v_lshl_add_u64 v[52:53], v[50:51], 0, v[182:183]
	global_store_dwordx4 v[52:53], v[14:17], off nt
	v_or_b32_e32 v34, v71, v25
	v_lshlrev_b32_e32 v182, 12, v34
	v_cvt_pk_bf16_f32 v14, v37, v35
	v_cvt_pk_bf16_f32 v15, v39, v41
	v_cvt_pk_bf16_f32 v16, v43, v45
	v_cvt_pk_bf16_f32 v17, v47, v49
	ds_read2_b32 v[36:37], v24 offset0:81 offset1:89
	ds_read2_b32 v[38:39], v24 offset0:16 offset1:24
	ds_read2_b32 v[40:41], v24 offset0:146 offset1:154
	ds_read2_b32 v[42:43], v24 offset0:211 offset1:219
	ds_read2_b32 v[44:45], v33 offset0:20 offset1:28
	ds_read2_b32 v[46:47], v33 offset0:85 offset1:93
	ds_read2_b32 v[48:49], v33 offset0:150 offset1:158
	ds_read2_b32 v[52:53], v33 offset0:215 offset1:223
	v_lshl_add_u64 v[34:35], v[50:51], 0, v[182:183]
	global_store_dwordx4 v[34:35], v[14:17], off nt
	v_or_b32_e32 v34, v71, v26
	v_lshlrev_b32_e32 v182, 12, v34
	s_waitcnt lgkmcnt(6)
	v_cvt_pk_bf16_f32 v14, v38, v36
	s_waitcnt lgkmcnt(4)
	v_cvt_pk_bf16_f32 v15, v40, v42
	s_waitcnt lgkmcnt(2)
	v_cvt_pk_bf16_f32 v16, v44, v46
	s_waitcnt lgkmcnt(0)
	v_cvt_pk_bf16_f32 v17, v48, v52
	v_lshl_add_u64 v[34:35], v[50:51], 0, v[182:183]
	global_store_dwordx4 v[34:35], v[14:17], off nt
	v_or_b32_e32 v34, v71, v27
	v_lshlrev_b32_e32 v182, 12, v34
	v_cvt_pk_bf16_f32 v14, v39, v37
	v_cvt_pk_bf16_f32 v15, v41, v43
	v_cvt_pk_bf16_f32 v16, v45, v47
	v_cvt_pk_bf16_f32 v17, v49, v53
	ds_read2_b32 v[36:37], v24 offset0:32 offset1:40
	ds_read2_b32 v[38:39], v24 offset0:97 offset1:105
	ds_read2_b32 v[40:41], v24 offset0:162 offset1:170
	ds_read2_b32 v[42:43], v24 offset0:227 offset1:235
	ds_read2_b32 v[44:45], v33 offset0:36 offset1:44
	ds_read2_b32 v[46:47], v33 offset0:101 offset1:109
	ds_read2_b32 v[48:49], v33 offset0:166 offset1:174
	ds_read2_b32 v[52:53], v33 offset0:231 offset1:239
	v_lshl_add_u64 v[34:35], v[50:51], 0, v[182:183]
	global_store_dwordx4 v[34:35], v[14:17], off nt
	v_or_b32_e32 v34, v71, v28
	v_lshlrev_b32_e32 v182, 12, v34
	s_waitcnt lgkmcnt(6)
	v_cvt_pk_bf16_f32 v14, v36, v38
	s_waitcnt lgkmcnt(4)
	v_cvt_pk_bf16_f32 v15, v40, v42
	s_waitcnt lgkmcnt(2)
	v_cvt_pk_bf16_f32 v16, v44, v46
	s_waitcnt lgkmcnt(0)
	v_cvt_pk_bf16_f32 v17, v48, v52
	v_lshl_add_u64 v[34:35], v[50:51], 0, v[182:183]
	global_store_dwordx4 v[34:35], v[14:17], off nt
	v_or_b32_e32 v34, v71, v29
	v_lshlrev_b32_e32 v182, 12, v34
	v_cvt_pk_bf16_f32 v14, v37, v39
	v_cvt_pk_bf16_f32 v15, v41, v43
	v_cvt_pk_bf16_f32 v16, v45, v47
	v_cvt_pk_bf16_f32 v17, v49, v53
	ds_read2_b32 v[36:37], v24 offset0:48 offset1:56
	ds_read2_b32 v[38:39], v24 offset0:113 offset1:121
	ds_read2_b32 v[40:41], v24 offset0:178 offset1:186
	ds_read2_b32 v[42:43], v24 offset0:243 offset1:251
	ds_read2_b32 v[44:45], v33 offset0:52 offset1:60
	ds_read2_b32 v[46:47], v33 offset0:117 offset1:125
	ds_read2_b32 v[48:49], v33 offset0:182 offset1:190
	ds_read2_b32 v[52:53], v33 offset0:247 offset1:255
	v_or_b32_e32 v33, v71, v30
	v_lshl_add_u64 v[34:35], v[50:51], 0, v[182:183]
	v_lshlrev_b32_e32 v182, 12, v33
	v_or_b32_e32 v33, v71, v31
	global_store_dwordx4 v[34:35], v[14:17], off nt
	v_lshl_add_u64 v[34:35], v[50:51], 0, v[182:183]
	v_lshlrev_b32_e32 v182, 12, v33
	s_waitcnt lgkmcnt(6)
	v_cvt_pk_bf16_f32 v14, v36, v38
	s_waitcnt lgkmcnt(4)
	v_cvt_pk_bf16_f32 v15, v40, v42
	s_waitcnt lgkmcnt(2)
	v_cvt_pk_bf16_f32 v16, v44, v46
	s_waitcnt lgkmcnt(0)
	v_cvt_pk_bf16_f32 v17, v48, v52
	global_store_dwordx4 v[34:35], v[14:17], off nt
	v_lshl_add_u64 v[34:35], v[50:51], 0, v[182:183]
	s_nop 0
	v_cvt_pk_bf16_f32 v14, v37, v39
	v_cvt_pk_bf16_f32 v15, v41, v43
	v_cvt_pk_bf16_f32 v16, v45, v47
	v_cvt_pk_bf16_f32 v17, v49, v53
	global_store_dwordx4 v[34:35], v[14:17], off nt
	s_waitcnt lgkmcnt(0)

; #define LAS __attribute__((address_space(3)))
; __device__ __forceinline__ void transpose_item(const float* W, int ldw, int K, bf16_t* WT, int nblk, LAS float* scr, int item, int lane) {
;     ...
;     for (int i = 0; i < 16; ++i) v[i] = *(const f32x4*)(W + (size_t)(k0 + (lane >> 4) + 4 * i) * ldw + n0 + (lane & 15) * 4);
; #pragma unroll
;     for (int i = 0; i < 16; ++i) { LAS float* d = scr + ((lane >> 4) + 4 * i) * 65 + (lane & 15) * 4; d[0] = v[i][0]; d[1] = v[i][1]; d[2] = v[i][2]; d[3] = v[i][3]; }
; __device__ __forceinline__ void transpose_range(const Params& p, LAS unsigned char* lds, int l, int lo, int hi, int gw, int NGW, int wave, int lane) {
;     ...
;         if (r < TI_IN) { transpose_item(p.w_in + (size_t)l * DM * INW, INW, DM, (bf16_t*)(ws + WS_WIN + l * SZ_WIN), ZW / 64, scr, r, lane); continue; } r -= TI_IN;
.LBB0_547:
	s_andn2_saveexec_b64 s[6:7], s[6:7]
	s_cbranch_execz .LBB0_540
	v_ashrrev_i32_e32 v14, 31, v22
	v_lshrrev_b32_e32 v14, 26, v14
	v_add_u32_e32 v15, v22, v14
	v_and_b32_e32 v14, 0xffffffc0, v15
	v_lshlrev_b32_e32 v15, 6, v15
	v_and_b32_e32 v15, 0xfffff000, v15
	v_sub_u32_e32 v16, v1, v15
	v_or_b32_e32 v15, v14, v68
	v_ashrrev_i32_e32 v17, 31, v16
	v_lshl_add_u64 v[66:67], v[16:17], 2, v[12:13]
	v_or_b32_e32 v17, 4, v15
	v_mad_i64_i32 v[34:35], s[8:9], v15, s21, v[66:67]
	v_mad_i64_i32 v[38:39], s[8:9], v17, s21, v[66:67]
	global_load_dwordx4 v[34:37], v[34:35], off nt
	v_or_b32_e32 v17, 8, v15
	global_load_dwordx4 v[38:41], v[38:39], off nt
	v_mad_i64_i32 v[42:43], s[8:9], v17, s21, v[66:67]
	global_load_dwordx4 v[42:45], v[42:43], off nt
	v_or_b32_e32 v17, 12, v15
	v_mad_i64_i32 v[46:47], s[8:9], v17, s21, v[66:67]
	global_load_dwordx4 v[46:49], v[46:47], off nt
	v_or_b32_e32 v17, 16, v15
	v_mad_i64_i32 v[50:51], s[8:9], v17, s21, v[66:67]
	global_load_dwordx4 v[50:53], v[50:51], off nt
	v_or_b32_e32 v17, 20, v15
	v_mad_i64_i32 v[54:55], s[8:9], v17, s21, v[66:67]
	global_load_dwordx4 v[54:57], v[54:55], off nt
	v_or_b32_e32 v17, 24, v15
	v_mad_i64_i32 v[58:59], s[8:9], v17, s21, v[66:67]
	global_load_dwordx4 v[58:61], v[58:59], off nt
	v_or_b32_e32 v17, 28, v15
	v_mad_i64_i32 v[62:63], s[8:9], v17, s21, v[66:67]
	global_load_dwordx4 v[62:65], v[62:63], off nt
	v_or_b32_e32 v17, 32, v15
	v_mad_i64_i32 v[72:73], s[8:9], v17, s21, v[66:67]
	global_load_dwordx4 v[72:75], v[72:73], off nt
	v_or_b32_e32 v17, 36, v15
	v_mad_i64_i32 v[76:77], s[8:9], v17, s21, v[66:67]
	global_load_dwordx4 v[76:79], v[76:77], off nt
	v_or_b32_e32 v17, 40, v15
	v_mad_i64_i32 v[80:81], s[8:9], v17, s21, v[66:67]
	global_load_dwordx4 v[80:83], v[80:81], off nt
	v_or_b32_e32 v17, 44, v15
	v_mad_i64_i32 v[84:85], s[8:9], v17, s21, v[66:67]
	global_load_dwordx4 v[84:87], v[84:85], off nt
	v_or_b32_e32 v17, 48, v15
	v_mad_i64_i32 v[88:89], s[8:9], v17, s21, v[66:67]
	global_load_dwordx4 v[88:91], v[88:89], off nt
	v_or_b32_e32 v17, 52, v15
	v_mad_i64_i32 v[92:93], s[8:9], v17, s21, v[66:67]
	global_load_dwordx4 v[92:95], v[92:93], off nt
	v_or_b32_e32 v17, 56, v15
	v_mad_i64_i32 v[96:97], s[8:9], v17, s21, v[66:67]
	global_load_dwordx4 v[96:99], v[96:97], off nt
	v_or_b32_e32 v15, 60, v15
	v_mad_i64_i32 v[66:67], s[8:9], v15, s21, v[66:67]
	global_load_dwordx4 v[100:103], v[66:67], off nt
	v_add_u32_e32 v15, 0x410, v23
	v_add_u32_e32 v33, 0x400, v24
	v_add_u32_e32 v16, v16, v69
	v_ashrrev_i32_e32 v17, 31, v16
	s_waitcnt vmcnt(15)
	ds_write2_b32 v23, v34, v35 offset1:1
	ds_write2_b32 v23, v36, v37 offset0:2 offset1:3
	s_waitcnt vmcnt(14)
	ds_write2_b32 v15, v38, v39 offset1:1
	v_add_u32_e32 v15, 0x418, v23
	ds_write2_b32 v15, v40, v41 offset1:1
	v_add_u32_e32 v15, 0x820, v23
	s_waitcnt vmcnt(13)
	ds_write2_b32 v15, v42, v43 offset1:1
	v_add_u32_e32 v15, 0x828, v23
	ds_write2_b32 v15, v44, v45 offset1:1
	v_add_u32_e32 v15, 0xc30, v23
	s_waitcnt vmcnt(12)
	ds_write2_b32 v15, v46, v47 offset1:1
	v_add_u32_e32 v15, 0xc38, v23
	ds_write2_b32 v15, v48, v49 offset1:1
	v_add_u32_e32 v15, 0x1040, v23
	s_waitcnt vmcnt(11)
	ds_write2_b32 v15, v50, v51 offset1:1
	v_add_u32_e32 v15, 0x1048, v23
	ds_write2_b32 v15, v52, v53 offset1:1
	v_add_u32_e32 v15, 0x1450, v23
	s_waitcnt vmcnt(10)
	ds_write2_b32 v15, v54, v55 offset1:1
	v_add_u32_e32 v15, 0x1458, v23
	ds_write2_b32 v15, v56, v57 offset1:1
	v_add_u32_e32 v15, 0x1860, v23
	s_waitcnt vmcnt(9)
	ds_write2_b32 v15, v58, v59 offset1:1
	v_add_u32_e32 v15, 0x1868, v23
	ds_write2_b32 v15, v60, v61 offset1:1
	v_add_u32_e32 v15, 0x1c70, v23
	s_waitcnt vmcnt(8)
	ds_write2_b32 v15, v62, v63 offset1:1
	v_add_u32_e32 v15, 0x1c78, v23
	ds_write2_b32 v15, v64, v65 offset1:1
	v_add_u32_e32 v15, 0x2080, v23
	s_waitcnt vmcnt(7)
	ds_write2_b32 v15, v72, v73 offset1:1
	v_add_u32_e32 v15, 0x2088, v23
	ds_write2_b32 v15, v74, v75 offset1:1
	v_add_u32_e32 v15, 0x2490, v23
	s_waitcnt vmcnt(6)
	ds_write2_b32 v15, v76, v77 offset1:1
	v_add_u32_e32 v15, 0x2498, v23
	ds_write2_b32 v15, v78, v79 offset1:1
	v_add_u32_e32 v15, 0x28a0, v23
	s_waitcnt vmcnt(5)
	ds_write2_b32 v15, v80, v81 offset1:1
	v_add_u32_e32 v15, 0x28a8, v23
	ds_write2_b32 v15, v82, v83 offset1:1
	v_add_u32_e32 v15, 0x2cb0, v23
	s_waitcnt vmcnt(4)
	ds_write2_b32 v15, v84, v85 offset1:1
	v_add_u32_e32 v15, 0x2cb8, v23
	ds_write2_b32 v15, v86, v87 offset1:1
	v_add_u32_e32 v15, 0x30c0, v23
	s_waitcnt vmcnt(3)
	ds_write2_b32 v15, v88, v89 offset1:1
	v_add_u32_e32 v15, 0x30c8, v23
	ds_write2_b32 v15, v90, v91 offset1:1
	v_add_u32_e32 v15, 0x34d0, v23
	s_waitcnt vmcnt(2)
	ds_write2_b32 v15, v92, v93 offset1:1
	v_add_u32_e32 v15, 0x34d8, v23
	ds_write2_b32 v15, v94, v95 offset1:1
	v_add_u32_e32 v15, 0x38e0, v23
	s_waitcnt vmcnt(1)
	ds_write2_b32 v15, v96, v97 offset1:1
	v_add_u32_e32 v15, 0x38e8, v23
	ds_write2_b32 v15, v98, v99 offset1:1
	v_add_u32_e32 v15, 0x3cf0, v23
	s_waitcnt vmcnt(0)
; #define LAS __attribute__((address_space(3)))
; __device__ __forceinline__ unsigned pk2(float lo, float hi) { const f32x2 v = {lo, hi}; const hwbf16x2 b = __builtin_convertvector(v, hwbf16x2); return __builtin_bit_cast(unsigned, b); }
; #define LDS_WAIT() asm volatile("s_waitcnt lgkmcnt(0)" ::: "memory")
; __device__ __forceinline__ void transpose_item(const float* W, int ldw, int K, bf16_t* WT, int nblk, LAS float* scr, int item, int lane) {
;     ...
;     LDS_WAIT();
;     const int c = lane & 7;
; #pragma unroll
;     for (int j = 0; j < 8; ++j) { const int n = (lane >> 3) + 8 * j; const LAS float* s = scr + (8 * c) * 65 + n;
;         u32x4 o; o.x = pk2(s[0 * 65], s[1 * 65]); o.y = pk2(s[2 * 65], s[3 * 65]); o.z = pk2(s[4 * 65], s[5 * 65]); o.w = pk2(s[6 * 65], s[7 * 65]);
;         *(u32x4*)(WT + (size_t)(n0 + n) * K + k0 + 8 * c) = o; }
;     LDS_WAIT();
	ds_write2_b32 v15, v100, v101 offset1:1
	v_add_u32_e32 v15, 0x3cf8, v23
	ds_write2_b32 v15, v102, v103 offset1:1
	s_waitcnt lgkmcnt(0)
	ds_read2_b32 v[38:39], v24 offset0:65 offset1:73
	ds_read2_b32 v[40:41], v24 offset1:8
	ds_read2_b32 v[42:43], v24 offset0:130 offset1:138
	ds_read2_b32 v[44:45], v24 offset0:195 offset1:203
	ds_read2_b32 v[46:47], v33 offset0:4 offset1:12
	ds_read2_b32 v[48:49], v33 offset0:69 offset1:77
	ds_read2_b32 v[50:51], v33 offset0:134 offset1:142
	ds_read2_b32 v[52:53], v33 offset0:199 offset1:207
	v_ashrrev_i32_e32 v15, 31, v14
	v_lshl_add_u64 v[14:15], v[14:15], 1, v[6:7]
	v_lshlrev_b64 v[54:55], 12, v[16:17]
	s_waitcnt lgkmcnt(6)
	v_cvt_pk_bf16_f32 v34, v40, v38
	s_waitcnt lgkmcnt(4)
	v_cvt_pk_bf16_f32 v35, v42, v44
	s_waitcnt lgkmcnt(2)
	v_cvt_pk_bf16_f32 v36, v46, v48
	s_waitcnt lgkmcnt(0)
	v_cvt_pk_bf16_f32 v37, v50, v52
	v_lshl_add_u64 v[54:55], v[14:15], 0, v[54:55]
	v_add_u32_e32 v38, 8, v16
	global_store_dwordx4 v[54:55], v[34:37], off nt
	v_add_u32_e32 v54, 16, v16
	v_ashrrev_i32_e32 v55, 31, v54
	v_cvt_pk_bf16_f32 v34, v41, v39
	v_ashrrev_i32_e32 v39, 31, v38
	v_lshlrev_b64 v[38:39], 12, v[38:39]
	v_cvt_pk_bf16_f32 v35, v43, v45
	v_cvt_pk_bf16_f32 v36, v47, v49
	v_cvt_pk_bf16_f32 v37, v51, v53
	v_lshl_add_u64 v[38:39], v[14:15], 0, v[38:39]
	global_store_dwordx4 v[38:39], v[34:37], off nt
	ds_read2_b32 v[38:39], v24 offset0:81 offset1:89
	ds_read2_b32 v[40:41], v24 offset0:16 offset1:24
	ds_read2_b32 v[42:43], v24 offset0:146 offset1:154
	ds_read2_b32 v[44:45], v24 offset0:211 offset1:219
	ds_read2_b32 v[46:47], v33 offset0:20 offset1:28
	ds_read2_b32 v[48:49], v33 offset0:85 offset1:93
	ds_read2_b32 v[50:51], v33 offset0:150 offset1:158
	ds_read2_b32 v[52:53], v33 offset0:215 offset1:223
	v_lshlrev_b64 v[54:55], 12, v[54:55]
	s_waitcnt lgkmcnt(6)
	v_cvt_pk_bf16_f32 v34, v40, v38
	s_waitcnt lgkmcnt(4)
	v_cvt_pk_bf16_f32 v35, v42, v44
	s_waitcnt lgkmcnt(2)
	v_cvt_pk_bf16_f32 v36, v46, v48
	s_waitcnt lgkmcnt(0)
	v_cvt_pk_bf16_f32 v37, v50, v52
	v_lshl_add_u64 v[54:55], v[14:15], 0, v[54:55]
	v_add_u32_e32 v38, 24, v16
	global_store_dwordx4 v[54:55], v[34:37], off nt
	v_add_u32_e32 v54, 32, v16
	v_ashrrev_i32_e32 v55, 31, v54
	v_cvt_pk_bf16_f32 v34, v41, v39
	v_ashrrev_i32_e32 v39, 31, v38
	v_lshlrev_b64 v[38:39], 12, v[38:39]
	v_cvt_pk_bf16_f32 v35, v43, v45
	v_cvt_pk_bf16_f32 v36, v47, v49
	v_cvt_pk_bf16_f32 v37, v51, v53
	v_lshl_add_u64 v[38:39], v[14:15], 0, v[38:39]
	global_store_dwordx4 v[38:39], v[34:37], off nt
	ds_read2_b32 v[38:39], v24 offset0:32 offset1:40
	ds_read2_b32 v[40:41], v24 offset0:97 offset1:105
	ds_read2_b32 v[42:43], v24 offset0:162 offset1:170
	ds_read2_b32 v[44:45], v24 offset0:227 offset1:235
	ds_read2_b32 v[46:47], v33 offset0:36 offset1:44
	ds_read2_b32 v[48:49], v33 offset0:101 offset1:109
	ds_read2_b32 v[50:51], v33 offset0:166 offset1:174
	ds_read2_b32 v[52:53], v33 offset0:231 offset1:239
	v_lshlrev_b64 v[54:55], 12, v[54:55]
	s_waitcnt lgkmcnt(6)
	v_cvt_pk_bf16_f32 v34, v38, v40
	s_waitcnt lgkmcnt(4)
	v_cvt_pk_bf16_f32 v35, v42, v44
	s_waitcnt lgkmcnt(2)
	v_cvt_pk_bf16_f32 v36, v46, v48
	s_waitcnt lgkmcnt(0)
	v_cvt_pk_bf16_f32 v37, v50, v52
	v_lshl_add_u64 v[54:55], v[14:15], 0, v[54:55]
	v_add_u32_e32 v38, 40, v16
	global_store_dwordx4 v[54:55], v[34:37], off nt
	v_add_u32_e32 v54, 48, v16
	v_ashrrev_i32_e32 v55, 31, v54
	v_cvt_pk_bf16_f32 v34, v39, v41
	v_ashrrev_i32_e32 v39, 31, v38
	v_lshlrev_b64 v[38:39], 12, v[38:39]
	v_cvt_pk_bf16_f32 v35, v43, v45
	v_cvt_pk_bf16_f32 v36, v47, v49
	v_cvt_pk_bf16_f32 v37, v51, v53
	v_lshl_add_u64 v[38:39], v[14:15], 0, v[38:39]
	global_store_dwordx4 v[38:39], v[34:37], off nt
	ds_read2_b32 v[38:39], v24 offset0:48 offset1:56
	ds_read2_b32 v[40:41], v24 offset0:113 offset1:121
	ds_read2_b32 v[42:43], v24 offset0:178 offset1:186
	ds_read2_b32 v[44:45], v24 offset0:243 offset1:251
	ds_read2_b32 v[46:47], v33 offset0:52 offset1:60
	ds_read2_b32 v[48:49], v33 offset0:117 offset1:125
	ds_read2_b32 v[50:51], v33 offset0:182 offset1:190
	ds_read2_b32 v[52:53], v33 offset0:247 offset1:255
	v_add_u32_e32 v16, 56, v16
	v_lshlrev_b64 v[54:55], 12, v[54:55]
	v_ashrrev_i32_e32 v17, 31, v16
	s_waitcnt lgkmcnt(6)
	v_cvt_pk_bf16_f32 v34, v38, v40
	s_waitcnt lgkmcnt(4)
	v_cvt_pk_bf16_f32 v35, v42, v44
	s_waitcnt lgkmcnt(2)
	v_cvt_pk_bf16_f32 v36, v46, v48
	s_waitcnt lgkmcnt(0)
	v_cvt_pk_bf16_f32 v37, v50, v52
	v_lshl_add_u64 v[54:55], v[14:15], 0, v[54:55]
	v_lshlrev_b64 v[16:17], 12, v[16:17]
	global_store_dwordx4 v[54:55], v[34:37], off nt
	v_lshl_add_u64 v[14:15], v[14:15], 0, v[16:17]
	s_nop 0
	v_cvt_pk_bf16_f32 v34, v39, v41
	v_cvt_pk_bf16_f32 v35, v43, v45
	v_cvt_pk_bf16_f32 v36, v47, v49
	v_cvt_pk_bf16_f32 v37, v51, v53
	global_store_dwordx4 v[14:15], v[34:37], off nt
	s_waitcnt lgkmcnt(0)
	s_branch .LBB0_540

; #define LAS __attribute__((address_space(3)))
; __device__ __forceinline__ void transpose_item(const float* W, int ldw, int K, bf16_t* WT, int nblk, LAS float* scr, int item, int lane) {
;     const int kb = item / nblk, nb = item % nblk, k0 = 64 * kb, n0 = 64 * nb;
;     f32x4 v[16];
; #pragma unroll
;     for (int i = 0; i < 16; ++i) v[i] = *(const f32x4*)(W + (size_t)(k0 + (lane >> 4) + 4 * i) * ldw + n0 + (lane & 15) * 4);
; #pragma unroll
;     for (int i = 0; i < 16; ++i) { LAS float* d = scr + ((lane >> 4) + 4 * i) * 65 + (lane & 15) * 4; d[0] = v[i][0]; d[1] = v[i][1]; d[2] = v[i][2]; d[3] = v[i][3]; }
; __device__ __forceinline__ void transpose_range(const Params& p, LAS unsigned char* lds, int l, int lo, int hi, int gw, int NGW, int wave, int lane) {
;     ...
;     for (int it = lo + gw; it < hi; it += NGW) {
;         int r = it;
;         if (r < TI_IN) { transpose_item(p.w_in + (size_t)l * DM * INW, INW, DM, (bf16_t*)(ws + WS_WIN + l * SZ_WIN), ZW / 64, scr, r, lane); continue; } r -= TI_IN;
.LBB0_551:
	v_ashrrev_i32_e32 v0, 31, v70
	v_lshrrev_b32_e32 v0, 26, v0
	v_add_u32_e32 v0, v70, v0
	v_and_b32_e32 v66, 0xffffffc0, v0
	v_lshlrev_b32_e32 v0, 6, v0
	v_and_b32_e32 v0, 0xfffff000, v0
	v_sub_u32_e32 v64, v72, v0
	v_ashrrev_i32_e32 v65, 31, v64
	v_or_b32_e32 v67, v66, v68
	v_lshl_add_u64 v[0:1], v[64:65], 2, v[62:63]
	v_mad_i64_i32 v[2:3], s[6:7], v67, s21, v[0:1]
	global_load_dwordx4 v[74:77], v[2:3], off nt
	v_or_b32_e32 v2, 4, v67
	v_mad_i64_i32 v[2:3], s[6:7], v2, s21, v[0:1]
	global_load_dwordx4 v[56:59], v[2:3], off nt
	v_or_b32_e32 v2, 8, v67
	v_mad_i64_i32 v[2:3], s[6:7], v2, s21, v[0:1]
	global_load_dwordx4 v[52:55], v[2:3], off nt
	v_or_b32_e32 v2, 12, v67
	v_mad_i64_i32 v[2:3], s[6:7], v2, s21, v[0:1]
	global_load_dwordx4 v[48:51], v[2:3], off nt
	v_or_b32_e32 v2, 16, v67
	v_mad_i64_i32 v[2:3], s[6:7], v2, s21, v[0:1]
	global_load_dwordx4 v[44:47], v[2:3], off nt
	v_or_b32_e32 v2, 20, v67
	v_mad_i64_i32 v[2:3], s[6:7], v2, s21, v[0:1]
	global_load_dwordx4 v[40:43], v[2:3], off nt
	v_or_b32_e32 v2, 24, v67
	v_mad_i64_i32 v[2:3], s[6:7], v2, s21, v[0:1]
	global_load_dwordx4 v[36:39], v[2:3], off nt
	v_or_b32_e32 v2, 28, v67
	v_mad_i64_i32 v[2:3], s[6:7], v2, s21, v[0:1]
	global_load_dwordx4 v[32:35], v[2:3], off nt
	v_or_b32_e32 v2, 32, v67
	v_mad_i64_i32 v[2:3], s[6:7], v2, s21, v[0:1]
	global_load_dwordx4 v[28:31], v[2:3], off nt
	v_or_b32_e32 v2, 36, v67
	v_mad_i64_i32 v[2:3], s[6:7], v2, s21, v[0:1]
	global_load_dwordx4 v[24:27], v[2:3], off nt
	v_or_b32_e32 v2, 40, v67
	v_mad_i64_i32 v[2:3], s[6:7], v2, s21, v[0:1]
	global_load_dwordx4 v[20:23], v[2:3], off nt
	v_or_b32_e32 v2, 44, v67
	v_mad_i64_i32 v[2:3], s[6:7], v2, s21, v[0:1]
	global_load_dwordx4 v[16:19], v[2:3], off nt
	v_or_b32_e32 v2, 48, v67
	v_mad_i64_i32 v[2:3], s[6:7], v2, s21, v[0:1]
	global_load_dwordx4 v[12:15], v[2:3], off nt
	v_or_b32_e32 v2, 52, v67
	v_mad_i64_i32 v[2:3], s[6:7], v2, s21, v[0:1]
	global_load_dwordx4 v[8:11], v[2:3], off nt
	v_or_b32_e32 v2, 56, v67
	v_mad_i64_i32 v[2:3], s[6:7], v2, s21, v[0:1]
	global_load_dwordx4 v[4:7], v[2:3], off nt
	v_or_b32_e32 v2, 60, v67
	v_mad_i64_i32 v[0:1], s[6:7], v2, s21, v[0:1]
	global_load_dwordx4 v[0:3], v[0:1], off nt
	v_add_u32_e32 v65, 0x410, v73
	v_ashrrev_i32_e32 v67, 31, v66
	v_cmp_lt_i32_e32 vcc, s67, v70
	v_add_u32_e32 v72, 0x10000, v72
	s_or_b64 s[2:3], vcc, s[2:3]
	s_waitcnt vmcnt(15)
	ds_write2_b32 v73, v74, v75 offset1:1
	ds_write2_b32 v73, v76, v77 offset0:2 offset1:3
	s_waitcnt vmcnt(14)
	ds_write2_b32 v65, v56, v57 offset1:1
	v_add_u32_e32 v56, 0x418, v73
	ds_write2_b32 v56, v58, v59 offset1:1
	v_add_u32_e32 v56, 0x820, v73
	s_waitcnt vmcnt(13)
	ds_write2_b32 v56, v52, v53 offset1:1
	v_add_u32_e32 v52, 0x828, v73
	ds_write2_b32 v52, v54, v55 offset1:1
	v_add_u32_e32 v52, 0xc30, v73
	s_waitcnt vmcnt(12)
	ds_write2_b32 v52, v48, v49 offset1:1
	v_add_u32_e32 v48, 0xc38, v73
	ds_write2_b32 v48, v50, v51 offset1:1
	v_add_u32_e32 v48, 0x1040, v73
	s_waitcnt vmcnt(11)
	ds_write2_b32 v48, v44, v45 offset1:1
	v_add_u32_e32 v44, 0x1048, v73
	ds_write2_b32 v44, v46, v47 offset1:1
	v_add_u32_e32 v44, 0x1450, v73
	s_waitcnt vmcnt(10)
	ds_write2_b32 v44, v40, v41 offset1:1
	v_add_u32_e32 v40, 0x1458, v73
	ds_write2_b32 v40, v42, v43 offset1:1
	v_add_u32_e32 v40, 0x1860, v73
	s_waitcnt vmcnt(9)
	ds_write2_b32 v40, v36, v37 offset1:1
	v_add_u32_e32 v36, 0x1868, v73
	ds_write2_b32 v36, v38, v39 offset1:1
	v_add_u32_e32 v36, 0x1c70, v73
	s_waitcnt vmcnt(8)
	ds_write2_b32 v36, v32, v33 offset1:1
	v_add_u32_e32 v32, 0x1c78, v73
	ds_write2_b32 v32, v34, v35 offset1:1
	v_add_u32_e32 v32, 0x2080, v73
	s_waitcnt vmcnt(7)
	ds_write2_b32 v32, v28, v29 offset1:1
	v_add_u32_e32 v28, 0x2088, v73
	ds_write2_b32 v28, v30, v31 offset1:1
	v_add_u32_e32 v28, 0x2490, v73
	s_waitcnt vmcnt(6)
	ds_write2_b32 v28, v24, v25 offset1:1
	v_add_u32_e32 v24, 0x2498, v73
	ds_write2_b32 v24, v26, v27 offset1:1
	v_add_u32_e32 v24, 0x28a0, v73
	s_waitcnt vmcnt(5)
	ds_write2_b32 v24, v20, v21 offset1:1
	v_add_u32_e32 v20, 0x28a8, v73
	ds_write2_b32 v20, v22, v23 offset1:1
	v_add_u32_e32 v20, 0x2cb0, v73
	s_waitcnt vmcnt(4)
	ds_write2_b32 v20, v16, v17 offset1:1
	v_add_u32_e32 v16, 0x2cb8, v73
	ds_write2_b32 v16, v18, v19 offset1:1
	v_add_u32_e32 v16, 0x30c0, v73
	s_waitcnt vmcnt(3)
	ds_write2_b32 v16, v12, v13 offset1:1
	v_add_u32_e32 v12, 0x30c8, v73
	ds_write2_b32 v12, v14, v15 offset1:1
	v_add_u32_e32 v12, 0x34d0, v73
	s_waitcnt vmcnt(2)
	ds_write2_b32 v12, v8, v9 offset1:1
	v_add_u32_e32 v8, 0x34d8, v73
	ds_write2_b32 v8, v10, v11 offset1:1
	v_add_u32_e32 v8, 0x38e0, v73
	s_waitcnt vmcnt(1)
	ds_write2_b32 v8, v4, v5 offset1:1
	v_add_u32_e32 v4, 0x38e8, v73
	ds_write2_b32 v4, v6, v7 offset1:1
	v_add_u32_e32 v4, 0x3cf0, v73
	s_waitcnt vmcnt(0)
; #define LAS __attribute__((address_space(3)))
; __device__ __forceinline__ unsigned pk2(float lo, float hi) { const f32x2 v = {lo, hi}; const hwbf16x2 b = __builtin_convertvector(v, hwbf16x2); return __builtin_bit_cast(unsigned, b); }
; #define LDS_WAIT() asm volatile("s_waitcnt lgkmcnt(0)" ::: "memory")
; __device__ __forceinline__ void transpose_item(const float* W, int ldw, int K, bf16_t* WT, int nblk, LAS float* scr, int item, int lane) {
;     ...
;     LDS_WAIT();
;     const int c = lane & 7;
; #pragma unroll
;     for (int j = 0; j < 8; ++j) { const int n = (lane >> 3) + 8 * j; const LAS float* s = scr + (8 * c) * 65 + n;
;         u32x4 o; o.x = pk2(s[0 * 65], s[1 * 65]); o.y = pk2(s[2 * 65], s[3 * 65]); o.z = pk2(s[4 * 65], s[5 * 65]); o.w = pk2(s[6 * 65], s[7 * 65]);
;         *(u32x4*)(WT + (size_t)(n0 + n) * K + k0 + 8 * c) = o; }
;     LDS_WAIT();
; __device__ __forceinline__ void transpose_range(const Params& p, LAS unsigned char* lds, int l, int lo, int hi, int gw, int NGW, int wave, int lane) {
;     ...
;     for (int it = lo + gw; it < hi; it += NGW) {
	ds_write2_b32 v4, v0, v1 offset1:1
	v_add_u32_e32 v0, 0x3cf8, v73
	ds_write2_b32 v0, v2, v3 offset1:1
	s_waitcnt lgkmcnt(0)
	v_add_u32_e32 v26, 0x400, v71
	ds_read2_b32 v[6:7], v71 offset0:65 offset1:73
	ds_read2_b32 v[8:9], v71 offset1:8
	ds_read2_b32 v[10:11], v71 offset0:130 offset1:138
	ds_read2_b32 v[12:13], v71 offset0:195 offset1:203
	ds_read2_b32 v[14:15], v26 offset0:4 offset1:12
	ds_read2_b32 v[16:17], v26 offset0:69 offset1:77
	ds_read2_b32 v[18:19], v26 offset0:134 offset1:142
	ds_read2_b32 v[20:21], v26 offset0:199 offset1:207
	v_add_u32_e32 v22, v64, v69
	v_ashrrev_i32_e32 v23, 31, v22
	v_lshl_add_u64 v[4:5], v[66:67], 1, v[60:61]
	v_lshlrev_b64 v[24:25], 12, v[22:23]
	s_waitcnt lgkmcnt(6)
	v_cvt_pk_bf16_f32 v0, v8, v6
	s_waitcnt lgkmcnt(4)
	v_cvt_pk_bf16_f32 v1, v10, v12
	s_waitcnt lgkmcnt(2)
	v_cvt_pk_bf16_f32 v2, v14, v16
	s_waitcnt lgkmcnt(0)
	v_cvt_pk_bf16_f32 v3, v18, v20
	v_lshl_add_u64 v[24:25], v[4:5], 0, v[24:25]
	v_add_u32_e32 v6, 8, v22
	global_store_dwordx4 v[24:25], v[0:3], off nt
	v_add_u32_e32 v24, 16, v22
	v_ashrrev_i32_e32 v25, 31, v24
	v_cvt_pk_bf16_f32 v0, v9, v7
	v_ashrrev_i32_e32 v7, 31, v6
	v_lshlrev_b64 v[6:7], 12, v[6:7]
	v_cvt_pk_bf16_f32 v1, v11, v13
	v_cvt_pk_bf16_f32 v2, v15, v17
	v_cvt_pk_bf16_f32 v3, v19, v21
	v_lshl_add_u64 v[6:7], v[4:5], 0, v[6:7]
	global_store_dwordx4 v[6:7], v[0:3], off nt
	ds_read2_b32 v[6:7], v71 offset0:81 offset1:89
	ds_read2_b32 v[8:9], v71 offset0:16 offset1:24
	ds_read2_b32 v[10:11], v71 offset0:146 offset1:154
	ds_read2_b32 v[12:13], v71 offset0:211 offset1:219
	ds_read2_b32 v[14:15], v26 offset0:20 offset1:28
	ds_read2_b32 v[16:17], v26 offset0:85 offset1:93
	ds_read2_b32 v[18:19], v26 offset0:150 offset1:158
	ds_read2_b32 v[20:21], v26 offset0:215 offset1:223
	v_lshlrev_b64 v[24:25], 12, v[24:25]
	s_waitcnt lgkmcnt(6)
	v_cvt_pk_bf16_f32 v0, v8, v6
	s_waitcnt lgkmcnt(4)
	v_cvt_pk_bf16_f32 v1, v10, v12
	s_waitcnt lgkmcnt(2)
	v_cvt_pk_bf16_f32 v2, v14, v16
	s_waitcnt lgkmcnt(0)
	v_cvt_pk_bf16_f32 v3, v18, v20
	v_lshl_add_u64 v[24:25], v[4:5], 0, v[24:25]
	v_add_u32_e32 v6, 24, v22
	global_store_dwordx4 v[24:25], v[0:3], off nt
	v_add_u32_e32 v24, 32, v22
	v_ashrrev_i32_e32 v25, 31, v24
	v_cvt_pk_bf16_f32 v0, v9, v7
	v_ashrrev_i32_e32 v7, 31, v6
	v_lshlrev_b64 v[6:7], 12, v[6:7]
	v_cvt_pk_bf16_f32 v1, v11, v13
	v_cvt_pk_bf16_f32 v2, v15, v17
	v_cvt_pk_bf16_f32 v3, v19, v21
	v_lshl_add_u64 v[6:7], v[4:5], 0, v[6:7]
	global_store_dwordx4 v[6:7], v[0:3], off nt
	ds_read2_b32 v[6:7], v71 offset0:32 offset1:40
	ds_read2_b32 v[8:9], v71 offset0:97 offset1:105
	ds_read2_b32 v[10:11], v71 offset0:162 offset1:170
	ds_read2_b32 v[12:13], v71 offset0:227 offset1:235
	ds_read2_b32 v[14:15], v26 offset0:36 offset1:44
	ds_read2_b32 v[16:17], v26 offset0:101 offset1:109
	ds_read2_b32 v[18:19], v26 offset0:166 offset1:174
	ds_read2_b32 v[20:21], v26 offset0:231 offset1:239
	v_lshlrev_b64 v[24:25], 12, v[24:25]
	s_waitcnt lgkmcnt(6)
	v_cvt_pk_bf16_f32 v0, v6, v8
	s_waitcnt lgkmcnt(4)
	v_cvt_pk_bf16_f32 v1, v10, v12
	s_waitcnt lgkmcnt(2)
	v_cvt_pk_bf16_f32 v2, v14, v16
	s_waitcnt lgkmcnt(0)
	v_cvt_pk_bf16_f32 v3, v18, v20
	v_lshl_add_u64 v[24:25], v[4:5], 0, v[24:25]
	v_add_u32_e32 v6, 40, v22
	global_store_dwordx4 v[24:25], v[0:3], off nt
	v_add_u32_e32 v24, 48, v22
	v_ashrrev_i32_e32 v25, 31, v24
	v_cvt_pk_bf16_f32 v0, v7, v9
	v_ashrrev_i32_e32 v7, 31, v6
	v_lshlrev_b64 v[6:7], 12, v[6:7]
	v_cvt_pk_bf16_f32 v1, v11, v13
	v_cvt_pk_bf16_f32 v2, v15, v17
	v_cvt_pk_bf16_f32 v3, v19, v21
	v_lshl_add_u64 v[6:7], v[4:5], 0, v[6:7]
	global_store_dwordx4 v[6:7], v[0:3], off nt
	ds_read2_b32 v[6:7], v71 offset0:48 offset1:56
	ds_read2_b32 v[8:9], v71 offset0:113 offset1:121
	ds_read2_b32 v[10:11], v71 offset0:178 offset1:186
	ds_read2_b32 v[12:13], v71 offset0:243 offset1:251
	ds_read2_b32 v[14:15], v26 offset0:52 offset1:60
	ds_read2_b32 v[16:17], v26 offset0:117 offset1:125
	ds_read2_b32 v[18:19], v26 offset0:182 offset1:190
	ds_read2_b32 v[20:21], v26 offset0:247 offset1:255
	v_lshlrev_b64 v[24:25], 12, v[24:25]
	s_waitcnt lgkmcnt(6)
	v_cvt_pk_bf16_f32 v0, v6, v8
	s_waitcnt lgkmcnt(4)
	v_cvt_pk_bf16_f32 v1, v10, v12
	s_waitcnt lgkmcnt(2)
	v_cvt_pk_bf16_f32 v2, v14, v16
	s_waitcnt lgkmcnt(0)
	v_cvt_pk_bf16_f32 v3, v18, v20
	v_lshl_add_u64 v[24:25], v[4:5], 0, v[24:25]
	v_add_u32_e32 v6, 56, v22
	global_store_dwordx4 v[24:25], v[0:3], off nt
	s_nop 1
	v_cvt_pk_bf16_f32 v0, v7, v9
	v_ashrrev_i32_e32 v7, 31, v6
	v_lshlrev_b64 v[6:7], 12, v[6:7]
	v_cvt_pk_bf16_f32 v1, v11, v13
	v_cvt_pk_bf16_f32 v2, v15, v17
	v_cvt_pk_bf16_f32 v3, v19, v21
	v_lshl_add_u64 v[4:5], v[4:5], 0, v[6:7]
	global_store_dwordx4 v[4:5], v[0:3], off nt
	s_waitcnt lgkmcnt(0)
	s_nop 1
	v_add_u32_e32 v0, 0x400, v70
	v_mov_b32_e32 v70, v0
	s_andn2_b64 exec, exec, s[2:3]
	s_cbranch_execnz .LBB0_551

; #define LAS __attribute__((address_space(3)))
; __device__ __forceinline__ void transpose_item(const float* W, int ldw, int K, bf16_t* WT, int nblk, LAS float* scr, int item, int lane) {
;     const int kb = item / nblk, nb = item % nblk, k0 = 64 * kb, n0 = 64 * nb;
;     f32x4 v[16];
; #pragma unroll
;     for (int i = 0; i < 16; ++i) v[i] = *(const f32x4*)(W + (size_t)(k0 + (lane >> 4) + 4 * i) * ldw + n0 + (lane & 15) * 4);
; #pragma unroll
;     for (int i = 0; i < 16; ++i) { LAS float* d = scr + ((lane >> 4) + 4 * i) * 65 + (lane & 15) * 4; d[0] = v[i][0]; d[1] = v[i][1]; d[2] = v[i][2]; d[3] = v[i][3]; }
; __device__ __forceinline__ void transpose_range(const Params& p, LAS unsigned char* lds, int l, int lo, int hi, int gw, int NGW, int wave, int lane) {
;     ...
;         transpose_item(p.ffn_down + (size_t)l * DFF * DM, DM, DFF, (bf16_t*)(ws + WS_WDN + l * SZ_WDN), DM / 64, scr, r, lane);
.LBB0_559:
	v_cmp_lt_i32_e32 vcc, s29, v47
	s_and_saveexec_b64 s[8:9], vcc
	s_xor_b64 s[8:9], exec, s[8:9]
	s_cbranch_execz .LBB0_569
	v_cmp_lt_u32_e32 vcc, s25, v47
	s_and_saveexec_b64 s[10:11], vcc
	s_xor_b64 s[10:11], exec, s[10:11]
	s_cbranch_execz .LBB0_566
	v_cmp_lt_u32_e32 vcc, s31, v47
	s_and_saveexec_b64 s[12:13], vcc
	s_xor_b64 s[12:13], exec, s[12:13]
	s_cbranch_execz .LBB0_563
	v_and_b32_e32 v48, 0x7fffffc0, v46
	v_add_u32_e32 v116, 0xffffbc00, v48
	v_and_b32_e32 v59, 0x7c0, v45
	v_or_b32_e32 v112, v116, v34
	v_lshlrev_b32_e32 v182, 2, v59
	v_lshl_add_u64 v[114:115], v[24:25], 0, v[182:183]
	v_or_b32_e32 v182, 4, v112
	v_lshlrev_b64 v[50:51], 13, v[182:183]
	v_or_b32_e32 v182, 8, v112
	v_lshlrev_b64 v[60:61], 13, v[182:183]
	v_or_b32_e32 v182, 12, v112
	v_lshlrev_b64 v[62:63], 13, v[182:183]
	v_or_b32_e32 v182, 16, v112
	v_mov_b32_e32 v113, v183
	v_lshlrev_b64 v[68:69], 13, v[182:183]
	v_or_b32_e32 v182, 20, v112
	v_lshlrev_b64 v[48:49], 13, v[112:113]
	v_lshlrev_b64 v[70:71], 13, v[182:183]
	v_or_b32_e32 v182, 24, v112
	v_lshl_add_u64 v[48:49], v[114:115], 0, v[48:49]
	v_lshl_add_u64 v[52:53], v[114:115], 0, v[50:51]
	v_lshl_add_u64 v[60:61], v[114:115], 0, v[60:61]
	v_lshl_add_u64 v[64:65], v[114:115], 0, v[62:63]
	v_lshl_add_u64 v[68:69], v[114:115], 0, v[68:69]
	v_lshl_add_u64 v[72:73], v[114:115], 0, v[70:71]
	v_lshlrev_b64 v[76:77], 13, v[182:183]
	global_load_dwordx4 v[48:51], v[48:49], off nt
	s_nop 0
	global_load_dwordx4 v[52:55], v[52:53], off nt
	s_nop 0
	global_load_dwordx4 v[60:63], v[60:61], off nt
	s_nop 0
	global_load_dwordx4 v[64:67], v[64:65], off nt
	s_nop 0
	global_load_dwordx4 v[68:71], v[68:69], off nt
	s_nop 0
	global_load_dwordx4 v[72:75], v[72:73], off nt
	v_lshl_add_u64 v[76:77], v[114:115], 0, v[76:77]
	v_or_b32_e32 v182, 28, v112
	global_load_dwordx4 v[76:79], v[76:77], off nt
	v_lshlrev_b64 v[80:81], 13, v[182:183]
	v_lshl_add_u64 v[80:81], v[114:115], 0, v[80:81]
	v_or_b32_e32 v182, 32, v112
	global_load_dwordx4 v[80:83], v[80:81], off nt
	v_lshlrev_b64 v[84:85], 13, v[182:183]
	v_lshl_add_u64 v[84:85], v[114:115], 0, v[84:85]
	v_or_b32_e32 v182, 36, v112
	global_load_dwordx4 v[84:87], v[84:85], off nt
	v_lshlrev_b64 v[88:89], 13, v[182:183]
	v_lshl_add_u64 v[88:89], v[114:115], 0, v[88:89]
	v_or_b32_e32 v182, 40, v112
	global_load_dwordx4 v[88:91], v[88:89], off nt
	v_lshlrev_b64 v[92:93], 13, v[182:183]
	v_lshl_add_u64 v[92:93], v[114:115], 0, v[92:93]
	v_or_b32_e32 v182, 44, v112
	global_load_dwordx4 v[92:95], v[92:93], off nt
	v_lshlrev_b64 v[96:97], 13, v[182:183]
	v_lshl_add_u64 v[96:97], v[114:115], 0, v[96:97]
	v_or_b32_e32 v182, 48, v112
	global_load_dwordx4 v[96:99], v[96:97], off nt
	v_lshlrev_b64 v[100:101], 13, v[182:183]
	v_lshl_add_u64 v[100:101], v[114:115], 0, v[100:101]
	v_or_b32_e32 v182, 52, v112
	global_load_dwordx4 v[100:103], v[100:101], off nt
	v_lshlrev_b64 v[104:105], 13, v[182:183]
	v_lshl_add_u64 v[104:105], v[114:115], 0, v[104:105]
	v_or_b32_e32 v182, 56, v112
	global_load_dwordx4 v[104:107], v[104:105], off nt
	v_lshlrev_b64 v[108:109], 13, v[182:183]
	v_lshl_add_u64 v[108:109], v[114:115], 0, v[108:109]
	v_or_b32_e32 v182, 60, v112
	global_load_dwordx4 v[108:111], v[108:109], off nt
	v_lshlrev_b64 v[112:113], 13, v[182:183]
	v_lshl_add_u64 v[112:113], v[114:115], 0, v[112:113]
	global_load_dwordx4 v[112:115], v[112:113], off nt
	v_add_u32_e32 v117, 0x410, v35
	v_add_u32_e32 v118, 0x418, v35
	v_add_u32_e32 v119, 0x820, v35
	v_add_u32_e32 v120, 0x828, v35
	v_add_u32_e32 v121, 0xc30, v35
	v_add_u32_e32 v122, 0xc38, v35
	v_add_u32_e32 v123, 0x1040, v35
	v_add_u32_e32 v124, 0x1048, v35
	v_add_u32_e32 v125, 0x1450, v35
	v_add_u32_e32 v126, 0x1458, v35
	s_waitcnt vmcnt(15)
	ds_write2_b32 v35, v48, v49 offset1:1
	ds_write2_b32 v35, v50, v51 offset0:2 offset1:3
	s_waitcnt vmcnt(14)
	ds_write2_b32 v117, v52, v53 offset1:1
	ds_write2_b32 v118, v54, v55 offset1:1
	s_waitcnt vmcnt(13)
	ds_write2_b32 v119, v60, v61 offset1:1
	ds_write2_b32 v120, v62, v63 offset1:1
	s_waitcnt vmcnt(12)
	ds_write2_b32 v121, v64, v65 offset1:1
	ds_write2_b32 v122, v66, v67 offset1:1
	s_waitcnt vmcnt(11)
	ds_write2_b32 v123, v68, v69 offset1:1
	ds_write2_b32 v124, v70, v71 offset1:1
	s_waitcnt vmcnt(10)
	ds_write2_b32 v125, v72, v73 offset1:1
	ds_write2_b32 v126, v74, v75 offset1:1
	v_add_u32_e32 v48, 0x1860, v35
	v_mov_b32_e32 v117, v183
	s_waitcnt vmcnt(9)
	ds_write2_b32 v48, v76, v77 offset1:1
	v_add_u32_e32 v48, 0x1868, v35
	ds_write2_b32 v48, v78, v79 offset1:1
	v_add_u32_e32 v48, 0x1c70, v35
	s_waitcnt vmcnt(8)
	ds_write2_b32 v48, v80, v81 offset1:1
	v_add_u32_e32 v48, 0x1c78, v35
	ds_write2_b32 v48, v82, v83 offset1:1
	v_add_u32_e32 v48, 0x2080, v35
	s_waitcnt vmcnt(7)
	ds_write2_b32 v48, v84, v85 offset1:1
	v_add_u32_e32 v48, 0x2088, v35
	ds_write2_b32 v48, v86, v87 offset1:1
	v_add_u32_e32 v48, 0x2490, v35
	s_waitcnt vmcnt(6)
	ds_write2_b32 v48, v88, v89 offset1:1
	v_add_u32_e32 v48, 0x2498, v35
	ds_write2_b32 v48, v90, v91 offset1:1
	v_add_u32_e32 v48, 0x28a0, v35
	s_waitcnt vmcnt(5)
	ds_write2_b32 v48, v92, v93 offset1:1
	v_add_u32_e32 v48, 0x28a8, v35
	ds_write2_b32 v48, v94, v95 offset1:1
	v_add_u32_e32 v48, 0x2cb0, v35
	s_waitcnt vmcnt(4)
	ds_write2_b32 v48, v96, v97 offset1:1
	v_add_u32_e32 v48, 0x2cb8, v35
	ds_write2_b32 v48, v98, v99 offset1:1
	v_add_u32_e32 v48, 0x30c0, v35
	s_waitcnt vmcnt(3)
	ds_write2_b32 v48, v100, v101 offset1:1
	v_add_u32_e32 v48, 0x30c8, v35
	ds_write2_b32 v48, v102, v103 offset1:1
	v_add_u32_e32 v48, 0x34d0, v35
	s_waitcnt vmcnt(2)
	ds_write2_b32 v48, v104, v105 offset1:1
	v_add_u32_e32 v48, 0x34d8, v35
	ds_write2_b32 v48, v106, v107 offset1:1
	v_add_u32_e32 v48, 0x38e0, v35
	s_waitcnt vmcnt(1)
; #define LAS __attribute__((address_space(3)))
; __device__ __forceinline__ unsigned pk2(float lo, float hi) { const f32x2 v = {lo, hi}; const hwbf16x2 b = __builtin_convertvector(v, hwbf16x2); return __builtin_bit_cast(unsigned, b); }
; #define LDS_WAIT() asm volatile("s_waitcnt lgkmcnt(0)" ::: "memory")
; __device__ __forceinline__ void transpose_item(const float* W, int ldw, int K, bf16_t* WT, int nblk, LAS float* scr, int item, int lane) {
;     ...
;     for (int i = 0; i < 16; ++i) { LAS float* d = scr + ((lane >> 4) + 4 * i) * 65 + (lane & 15) * 4; d[0] = v[i][0]; d[1] = v[i][1]; d[2] = v[i][2]; d[3] = v[i][3]; }
;     LDS_WAIT();
;     const int c = lane & 7;
; #pragma unroll
;     for (int j = 0; j < 8; ++j) { const int n = (lane >> 3) + 8 * j; const LAS float* s = scr + (8 * c) * 65 + n;
;         u32x4 o; o.x = pk2(s[0 * 65], s[1 * 65]); o.y = pk2(s[2 * 65], s[3 * 65]); o.z = pk2(s[4 * 65], s[5 * 65]); o.w = pk2(s[6 * 65], s[7 * 65]);
;         *(u32x4*)(WT + (size_t)(n0 + n) * K + k0 + 8 * c) = o; }
;     LDS_WAIT();
	ds_write2_b32 v48, v108, v109 offset1:1
	v_add_u32_e32 v48, 0x38e8, v35
	ds_write2_b32 v48, v110, v111 offset1:1
	v_add_u32_e32 v48, 0x3cf0, v35
	s_waitcnt vmcnt(0)
	ds_write2_b32 v48, v112, v113 offset1:1
	v_add_u32_e32 v48, 0x3cf8, v35
	ds_write2_b32 v48, v114, v115 offset1:1
	s_waitcnt lgkmcnt(0)
	ds_read2_b32 v[52:53], v37 offset0:65 offset1:73
	ds_read2_b32 v[54:55], v37 offset1:8
	ds_read2_b32 v[60:61], v37 offset0:130 offset1:138
	ds_read2_b32 v[62:63], v37 offset0:195 offset1:203
	v_add_u32_e32 v76, 0x400, v37
	ds_read2_b32 v[64:65], v76 offset0:4 offset1:12
	ds_read2_b32 v[66:67], v76 offset0:69 offset1:77
	ds_read2_b32 v[68:69], v76 offset0:134 offset1:142
	ds_read2_b32 v[70:71], v76 offset0:199 offset1:207
	s_waitcnt lgkmcnt(6)
	v_cvt_pk_bf16_f32 v48, v54, v52
	v_or_b32_e32 v52, v59, v36
	v_mul_u32_u24_e32 v52, 0x1600, v52
	v_lshl_add_u64 v[72:73], v[116:117], 1, v[16:17]
	v_lshlrev_b32_e32 v182, 1, v52
	s_waitcnt lgkmcnt(4)
	v_cvt_pk_bf16_f32 v49, v60, v62
	s_waitcnt lgkmcnt(2)
	v_cvt_pk_bf16_f32 v50, v64, v66
	s_waitcnt lgkmcnt(0)
	v_cvt_pk_bf16_f32 v51, v68, v70
	v_lshl_add_u64 v[74:75], v[72:73], 0, v[182:183]
	v_or_b32_e32 v52, v59, v38
	global_store_dwordx4 v[74:75], v[48:51], off nt
	v_mul_u32_u24_e32 v52, 0x1600, v52
	v_lshlrev_b32_e32 v182, 1, v52
	v_cvt_pk_bf16_f32 v48, v55, v53
	v_cvt_pk_bf16_f32 v49, v61, v63
	v_cvt_pk_bf16_f32 v50, v65, v67
	v_cvt_pk_bf16_f32 v51, v69, v71
	ds_read2_b32 v[54:55], v37 offset0:16 offset1:24
	ds_read2_b32 v[60:61], v37 offset0:81 offset1:89
	ds_read2_b32 v[62:63], v37 offset0:146 offset1:154
	ds_read2_b32 v[64:65], v37 offset0:211 offset1:219
	ds_read2_b32 v[66:67], v76 offset0:20 offset1:28
	ds_read2_b32 v[68:69], v76 offset0:85 offset1:93
	ds_read2_b32 v[70:71], v76 offset0:150 offset1:158
	ds_read2_b32 v[74:75], v76 offset0:215 offset1:223
	v_lshl_add_u64 v[52:53], v[72:73], 0, v[182:183]
	global_store_dwordx4 v[52:53], v[48:51], off nt
	v_or_b32_e32 v52, v59, v39
	v_mul_u32_u24_e32 v52, 0x1600, v52
	v_lshlrev_b32_e32 v182, 1, v52
	s_waitcnt lgkmcnt(6)
	v_cvt_pk_bf16_f32 v48, v54, v60
	s_waitcnt lgkmcnt(4)
	v_cvt_pk_bf16_f32 v49, v62, v64
	s_waitcnt lgkmcnt(2)
	v_cvt_pk_bf16_f32 v50, v66, v68
	s_waitcnt lgkmcnt(0)
	v_cvt_pk_bf16_f32 v51, v70, v74
	v_lshl_add_u64 v[52:53], v[72:73], 0, v[182:183]
	global_store_dwordx4 v[52:53], v[48:51], off nt
	v_or_b32_e32 v52, v59, v40
	v_mul_u32_u24_e32 v52, 0x1600, v52
	v_cvt_pk_bf16_f32 v48, v55, v61
	v_cvt_pk_bf16_f32 v49, v63, v65
	v_cvt_pk_bf16_f32 v50, v67, v69
	v_cvt_pk_bf16_f32 v51, v71, v75
	v_lshlrev_b32_e32 v182, 1, v52
	ds_read2_b32 v[54:55], v37 offset0:32 offset1:40
	ds_read2_b32 v[60:61], v37 offset0:97 offset1:105
	ds_read2_b32 v[62:63], v37 offset0:162 offset1:170
	ds_read2_b32 v[64:65], v37 offset0:227 offset1:235
	ds_read2_b32 v[66:67], v76 offset0:36 offset1:44
	ds_read2_b32 v[68:69], v76 offset0:101 offset1:109
	ds_read2_b32 v[70:71], v76 offset0:166 offset1:174
	ds_read2_b32 v[74:75], v76 offset0:231 offset1:239
	v_lshl_add_u64 v[52:53], v[72:73], 0, v[182:183]
	global_store_dwordx4 v[52:53], v[48:51], off nt
	v_or_b32_e32 v52, v59, v41
	v_mul_u32_u24_e32 v52, 0x1600, v52
	v_lshlrev_b32_e32 v182, 1, v52
	s_waitcnt lgkmcnt(6)
	v_cvt_pk_bf16_f32 v48, v54, v60
	s_waitcnt lgkmcnt(4)
	v_cvt_pk_bf16_f32 v49, v62, v64
	s_waitcnt lgkmcnt(2)
	v_cvt_pk_bf16_f32 v50, v66, v68
	s_waitcnt lgkmcnt(0)
	v_cvt_pk_bf16_f32 v51, v70, v74
	v_lshl_add_u64 v[52:53], v[72:73], 0, v[182:183]
	global_store_dwordx4 v[52:53], v[48:51], off nt
	v_or_b32_e32 v52, v59, v42
	v_mul_u32_u24_e32 v52, 0x1600, v52
	v_cvt_pk_bf16_f32 v48, v55, v61
	v_cvt_pk_bf16_f32 v49, v63, v65
	v_cvt_pk_bf16_f32 v50, v67, v69
	v_cvt_pk_bf16_f32 v51, v71, v75
	v_lshlrev_b32_e32 v182, 1, v52
	ds_read2_b32 v[54:55], v37 offset0:48 offset1:56
	ds_read2_b32 v[60:61], v37 offset0:113 offset1:121
	ds_read2_b32 v[62:63], v37 offset0:178 offset1:186
	ds_read2_b32 v[64:65], v37 offset0:243 offset1:251
	ds_read2_b32 v[66:67], v76 offset0:52 offset1:60
	ds_read2_b32 v[68:69], v76 offset0:117 offset1:125
	ds_read2_b32 v[70:71], v76 offset0:182 offset1:190
	ds_read2_b32 v[74:75], v76 offset0:247 offset1:255
	v_lshl_add_u64 v[52:53], v[72:73], 0, v[182:183]
	global_store_dwordx4 v[52:53], v[48:51], off nt
	v_or_b32_e32 v52, v59, v43
	v_mul_u32_u24_e32 v52, 0x1600, v52
	v_lshlrev_b32_e32 v182, 1, v52
	s_waitcnt lgkmcnt(6)
	v_cvt_pk_bf16_f32 v48, v54, v60
	s_waitcnt lgkmcnt(4)
	v_cvt_pk_bf16_f32 v49, v62, v64
	s_waitcnt lgkmcnt(2)
	v_cvt_pk_bf16_f32 v50, v66, v68
	s_waitcnt lgkmcnt(0)
	v_cvt_pk_bf16_f32 v51, v70, v74
	v_lshl_add_u64 v[52:53], v[72:73], 0, v[182:183]
	global_store_dwordx4 v[52:53], v[48:51], off nt
	v_or_b32_e32 v52, v59, v44
	v_mul_u32_u24_e32 v52, 0x1600, v52
	v_lshlrev_b32_e32 v182, 1, v52
	v_cvt_pk_bf16_f32 v48, v55, v61
	v_cvt_pk_bf16_f32 v49, v63, v65
	v_cvt_pk_bf16_f32 v50, v67, v69
	v_cvt_pk_bf16_f32 v51, v71, v75
	v_lshl_add_u64 v[52:53], v[72:73], 0, v[182:183]
	global_store_dwordx4 v[52:53], v[48:51], off nt
	s_waitcnt lgkmcnt(0)
; #define LAS __attribute__((address_space(3)))
; __device__ __forceinline__ void transpose_item(const float* W, int ldw, int K, bf16_t* WT, int nblk, LAS float* scr, int item, int lane) {
;     ...
;     for (int i = 0; i < 16; ++i) v[i] = *(const f32x4*)(W + (size_t)(k0 + (lane >> 4) + 4 * i) * ldw + n0 + (lane & 15) * 4);
; #pragma unroll
;     for (int i = 0; i < 16; ++i) { LAS float* d = scr + ((lane >> 4) + 4 * i) * 65 + (lane & 15) * 4; d[0] = v[i][0]; d[1] = v[i][1]; d[2] = v[i][2]; d[3] = v[i][3]; }
; __device__ __forceinline__ void transpose_range(const Params& p, LAS unsigned char* lds, int l, int lo, int hi, int gw, int NGW, int wave, int lane) {
;     ...
;         if (r < TI_UP) { transpose_item(p.ffn_up + (size_t)l * DM * DFF2, DFF2, DM, (bf16_t*)(ws + WS_WUP + l * SZ_WUP), DFF2 / 64, scr, r, lane); continue; } r -= TI_UP;
.LBB0_563:
	s_andn2_saveexec_b64 s[12:13], s[12:13]
	s_cbranch_execz .LBB0_565
	v_add_u16_e32 v48, 0xf400, v47
	v_mul_u32_u24_e32 v49, 0xba2f, v48
	v_lshrrev_b32_e32 v49, 23, v49
	v_mul_lo_u16_e32 v50, 0xb0, v49
	v_sub_u16_e32 v48, v48, v50
	v_lshlrev_b16_e32 v59, 6, v49
	v_lshlrev_b16_e32 v116, 6, v48
	v_or_b32_e32 v50, v34, v59
	v_lshlrev_b32_e32 v182, 2, v116
	v_mul_u32_u24_e32 v50, 0x2c00, v50
	v_lshl_add_u64 v[48:49], v[26:27], 0, v[182:183]
	v_lshlrev_b32_e32 v182, 2, v50
	v_lshl_add_u64 v[112:113], v[48:49], 0, v[182:183]
	v_add_co_u32_e32 v52, vcc, s58, v112
	s_mov_b32 s26, 0x18c000
	s_nop 0
	v_addc_co_u32_e32 v53, vcc, 0, v113, vcc
	v_add_co_u32_e32 v60, vcc, s28, v112
	global_load_dwordx4 v[48:51], v[112:113], off nt
	s_nop 0
	global_load_dwordx4 v[52:55], v[52:53], off nt
	v_addc_co_u32_e32 v61, vcc, 0, v113, vcc
	v_add_co_u32_e32 v64, vcc, s59, v112
	v_lshlrev_b32_e32 v182, 1, v59
	s_nop 0
	v_addc_co_u32_e32 v65, vcc, 0, v113, vcc
	global_load_dwordx4 v[60:63], v[60:61], off nt
	s_nop 0
	global_load_dwordx4 v[64:67], v[64:65], off nt
	v_add_co_u32_e32 v68, vcc, s64, v112
	v_add_u32_e32 v59, 0x400, v37
	s_nop 0
	v_addc_co_u32_e32 v69, vcc, 0, v113, vcc
	v_add_co_u32_e32 v72, vcc, s65, v112
	s_nop 1
	v_addc_co_u32_e32 v73, vcc, 0, v113, vcc
	global_load_dwordx4 v[68:71], v[68:69], off nt
	s_nop 0
	global_load_dwordx4 v[72:75], v[72:73], off nt
	v_add_co_u32_e32 v76, vcc, s66, v112
	s_nop 1
	v_addc_co_u32_e32 v77, vcc, 0, v113, vcc
	v_add_co_u32_e32 v80, vcc, s68, v112
	s_nop 1
	v_addc_co_u32_e32 v81, vcc, 0, v113, vcc
	global_load_dwordx4 v[76:79], v[76:77], off nt
	s_nop 0
	global_load_dwordx4 v[80:83], v[80:81], off nt
	v_add_co_u32_e32 v84, vcc, s69, v112
	s_nop 1
	v_addc_co_u32_e32 v85, vcc, 0, v113, vcc
	v_add_co_u32_e32 v88, vcc, s26, v112
	s_mov_b32 s26, 0x1b8000
	s_nop 0
	v_addc_co_u32_e32 v89, vcc, 0, v113, vcc
	global_load_dwordx4 v[84:87], v[84:85], off nt
	s_nop 0
	global_load_dwordx4 v[88:91], v[88:89], off nt
	v_add_co_u32_e32 v92, vcc, s26, v112
	s_mov_b32 s26, 0x1e4000
	s_nop 0
	v_addc_co_u32_e32 v93, vcc, 0, v113, vcc
	v_add_co_u32_e32 v96, vcc, s26, v112
	s_mov_b32 s26, 0x210000
	s_nop 0
	v_addc_co_u32_e32 v97, vcc, 0, v113, vcc
	global_load_dwordx4 v[92:95], v[92:93], off nt
	s_nop 0
	global_load_dwordx4 v[96:99], v[96:97], off nt
	v_add_co_u32_e32 v100, vcc, s26, v112
	s_mov_b32 s26, 0x23c000
	s_nop 0
	v_addc_co_u32_e32 v101, vcc, 0, v113, vcc
	v_add_co_u32_e32 v104, vcc, s26, v112
	s_mov_b32 s26, 0x268000
	s_nop 0
	v_addc_co_u32_e32 v105, vcc, 0, v113, vcc
	global_load_dwordx4 v[100:103], v[100:101], off nt
	s_nop 0
	global_load_dwordx4 v[104:107], v[104:105], off nt
	v_add_co_u32_e32 v108, vcc, s26, v112
	s_mov_b32 s26, 0x294000
	s_nop 0
	v_addc_co_u32_e32 v109, vcc, 0, v113, vcc
	global_load_dwordx4 v[108:111], v[108:109], off nt
	v_add_co_u32_e32 v112, vcc, s26, v112
	s_nop 1
	v_addc_co_u32_e32 v113, vcc, 0, v113, vcc
	global_load_dwordx4 v[112:115], v[112:113], off nt
	s_waitcnt vmcnt(15)
	ds_write2_b32 v35, v48, v49 offset1:1
	ds_write2_b32 v35, v50, v51 offset0:2 offset1:3
	v_add_u32_e32 v48, 0x410, v35
	s_waitcnt vmcnt(14)
	ds_write2_b32 v48, v52, v53 offset1:1
	v_add_u32_e32 v48, 0x418, v35
	ds_write2_b32 v48, v54, v55 offset1:1
	v_add_u32_e32 v48, 0x820, v35
	s_waitcnt vmcnt(13)
	ds_write2_b32 v48, v60, v61 offset1:1
	v_add_u32_e32 v48, 0x828, v35
	ds_write2_b32 v48, v62, v63 offset1:1
	v_add_u32_e32 v48, 0xc30, v35
	s_waitcnt vmcnt(12)
	ds_write2_b32 v48, v64, v65 offset1:1
	v_add_u32_e32 v48, 0xc38, v35
	ds_write2_b32 v48, v66, v67 offset1:1
	v_add_u32_e32 v48, 0x1040, v35
	s_waitcnt vmcnt(11)
	ds_write2_b32 v48, v68, v69 offset1:1
	v_add_u32_e32 v48, 0x1048, v35
	ds_write2_b32 v48, v70, v71 offset1:1
	v_add_u32_e32 v48, 0x1450, v35
	s_waitcnt vmcnt(10)
	ds_write2_b32 v48, v72, v73 offset1:1
	v_add_u32_e32 v48, 0x1458, v35
	ds_write2_b32 v48, v74, v75 offset1:1
	v_add_u32_e32 v48, 0x1860, v35
	v_lshl_add_u64 v[72:73], v[18:19], 0, v[182:183]
	s_waitcnt vmcnt(9)
	ds_write2_b32 v48, v76, v77 offset1:1
	v_add_u32_e32 v48, 0x1868, v35
	ds_write2_b32 v48, v78, v79 offset1:1
	v_add_u32_e32 v48, 0x1c70, v35
	s_waitcnt vmcnt(8)
	ds_write2_b32 v48, v80, v81 offset1:1
	v_add_u32_e32 v48, 0x1c78, v35
	ds_write2_b32 v48, v82, v83 offset1:1
	v_add_u32_e32 v48, 0x2080, v35
	s_waitcnt vmcnt(7)
	ds_write2_b32 v48, v84, v85 offset1:1
	v_add_u32_e32 v48, 0x2088, v35
	ds_write2_b32 v48, v86, v87 offset1:1
	v_add_u32_e32 v48, 0x2490, v35
	s_waitcnt vmcnt(6)
	ds_write2_b32 v48, v88, v89 offset1:1
	v_add_u32_e32 v48, 0x2498, v35
	ds_write2_b32 v48, v90, v91 offset1:1
	v_add_u32_e32 v48, 0x28a0, v35
	s_waitcnt vmcnt(5)
	ds_write2_b32 v48, v92, v93 offset1:1
	v_add_u32_e32 v48, 0x28a8, v35
	ds_write2_b32 v48, v94, v95 offset1:1
	v_add_u32_e32 v48, 0x2cb0, v35
	s_waitcnt vmcnt(4)
	ds_write2_b32 v48, v96, v97 offset1:1
	v_add_u32_e32 v48, 0x2cb8, v35
	ds_write2_b32 v48, v98, v99 offset1:1
	v_add_u32_e32 v48, 0x30c0, v35
	s_waitcnt vmcnt(3)
; #define LAS __attribute__((address_space(3)))
; __device__ __forceinline__ unsigned pk2(float lo, float hi) { const f32x2 v = {lo, hi}; const hwbf16x2 b = __builtin_convertvector(v, hwbf16x2); return __builtin_bit_cast(unsigned, b); }
; #define LDS_WAIT() asm volatile("s_waitcnt lgkmcnt(0)" ::: "memory")
; __device__ __forceinline__ void transpose_item(const float* W, int ldw, int K, bf16_t* WT, int nblk, LAS float* scr, int item, int lane) {
;     ...
;     for (int i = 0; i < 16; ++i) { LAS float* d = scr + ((lane >> 4) + 4 * i) * 65 + (lane & 15) * 4; d[0] = v[i][0]; d[1] = v[i][1]; d[2] = v[i][2]; d[3] = v[i][3]; }
;     LDS_WAIT();
;     const int c = lane & 7;
; #pragma unroll
;     for (int j = 0; j < 8; ++j) { const int n = (lane >> 3) + 8 * j; const LAS float* s = scr + (8 * c) * 65 + n;
;         u32x4 o; o.x = pk2(s[0 * 65], s[1 * 65]); o.y = pk2(s[2 * 65], s[3 * 65]); o.z = pk2(s[4 * 65], s[5 * 65]); o.w = pk2(s[6 * 65], s[7 * 65]);
;         *(u32x4*)(WT + (size_t)(n0 + n) * K + k0 + 8 * c) = o; }
;     LDS_WAIT();
	ds_write2_b32 v48, v100, v101 offset1:1
	v_add_u32_e32 v48, 0x30c8, v35
	ds_write2_b32 v48, v102, v103 offset1:1
	v_add_u32_e32 v48, 0x34d0, v35
	s_waitcnt vmcnt(2)
	ds_write2_b32 v48, v104, v105 offset1:1
	v_add_u32_e32 v48, 0x34d8, v35
	ds_write2_b32 v48, v106, v107 offset1:1
	v_add_u32_e32 v48, 0x38e0, v35
	s_waitcnt vmcnt(1)
	ds_write2_b32 v48, v108, v109 offset1:1
	v_add_u32_e32 v48, 0x38e8, v35
	ds_write2_b32 v48, v110, v111 offset1:1
	v_add_u32_e32 v48, 0x3cf0, v35
	s_waitcnt vmcnt(0)
	ds_write2_b32 v48, v112, v113 offset1:1
	v_add_u32_e32 v48, 0x3cf8, v35
	ds_write2_b32 v48, v114, v115 offset1:1
	s_waitcnt lgkmcnt(0)
	ds_read2_b32 v[52:53], v37 offset0:65 offset1:73
	ds_read2_b32 v[54:55], v37 offset1:8
	ds_read2_b32 v[60:61], v37 offset0:130 offset1:138
	ds_read2_b32 v[62:63], v37 offset0:195 offset1:203
	ds_read2_b32 v[64:65], v59 offset0:4 offset1:12
	ds_read2_b32 v[66:67], v59 offset0:69 offset1:77
	ds_read2_b32 v[68:69], v59 offset0:134 offset1:142
	ds_read2_b32 v[70:71], v59 offset0:199 offset1:207
	s_waitcnt lgkmcnt(6)
	v_cvt_pk_bf16_f32 v48, v54, v52
	v_or_b32_e32 v52, v36, v116
	v_lshlrev_b32_e32 v182, 12, v52
	s_waitcnt lgkmcnt(4)
	v_cvt_pk_bf16_f32 v49, v60, v62
	s_waitcnt lgkmcnt(2)
	v_cvt_pk_bf16_f32 v50, v64, v66
	s_waitcnt lgkmcnt(0)
	v_cvt_pk_bf16_f32 v51, v68, v70
	v_lshl_add_u64 v[74:75], v[72:73], 0, v[182:183]
	global_store_dwordx4 v[74:75], v[48:51], off nt
	v_or_b32_e32 v52, v38, v116
	v_lshlrev_b32_e32 v182, 12, v52
	v_cvt_pk_bf16_f32 v48, v55, v53
	v_cvt_pk_bf16_f32 v49, v61, v63
	v_cvt_pk_bf16_f32 v50, v65, v67
	v_cvt_pk_bf16_f32 v51, v69, v71
	ds_read2_b32 v[54:55], v37 offset0:81 offset1:89
	ds_read2_b32 v[60:61], v37 offset0:16 offset1:24
	ds_read2_b32 v[62:63], v37 offset0:146 offset1:154
	ds_read2_b32 v[64:65], v37 offset0:211 offset1:219
	ds_read2_b32 v[66:67], v59 offset0:20 offset1:28
	ds_read2_b32 v[68:69], v59 offset0:85 offset1:93
	ds_read2_b32 v[70:71], v59 offset0:150 offset1:158
	ds_read2_b32 v[74:75], v59 offset0:215 offset1:223
	v_lshl_add_u64 v[52:53], v[72:73], 0, v[182:183]
	global_store_dwordx4 v[52:53], v[48:51], off nt
	v_or_b32_e32 v52, v39, v116
	v_lshlrev_b32_e32 v182, 12, v52
	s_waitcnt lgkmcnt(6)
	v_cvt_pk_bf16_f32 v48, v60, v54
	s_waitcnt lgkmcnt(4)
	v_cvt_pk_bf16_f32 v49, v62, v64
	s_waitcnt lgkmcnt(2)
	v_cvt_pk_bf16_f32 v50, v66, v68
	s_waitcnt lgkmcnt(0)
	v_cvt_pk_bf16_f32 v51, v70, v74
	v_lshl_add_u64 v[52:53], v[72:73], 0, v[182:183]
	global_store_dwordx4 v[52:53], v[48:51], off nt
	v_or_b32_e32 v52, v40, v116
	v_lshlrev_b32_e32 v182, 12, v52
	v_cvt_pk_bf16_f32 v48, v61, v55
	v_cvt_pk_bf16_f32 v49, v63, v65
	v_cvt_pk_bf16_f32 v50, v67, v69
	v_cvt_pk_bf16_f32 v51, v71, v75
	ds_read2_b32 v[54:55], v37 offset0:32 offset1:40
	ds_read2_b32 v[60:61], v37 offset0:97 offset1:105
	ds_read2_b32 v[62:63], v37 offset0:162 offset1:170
	ds_read2_b32 v[64:65], v37 offset0:227 offset1:235
	ds_read2_b32 v[66:67], v59 offset0:36 offset1:44
	ds_read2_b32 v[68:69], v59 offset0:101 offset1:109
	ds_read2_b32 v[70:71], v59 offset0:166 offset1:174
	ds_read2_b32 v[74:75], v59 offset0:231 offset1:239
	v_lshl_add_u64 v[52:53], v[72:73], 0, v[182:183]
	global_store_dwordx4 v[52:53], v[48:51], off nt
	v_or_b32_e32 v52, v41, v116
	v_lshlrev_b32_e32 v182, 12, v52
	s_waitcnt lgkmcnt(6)
	v_cvt_pk_bf16_f32 v48, v54, v60
	s_waitcnt lgkmcnt(4)
	v_cvt_pk_bf16_f32 v49, v62, v64
	s_waitcnt lgkmcnt(2)
	v_cvt_pk_bf16_f32 v50, v66, v68
	s_waitcnt lgkmcnt(0)
	v_cvt_pk_bf16_f32 v51, v70, v74
	v_lshl_add_u64 v[52:53], v[72:73], 0, v[182:183]
	global_store_dwordx4 v[52:53], v[48:51], off nt
	v_or_b32_e32 v52, v42, v116
	v_lshlrev_b32_e32 v182, 12, v52
	v_cvt_pk_bf16_f32 v48, v55, v61
	v_cvt_pk_bf16_f32 v49, v63, v65
	v_cvt_pk_bf16_f32 v50, v67, v69
	v_cvt_pk_bf16_f32 v51, v71, v75
	ds_read2_b32 v[54:55], v37 offset0:48 offset1:56
	ds_read2_b32 v[60:61], v37 offset0:113 offset1:121
	ds_read2_b32 v[62:63], v37 offset0:178 offset1:186
	ds_read2_b32 v[64:65], v37 offset0:243 offset1:251
	ds_read2_b32 v[66:67], v59 offset0:52 offset1:60
	ds_read2_b32 v[68:69], v59 offset0:117 offset1:125
	ds_read2_b32 v[70:71], v59 offset0:182 offset1:190
	ds_read2_b32 v[74:75], v59 offset0:247 offset1:255
	v_lshl_add_u64 v[52:53], v[72:73], 0, v[182:183]
	global_store_dwordx4 v[52:53], v[48:51], off nt
	v_or_b32_e32 v52, v43, v116
	v_lshlrev_b32_e32 v182, 12, v52
	s_waitcnt lgkmcnt(6)
	v_cvt_pk_bf16_f32 v48, v54, v60
	s_waitcnt lgkmcnt(4)
	v_cvt_pk_bf16_f32 v49, v62, v64
	s_waitcnt lgkmcnt(2)
	v_cvt_pk_bf16_f32 v50, v66, v68
	s_waitcnt lgkmcnt(0)
	v_cvt_pk_bf16_f32 v51, v70, v74
	v_lshl_add_u64 v[52:53], v[72:73], 0, v[182:183]
	global_store_dwordx4 v[52:53], v[48:51], off nt
	v_or_b32_e32 v52, v44, v116
	v_lshlrev_b32_e32 v182, 12, v52
	v_cvt_pk_bf16_f32 v48, v55, v61
	v_cvt_pk_bf16_f32 v49, v63, v65
	v_cvt_pk_bf16_f32 v50, v67, v69
	v_cvt_pk_bf16_f32 v51, v71, v75
	v_lshl_add_u64 v[52:53], v[72:73], 0, v[182:183]
	global_store_dwordx4 v[52:53], v[48:51], off nt
	s_waitcnt lgkmcnt(0)

; #define LAS __attribute__((address_space(3)))
; __device__ __forceinline__ void transpose_item(const float* W, int ldw, int K, bf16_t* WT, int nblk, LAS float* scr, int item, int lane) {
;     ...
;     for (int i = 0; i < 16; ++i) v[i] = *(const f32x4*)(W + (size_t)(k0 + (lane >> 4) + 4 * i) * ldw + n0 + (lane & 15) * 4);
; #pragma unroll
;     for (int i = 0; i < 16; ++i) { LAS float* d = scr + ((lane >> 4) + 4 * i) * 65 + (lane & 15) * 4; d[0] = v[i][0]; d[1] = v[i][1]; d[2] = v[i][2]; d[3] = v[i][3]; }
; __device__ __forceinline__ void transpose_range(const Params& p, LAS unsigned char* lds, int l, int lo, int hi, int gw, int NGW, int wave, int lane) {
;     ...
;         if (r < TI_OUT) { transpose_item(p.w_out + (size_t)l * DM * DM, DM, DM, (bf16_t*)(ws + WS_WOUT + l * SZ_WOUT), DM / 64, scr, r, lane); continue; } r -= TI_OUT;
.LBB0_566:
	s_andn2_saveexec_b64 s[10:11], s[10:11]
	s_cbranch_execz .LBB0_568
	v_add_u32_e32 v48, 0x1f000, v46
	v_and_b32_e32 v59, 0x1ffc0, v48
	v_and_b32_e32 v116, 0x7c0, v45
	v_or_b32_e32 v50, v59, v34
	v_lshlrev_b32_e32 v182, 2, v116
	v_lshl_add_u64 v[48:49], v[28:29], 0, v[182:183]
	v_lshlrev_b32_e32 v182, 13, v50
	v_lshl_add_u64 v[112:113], v[48:49], 0, v[182:183]
	v_add_co_u32_e32 v52, vcc, 0x8000, v112
	v_lshlrev_b32_e32 v182, 1, v59
	s_nop 0
	v_addc_co_u32_e32 v53, vcc, 0, v113, vcc
	v_add_co_u32_e32 v60, vcc, s5, v112
	global_load_dwordx4 v[48:51], v[112:113], off nt
	s_nop 0
	global_load_dwordx4 v[52:55], v[52:53], off nt
	v_addc_co_u32_e32 v61, vcc, 0, v113, vcc
	v_add_co_u32_e32 v64, vcc, s61, v112
	v_add_u32_e32 v59, 0x400, v37
	s_nop 0
	v_addc_co_u32_e32 v65, vcc, 0, v113, vcc
	global_load_dwordx4 v[60:63], v[60:61], off nt
	s_nop 0
	global_load_dwordx4 v[64:67], v[64:65], off nt
	v_add_co_u32_e32 v68, vcc, 0x20000, v112
	s_nop 1
	v_addc_co_u32_e32 v69, vcc, 0, v113, vcc
	v_add_co_u32_e32 v72, vcc, 0x28000, v112
	s_nop 1
	v_addc_co_u32_e32 v73, vcc, 0, v113, vcc
	global_load_dwordx4 v[68:71], v[68:69], off nt
	s_nop 0
	global_load_dwordx4 v[72:75], v[72:73], off nt
	v_add_co_u32_e32 v76, vcc, 0x30000, v112
	s_nop 1
	v_addc_co_u32_e32 v77, vcc, 0, v113, vcc
	v_add_co_u32_e32 v80, vcc, 0x38000, v112
	s_nop 1
	v_addc_co_u32_e32 v81, vcc, 0, v113, vcc
	global_load_dwordx4 v[76:79], v[76:77], off nt
	s_nop 0
	global_load_dwordx4 v[80:83], v[80:81], off nt
	v_add_co_u32_e32 v84, vcc, 0x40000, v112
	s_nop 1
	v_addc_co_u32_e32 v85, vcc, 0, v113, vcc
	v_add_co_u32_e32 v88, vcc, 0x48000, v112
	s_nop 1
	v_addc_co_u32_e32 v89, vcc, 0, v113, vcc
	global_load_dwordx4 v[84:87], v[84:85], off nt
	s_nop 0
	global_load_dwordx4 v[88:91], v[88:89], off nt
	v_add_co_u32_e32 v92, vcc, 0x50000, v112
	s_nop 1
	v_addc_co_u32_e32 v93, vcc, 0, v113, vcc
	v_add_co_u32_e32 v96, vcc, s28, v112
	s_nop 1
	v_addc_co_u32_e32 v97, vcc, 0, v113, vcc
	global_load_dwordx4 v[92:95], v[92:93], off nt
	s_nop 0
	global_load_dwordx4 v[96:99], v[96:97], off nt
	v_add_co_u32_e32 v100, vcc, 0x60000, v112
	s_nop 1
	v_addc_co_u32_e32 v101, vcc, 0, v113, vcc
	v_add_co_u32_e32 v104, vcc, 0x68000, v112
	s_nop 1
	v_addc_co_u32_e32 v105, vcc, 0, v113, vcc
	global_load_dwordx4 v[100:103], v[100:101], off nt
	s_nop 0
	global_load_dwordx4 v[104:107], v[104:105], off nt
	v_add_co_u32_e32 v108, vcc, 0x70000, v112
	s_nop 1
	v_addc_co_u32_e32 v109, vcc, 0, v113, vcc
	global_load_dwordx4 v[108:111], v[108:109], off nt
	v_add_co_u32_e32 v112, vcc, 0x78000, v112
	s_nop 1
	v_addc_co_u32_e32 v113, vcc, 0, v113, vcc
	global_load_dwordx4 v[112:115], v[112:113], off nt
	s_waitcnt vmcnt(15)
	ds_write2_b32 v35, v48, v49 offset1:1
	ds_write2_b32 v35, v50, v51 offset0:2 offset1:3
	v_add_u32_e32 v48, 0x410, v35
	s_waitcnt vmcnt(14)
	ds_write2_b32 v48, v52, v53 offset1:1
	v_add_u32_e32 v48, 0x418, v35
	ds_write2_b32 v48, v54, v55 offset1:1
	v_add_u32_e32 v48, 0x820, v35
	s_waitcnt vmcnt(13)
	ds_write2_b32 v48, v60, v61 offset1:1
	v_add_u32_e32 v48, 0x828, v35
	ds_write2_b32 v48, v62, v63 offset1:1
	v_add_u32_e32 v48, 0xc30, v35
	s_waitcnt vmcnt(12)
	ds_write2_b32 v48, v64, v65 offset1:1
	v_add_u32_e32 v48, 0xc38, v35
	ds_write2_b32 v48, v66, v67 offset1:1
	v_add_u32_e32 v48, 0x1040, v35
	s_waitcnt vmcnt(11)
	ds_write2_b32 v48, v68, v69 offset1:1
	v_add_u32_e32 v48, 0x1048, v35
	ds_write2_b32 v48, v70, v71 offset1:1
	v_add_u32_e32 v48, 0x1450, v35
	s_waitcnt vmcnt(10)
	ds_write2_b32 v48, v72, v73 offset1:1
	v_add_u32_e32 v48, 0x1458, v35
	ds_write2_b32 v48, v74, v75 offset1:1
	v_add_u32_e32 v48, 0x1860, v35
	v_lshl_add_u64 v[72:73], v[20:21], 0, v[182:183]
	s_waitcnt vmcnt(9)
	ds_write2_b32 v48, v76, v77 offset1:1
	v_add_u32_e32 v48, 0x1868, v35
	ds_write2_b32 v48, v78, v79 offset1:1
	v_add_u32_e32 v48, 0x1c70, v35
	s_waitcnt vmcnt(8)
	ds_write2_b32 v48, v80, v81 offset1:1
	v_add_u32_e32 v48, 0x1c78, v35
	ds_write2_b32 v48, v82, v83 offset1:1
	v_add_u32_e32 v48, 0x2080, v35
	s_waitcnt vmcnt(7)
	ds_write2_b32 v48, v84, v85 offset1:1
	v_add_u32_e32 v48, 0x2088, v35
	ds_write2_b32 v48, v86, v87 offset1:1
	v_add_u32_e32 v48, 0x2490, v35
	s_waitcnt vmcnt(6)
	ds_write2_b32 v48, v88, v89 offset1:1
	v_add_u32_e32 v48, 0x2498, v35
	ds_write2_b32 v48, v90, v91 offset1:1
	v_add_u32_e32 v48, 0x28a0, v35
	s_waitcnt vmcnt(5)
	ds_write2_b32 v48, v92, v93 offset1:1
	v_add_u32_e32 v48, 0x28a8, v35
	ds_write2_b32 v48, v94, v95 offset1:1
	v_add_u32_e32 v48, 0x2cb0, v35
	s_waitcnt vmcnt(4)
	ds_write2_b32 v48, v96, v97 offset1:1
	v_add_u32_e32 v48, 0x2cb8, v35
	ds_write2_b32 v48, v98, v99 offset1:1
	v_add_u32_e32 v48, 0x30c0, v35
	s_waitcnt vmcnt(3)
	ds_write2_b32 v48, v100, v101 offset1:1
	v_add_u32_e32 v48, 0x30c8, v35
	ds_write2_b32 v48, v102, v103 offset1:1
	v_add_u32_e32 v48, 0x34d0, v35
	s_waitcnt vmcnt(2)
; #define LAS __attribute__((address_space(3)))
; __device__ __forceinline__ unsigned pk2(float lo, float hi) { const f32x2 v = {lo, hi}; const hwbf16x2 b = __builtin_convertvector(v, hwbf16x2); return __builtin_bit_cast(unsigned, b); }
; #define LDS_WAIT() asm volatile("s_waitcnt lgkmcnt(0)" ::: "memory")
; __device__ __forceinline__ void transpose_item(const float* W, int ldw, int K, bf16_t* WT, int nblk, LAS float* scr, int item, int lane) {
;     ...
;     for (int i = 0; i < 16; ++i) { LAS float* d = scr + ((lane >> 4) + 4 * i) * 65 + (lane & 15) * 4; d[0] = v[i][0]; d[1] = v[i][1]; d[2] = v[i][2]; d[3] = v[i][3]; }
;     LDS_WAIT();
;     const int c = lane & 7;
; #pragma unroll
;     for (int j = 0; j < 8; ++j) { const int n = (lane >> 3) + 8 * j; const LAS float* s = scr + (8 * c) * 65 + n;
;         u32x4 o; o.x = pk2(s[0 * 65], s[1 * 65]); o.y = pk2(s[2 * 65], s[3 * 65]); o.z = pk2(s[4 * 65], s[5 * 65]); o.w = pk2(s[6 * 65], s[7 * 65]);
;         *(u32x4*)(WT + (size_t)(n0 + n) * K + k0 + 8 * c) = o; }
;     LDS_WAIT();
	ds_write2_b32 v48, v104, v105 offset1:1
	v_add_u32_e32 v48, 0x34d8, v35
	ds_write2_b32 v48, v106, v107 offset1:1
	v_add_u32_e32 v48, 0x38e0, v35
	s_waitcnt vmcnt(1)
	ds_write2_b32 v48, v108, v109 offset1:1
	v_add_u32_e32 v48, 0x38e8, v35
	ds_write2_b32 v48, v110, v111 offset1:1
	v_add_u32_e32 v48, 0x3cf0, v35
	s_waitcnt vmcnt(0)
	ds_write2_b32 v48, v112, v113 offset1:1
	v_add_u32_e32 v48, 0x3cf8, v35
	ds_write2_b32 v48, v114, v115 offset1:1
	s_waitcnt lgkmcnt(0)
	ds_read2_b32 v[52:53], v37 offset0:65 offset1:73
	ds_read2_b32 v[54:55], v37 offset1:8
	ds_read2_b32 v[60:61], v37 offset0:130 offset1:138
	ds_read2_b32 v[62:63], v37 offset0:195 offset1:203
	ds_read2_b32 v[64:65], v59 offset0:4 offset1:12
	ds_read2_b32 v[66:67], v59 offset0:69 offset1:77
	ds_read2_b32 v[68:69], v59 offset0:134 offset1:142
	ds_read2_b32 v[70:71], v59 offset0:199 offset1:207
	s_waitcnt lgkmcnt(6)
	v_cvt_pk_bf16_f32 v48, v54, v52
	v_or_b32_e32 v52, v116, v36
	v_lshlrev_b32_e32 v182, 12, v52
	s_waitcnt lgkmcnt(4)
	v_cvt_pk_bf16_f32 v49, v60, v62
	s_waitcnt lgkmcnt(2)
	v_cvt_pk_bf16_f32 v50, v64, v66
	s_waitcnt lgkmcnt(0)
	v_cvt_pk_bf16_f32 v51, v68, v70
	v_lshl_add_u64 v[74:75], v[72:73], 0, v[182:183]
	global_store_dwordx4 v[74:75], v[48:51], off nt
	v_or_b32_e32 v52, v116, v38
	v_lshlrev_b32_e32 v182, 12, v52
	v_cvt_pk_bf16_f32 v48, v55, v53
	v_cvt_pk_bf16_f32 v49, v61, v63
	v_cvt_pk_bf16_f32 v50, v65, v67
	v_cvt_pk_bf16_f32 v51, v69, v71
	ds_read2_b32 v[54:55], v37 offset0:81 offset1:89
	ds_read2_b32 v[60:61], v37 offset0:16 offset1:24
	ds_read2_b32 v[62:63], v37 offset0:146 offset1:154
	ds_read2_b32 v[64:65], v37 offset0:211 offset1:219
	ds_read2_b32 v[66:67], v59 offset0:20 offset1:28
	ds_read2_b32 v[68:69], v59 offset0:85 offset1:93
	ds_read2_b32 v[70:71], v59 offset0:150 offset1:158
	ds_read2_b32 v[74:75], v59 offset0:215 offset1:223
	v_lshl_add_u64 v[52:53], v[72:73], 0, v[182:183]
	global_store_dwordx4 v[52:53], v[48:51], off nt
	v_or_b32_e32 v52, v116, v39
	v_lshlrev_b32_e32 v182, 12, v52
	s_waitcnt lgkmcnt(6)
	v_cvt_pk_bf16_f32 v48, v60, v54
	s_waitcnt lgkmcnt(4)
	v_cvt_pk_bf16_f32 v49, v62, v64
	s_waitcnt lgkmcnt(2)
	v_cvt_pk_bf16_f32 v50, v66, v68
	s_waitcnt lgkmcnt(0)
	v_cvt_pk_bf16_f32 v51, v70, v74
	v_lshl_add_u64 v[52:53], v[72:73], 0, v[182:183]
	global_store_dwordx4 v[52:53], v[48:51], off nt
	v_or_b32_e32 v52, v116, v40
	v_lshlrev_b32_e32 v182, 12, v52
	v_cvt_pk_bf16_f32 v48, v61, v55
	v_cvt_pk_bf16_f32 v49, v63, v65
	v_cvt_pk_bf16_f32 v50, v67, v69
	v_cvt_pk_bf16_f32 v51, v71, v75
	ds_read2_b32 v[54:55], v37 offset0:32 offset1:40
	ds_read2_b32 v[60:61], v37 offset0:97 offset1:105
	ds_read2_b32 v[62:63], v37 offset0:162 offset1:170
	ds_read2_b32 v[64:65], v37 offset0:227 offset1:235
	ds_read2_b32 v[66:67], v59 offset0:36 offset1:44
	ds_read2_b32 v[68:69], v59 offset0:101 offset1:109
	ds_read2_b32 v[70:71], v59 offset0:166 offset1:174
	ds_read2_b32 v[74:75], v59 offset0:231 offset1:239
	v_lshl_add_u64 v[52:53], v[72:73], 0, v[182:183]
	global_store_dwordx4 v[52:53], v[48:51], off nt
	v_or_b32_e32 v52, v116, v41
	v_lshlrev_b32_e32 v182, 12, v52
	s_waitcnt lgkmcnt(6)
	v_cvt_pk_bf16_f32 v48, v54, v60
	s_waitcnt lgkmcnt(4)
	v_cvt_pk_bf16_f32 v49, v62, v64
	s_waitcnt lgkmcnt(2)
	v_cvt_pk_bf16_f32 v50, v66, v68
	s_waitcnt lgkmcnt(0)
	v_cvt_pk_bf16_f32 v51, v70, v74
	v_lshl_add_u64 v[52:53], v[72:73], 0, v[182:183]
	global_store_dwordx4 v[52:53], v[48:51], off nt
	v_or_b32_e32 v52, v116, v42
	v_lshlrev_b32_e32 v182, 12, v52
	v_cvt_pk_bf16_f32 v48, v55, v61
	v_cvt_pk_bf16_f32 v49, v63, v65
	v_cvt_pk_bf16_f32 v50, v67, v69
	v_cvt_pk_bf16_f32 v51, v71, v75
	ds_read2_b32 v[54:55], v37 offset0:48 offset1:56
	ds_read2_b32 v[60:61], v37 offset0:113 offset1:121
	ds_read2_b32 v[62:63], v37 offset0:178 offset1:186
	ds_read2_b32 v[64:65], v37 offset0:243 offset1:251
	ds_read2_b32 v[66:67], v59 offset0:52 offset1:60
	ds_read2_b32 v[68:69], v59 offset0:117 offset1:125
	ds_read2_b32 v[70:71], v59 offset0:182 offset1:190
	ds_read2_b32 v[74:75], v59 offset0:247 offset1:255
	v_lshl_add_u64 v[52:53], v[72:73], 0, v[182:183]
	global_store_dwordx4 v[52:53], v[48:51], off nt
	v_or_b32_e32 v52, v116, v43
	v_lshlrev_b32_e32 v182, 12, v52
	s_waitcnt lgkmcnt(6)
	v_cvt_pk_bf16_f32 v48, v54, v60
	s_waitcnt lgkmcnt(4)
	v_cvt_pk_bf16_f32 v49, v62, v64
	s_waitcnt lgkmcnt(2)
	v_cvt_pk_bf16_f32 v50, v66, v68
	s_waitcnt lgkmcnt(0)
	v_cvt_pk_bf16_f32 v51, v70, v74
	v_lshl_add_u64 v[52:53], v[72:73], 0, v[182:183]
	global_store_dwordx4 v[52:53], v[48:51], off nt
	v_or_b32_e32 v52, v116, v44
	v_lshlrev_b32_e32 v182, 12, v52
	v_cvt_pk_bf16_f32 v48, v55, v61
	v_cvt_pk_bf16_f32 v49, v63, v65
	v_cvt_pk_bf16_f32 v50, v67, v69
	v_cvt_pk_bf16_f32 v51, v71, v75
	v_lshl_add_u64 v[52:53], v[72:73], 0, v[182:183]
	global_store_dwordx4 v[52:53], v[48:51], off nt
	s_waitcnt lgkmcnt(0)

; #define LAS __attribute__((address_space(3)))
; __device__ __forceinline__ void transpose_item(const float* W, int ldw, int K, bf16_t* WT, int nblk, LAS float* scr, int item, int lane) {
;     ...
;     for (int i = 0; i < 16; ++i) v[i] = *(const f32x4*)(W + (size_t)(k0 + (lane >> 4) + 4 * i) * ldw + n0 + (lane & 15) * 4);
; #pragma unroll
;     for (int i = 0; i < 16; ++i) { LAS float* d = scr + ((lane >> 4) + 4 * i) * 65 + (lane & 15) * 4; d[0] = v[i][0]; d[1] = v[i][1]; d[2] = v[i][2]; d[3] = v[i][3]; }
; __device__ __forceinline__ void transpose_range(const Params& p, LAS unsigned char* lds, int l, int lo, int hi, int gw, int NGW, int wave, int lane) {
;     ...
;         if (r < TI_IN) { transpose_item(p.w_in + (size_t)l * DM * INW, INW, DM, (bf16_t*)(ws + WS_WIN + l * SZ_WIN), ZW / 64, scr, r, lane); continue; } r -= TI_IN;
.LBB0_569:
	s_andn2_saveexec_b64 s[8:9], s[8:9]
	s_cbranch_execz .LBB0_558
	v_ashrrev_i32_e32 v48, 31, v47
	v_lshrrev_b32_e32 v48, 26, v48
	v_add_u32_e32 v48, v47, v48
	v_and_b32_e32 v116, 0xffffffc0, v48
	v_lshlrev_b32_e32 v48, 6, v48
	v_and_b32_e32 v48, 0xfffff000, v48
	v_sub_u32_e32 v118, v45, v48
	v_or_b32_e32 v59, v116, v34
	v_ashrrev_i32_e32 v119, 31, v118
	v_lshl_add_u64 v[112:113], v[118:119], 2, v[30:31]
	v_or_b32_e32 v50, 4, v59
	v_or_b32_e32 v60, 8, v59
	v_or_b32_e32 v62, 12, v59
	v_mad_i64_i32 v[48:49], s[10:11], v59, s21, v[112:113]
	v_mad_i64_i32 v[52:53], s[10:11], v50, s21, v[112:113]
	v_mad_i64_i32 v[60:61], s[10:11], v60, s21, v[112:113]
	v_mad_i64_i32 v[64:65], s[10:11], v62, s21, v[112:113]
	v_or_b32_e32 v68, 16, v59
	v_or_b32_e32 v72, 20, v59
	global_load_dwordx4 v[48:51], v[48:49], off nt
	s_nop 0
	global_load_dwordx4 v[52:55], v[52:53], off nt
	s_nop 0
	global_load_dwordx4 v[60:63], v[60:61], off nt
	s_nop 0
	global_load_dwordx4 v[64:67], v[64:65], off nt
	v_mad_i64_i32 v[68:69], s[10:11], v68, s21, v[112:113]
	v_mad_i64_i32 v[72:73], s[10:11], v72, s21, v[112:113]
	global_load_dwordx4 v[68:71], v[68:69], off nt
	v_or_b32_e32 v76, 24, v59
	global_load_dwordx4 v[72:75], v[72:73], off nt
	v_mad_i64_i32 v[76:77], s[10:11], v76, s21, v[112:113]
	global_load_dwordx4 v[76:79], v[76:77], off nt
	v_or_b32_e32 v80, 28, v59
	v_mad_i64_i32 v[80:81], s[10:11], v80, s21, v[112:113]
	global_load_dwordx4 v[80:83], v[80:81], off nt
	v_or_b32_e32 v84, 32, v59
	v_mad_i64_i32 v[84:85], s[10:11], v84, s21, v[112:113]
	global_load_dwordx4 v[84:87], v[84:85], off nt
	v_or_b32_e32 v88, 36, v59
	v_mad_i64_i32 v[88:89], s[10:11], v88, s21, v[112:113]
	global_load_dwordx4 v[88:91], v[88:89], off nt
	v_or_b32_e32 v92, 40, v59
	v_mad_i64_i32 v[92:93], s[10:11], v92, s21, v[112:113]
	global_load_dwordx4 v[92:95], v[92:93], off nt
	v_or_b32_e32 v96, 44, v59
	v_mad_i64_i32 v[96:97], s[10:11], v96, s21, v[112:113]
	global_load_dwordx4 v[96:99], v[96:97], off nt
	v_or_b32_e32 v100, 48, v59
	v_mad_i64_i32 v[100:101], s[10:11], v100, s21, v[112:113]
	global_load_dwordx4 v[100:103], v[100:101], off nt
	v_or_b32_e32 v104, 52, v59
	v_mad_i64_i32 v[104:105], s[10:11], v104, s21, v[112:113]
	global_load_dwordx4 v[104:107], v[104:105], off nt
	v_or_b32_e32 v108, 56, v59
	v_mad_i64_i32 v[108:109], s[10:11], v108, s21, v[112:113]
	global_load_dwordx4 v[108:111], v[108:109], off nt
	v_or_b32_e32 v59, 60, v59
	v_mad_i64_i32 v[112:113], s[10:11], v59, s21, v[112:113]
	global_load_dwordx4 v[112:115], v[112:113], off nt
	v_add_u32_e32 v59, 0x410, v35
	v_add_u32_e32 v117, 0x418, v35
	v_add_u32_e32 v119, 0x820, v35
	v_add_u32_e32 v120, 0x828, v35
	v_add_u32_e32 v121, 0xc30, v35
	v_add_u32_e32 v122, 0xc38, v35
	v_add_u32_e32 v123, 0x1040, v35
	v_add_u32_e32 v124, 0x1048, v35
	s_waitcnt vmcnt(15)
	ds_write2_b32 v35, v48, v49 offset1:1
	ds_write2_b32 v35, v50, v51 offset0:2 offset1:3
	s_waitcnt vmcnt(14)
	ds_write2_b32 v59, v52, v53 offset1:1
	ds_write2_b32 v117, v54, v55 offset1:1
	s_waitcnt vmcnt(13)
	ds_write2_b32 v119, v60, v61 offset1:1
	ds_write2_b32 v120, v62, v63 offset1:1
	s_waitcnt vmcnt(12)
	ds_write2_b32 v121, v64, v65 offset1:1
	ds_write2_b32 v122, v66, v67 offset1:1
	s_waitcnt vmcnt(11)
	ds_write2_b32 v123, v68, v69 offset1:1
	ds_write2_b32 v124, v70, v71 offset1:1
	v_add_u32_e32 v48, 0x1450, v35
	v_add_u32_e32 v59, 0x400, v37
	v_ashrrev_i32_e32 v117, 31, v116
	s_waitcnt vmcnt(10)
	ds_write2_b32 v48, v72, v73 offset1:1
	v_add_u32_e32 v48, 0x1458, v35
	ds_write2_b32 v48, v74, v75 offset1:1
	v_add_u32_e32 v48, 0x1860, v35
	s_waitcnt vmcnt(9)
	ds_write2_b32 v48, v76, v77 offset1:1
	v_add_u32_e32 v48, 0x1868, v35
	ds_write2_b32 v48, v78, v79 offset1:1
	v_add_u32_e32 v48, 0x1c70, v35
	s_waitcnt vmcnt(8)
	ds_write2_b32 v48, v80, v81 offset1:1
	v_add_u32_e32 v48, 0x1c78, v35
	ds_write2_b32 v48, v82, v83 offset1:1
	v_add_u32_e32 v48, 0x2080, v35
	s_waitcnt vmcnt(7)
	ds_write2_b32 v48, v84, v85 offset1:1
	v_add_u32_e32 v48, 0x2088, v35
	ds_write2_b32 v48, v86, v87 offset1:1
	v_add_u32_e32 v48, 0x2490, v35
	s_waitcnt vmcnt(6)
	ds_write2_b32 v48, v88, v89 offset1:1
	v_add_u32_e32 v48, 0x2498, v35
	ds_write2_b32 v48, v90, v91 offset1:1
	v_add_u32_e32 v48, 0x28a0, v35
	s_waitcnt vmcnt(5)
	ds_write2_b32 v48, v92, v93 offset1:1
	v_add_u32_e32 v48, 0x28a8, v35
	ds_write2_b32 v48, v94, v95 offset1:1
	v_add_u32_e32 v48, 0x2cb0, v35
	s_waitcnt vmcnt(4)
	ds_write2_b32 v48, v96, v97 offset1:1
	v_add_u32_e32 v48, 0x2cb8, v35
	ds_write2_b32 v48, v98, v99 offset1:1
	v_add_u32_e32 v48, 0x30c0, v35
	s_waitcnt vmcnt(3)
	ds_write2_b32 v48, v100, v101 offset1:1
	v_add_u32_e32 v48, 0x30c8, v35
	ds_write2_b32 v48, v102, v103 offset1:1
	v_add_u32_e32 v48, 0x34d0, v35
	s_waitcnt vmcnt(2)
	ds_write2_b32 v48, v104, v105 offset1:1
	v_add_u32_e32 v48, 0x34d8, v35
	ds_write2_b32 v48, v106, v107 offset1:1
	v_add_u32_e32 v48, 0x38e0, v35
	s_waitcnt vmcnt(1)
; #define LAS __attribute__((address_space(3)))
; __device__ __forceinline__ unsigned pk2(float lo, float hi) { const f32x2 v = {lo, hi}; const hwbf16x2 b = __builtin_convertvector(v, hwbf16x2); return __builtin_bit_cast(unsigned, b); }
; #define LDS_WAIT() asm volatile("s_waitcnt lgkmcnt(0)" ::: "memory")
; __device__ __forceinline__ void transpose_item(const float* W, int ldw, int K, bf16_t* WT, int nblk, LAS float* scr, int item, int lane) {
;     ...
;     for (int i = 0; i < 16; ++i) { LAS float* d = scr + ((lane >> 4) + 4 * i) * 65 + (lane & 15) * 4; d[0] = v[i][0]; d[1] = v[i][1]; d[2] = v[i][2]; d[3] = v[i][3]; }
;     LDS_WAIT();
;     const int c = lane & 7;
; #pragma unroll
;     for (int j = 0; j < 8; ++j) { const int n = (lane >> 3) + 8 * j; const LAS float* s = scr + (8 * c) * 65 + n;
;         u32x4 o; o.x = pk2(s[0 * 65], s[1 * 65]); o.y = pk2(s[2 * 65], s[3 * 65]); o.z = pk2(s[4 * 65], s[5 * 65]); o.w = pk2(s[6 * 65], s[7 * 65]);
;         *(u32x4*)(WT + (size_t)(n0 + n) * K + k0 + 8 * c) = o; }
;     LDS_WAIT();
	ds_write2_b32 v48, v108, v109 offset1:1
	v_add_u32_e32 v48, 0x38e8, v35
	ds_write2_b32 v48, v110, v111 offset1:1
	v_add_u32_e32 v48, 0x3cf0, v35
	s_waitcnt vmcnt(0)
	ds_write2_b32 v48, v112, v113 offset1:1
	v_add_u32_e32 v48, 0x3cf8, v35
	ds_write2_b32 v48, v114, v115 offset1:1
	s_waitcnt lgkmcnt(0)
	ds_read2_b32 v[52:53], v37 offset0:65 offset1:73
	ds_read2_b32 v[54:55], v37 offset1:8
	ds_read2_b32 v[60:61], v37 offset0:130 offset1:138
	ds_read2_b32 v[62:63], v37 offset0:195 offset1:203
	ds_read2_b32 v[64:65], v59 offset0:4 offset1:12
	ds_read2_b32 v[66:67], v59 offset0:69 offset1:77
	ds_read2_b32 v[68:69], v59 offset0:134 offset1:142
	ds_read2_b32 v[70:71], v59 offset0:199 offset1:207
	v_add_u32_e32 v74, v118, v36
	v_ashrrev_i32_e32 v75, 31, v74
	v_lshl_add_u64 v[72:73], v[116:117], 1, v[22:23]
	v_lshlrev_b64 v[76:77], 12, v[74:75]
	s_waitcnt lgkmcnt(6)
	v_cvt_pk_bf16_f32 v48, v54, v52
	s_waitcnt lgkmcnt(4)
	v_cvt_pk_bf16_f32 v49, v60, v62
	s_waitcnt lgkmcnt(2)
	v_cvt_pk_bf16_f32 v50, v64, v66
	s_waitcnt lgkmcnt(0)
	v_cvt_pk_bf16_f32 v51, v68, v70
	v_lshl_add_u64 v[76:77], v[72:73], 0, v[76:77]
	v_add_u32_e32 v52, 8, v74
	global_store_dwordx4 v[76:77], v[48:51], off nt
	s_nop 1
	v_cvt_pk_bf16_f32 v48, v55, v53
	v_ashrrev_i32_e32 v53, 31, v52
	v_cvt_pk_bf16_f32 v49, v61, v63
	v_cvt_pk_bf16_f32 v50, v65, v67
	v_cvt_pk_bf16_f32 v51, v69, v71
	v_lshlrev_b64 v[52:53], 12, v[52:53]
	ds_read2_b32 v[54:55], v37 offset0:81 offset1:89
	ds_read2_b32 v[60:61], v37 offset0:16 offset1:24
	ds_read2_b32 v[62:63], v37 offset0:146 offset1:154
	ds_read2_b32 v[64:65], v37 offset0:211 offset1:219
	ds_read2_b32 v[66:67], v59 offset0:20 offset1:28
	ds_read2_b32 v[68:69], v59 offset0:85 offset1:93
	ds_read2_b32 v[70:71], v59 offset0:150 offset1:158
	ds_read2_b32 v[76:77], v59 offset0:215 offset1:223
	v_lshl_add_u64 v[52:53], v[72:73], 0, v[52:53]
	global_store_dwordx4 v[52:53], v[48:51], off nt
	v_add_u32_e32 v52, 16, v74
	v_ashrrev_i32_e32 v53, 31, v52
	v_lshlrev_b64 v[52:53], 12, v[52:53]
	s_waitcnt lgkmcnt(6)
	v_cvt_pk_bf16_f32 v48, v60, v54
	s_waitcnt lgkmcnt(4)
	v_cvt_pk_bf16_f32 v49, v62, v64
	s_waitcnt lgkmcnt(2)
	v_cvt_pk_bf16_f32 v50, v66, v68
	s_waitcnt lgkmcnt(0)
	v_cvt_pk_bf16_f32 v51, v70, v76
	v_lshl_add_u64 v[52:53], v[72:73], 0, v[52:53]
	global_store_dwordx4 v[52:53], v[48:51], off nt
	v_add_u32_e32 v52, 24, v74
	v_ashrrev_i32_e32 v53, 31, v52
	v_cvt_pk_bf16_f32 v48, v61, v55
	v_cvt_pk_bf16_f32 v49, v63, v65
	v_cvt_pk_bf16_f32 v50, v67, v69
	v_cvt_pk_bf16_f32 v51, v71, v77
	v_lshlrev_b64 v[52:53], 12, v[52:53]
	ds_read2_b32 v[54:55], v37 offset0:32 offset1:40
	ds_read2_b32 v[60:61], v37 offset0:97 offset1:105
	ds_read2_b32 v[62:63], v37 offset0:162 offset1:170
	ds_read2_b32 v[64:65], v37 offset0:227 offset1:235
	ds_read2_b32 v[66:67], v59 offset0:36 offset1:44
	ds_read2_b32 v[68:69], v59 offset0:101 offset1:109
	ds_read2_b32 v[70:71], v59 offset0:166 offset1:174
	ds_read2_b32 v[76:77], v59 offset0:231 offset1:239
	v_lshl_add_u64 v[52:53], v[72:73], 0, v[52:53]
	global_store_dwordx4 v[52:53], v[48:51], off nt
	v_add_u32_e32 v52, 32, v74
	v_ashrrev_i32_e32 v53, 31, v52
	v_lshlrev_b64 v[52:53], 12, v[52:53]
	s_waitcnt lgkmcnt(6)
	v_cvt_pk_bf16_f32 v48, v54, v60
	s_waitcnt lgkmcnt(4)
	v_cvt_pk_bf16_f32 v49, v62, v64
	s_waitcnt lgkmcnt(2)
	v_cvt_pk_bf16_f32 v50, v66, v68
	s_waitcnt lgkmcnt(0)
	v_cvt_pk_bf16_f32 v51, v70, v76
	v_lshl_add_u64 v[52:53], v[72:73], 0, v[52:53]
	global_store_dwordx4 v[52:53], v[48:51], off nt
	v_add_u32_e32 v52, 40, v74
	v_ashrrev_i32_e32 v53, 31, v52
	v_cvt_pk_bf16_f32 v48, v55, v61
	v_cvt_pk_bf16_f32 v49, v63, v65
	v_cvt_pk_bf16_f32 v50, v67, v69
	v_cvt_pk_bf16_f32 v51, v71, v77
	v_lshlrev_b64 v[52:53], 12, v[52:53]
	ds_read2_b32 v[54:55], v37 offset0:48 offset1:56
	ds_read2_b32 v[60:61], v37 offset0:113 offset1:121
	ds_read2_b32 v[62:63], v37 offset0:178 offset1:186
	ds_read2_b32 v[64:65], v37 offset0:243 offset1:251
	ds_read2_b32 v[66:67], v59 offset0:52 offset1:60
	ds_read2_b32 v[68:69], v59 offset0:117 offset1:125
	ds_read2_b32 v[70:71], v59 offset0:182 offset1:190
	ds_read2_b32 v[76:77], v59 offset0:247 offset1:255
	v_lshl_add_u64 v[52:53], v[72:73], 0, v[52:53]
	global_store_dwordx4 v[52:53], v[48:51], off nt
	v_add_u32_e32 v52, 48, v74
	v_ashrrev_i32_e32 v53, 31, v52
	v_lshlrev_b64 v[52:53], 12, v[52:53]
	s_waitcnt lgkmcnt(6)
	v_cvt_pk_bf16_f32 v48, v54, v60
	s_waitcnt lgkmcnt(4)
	v_cvt_pk_bf16_f32 v49, v62, v64
	s_waitcnt lgkmcnt(2)
	v_cvt_pk_bf16_f32 v50, v66, v68
	s_waitcnt lgkmcnt(0)
	v_cvt_pk_bf16_f32 v51, v70, v76
	v_lshl_add_u64 v[52:53], v[72:73], 0, v[52:53]
	global_store_dwordx4 v[52:53], v[48:51], off nt
	v_add_u32_e32 v52, 56, v74
	v_ashrrev_i32_e32 v53, 31, v52
	v_lshlrev_b64 v[52:53], 12, v[52:53]
	v_cvt_pk_bf16_f32 v48, v55, v61
	v_cvt_pk_bf16_f32 v49, v63, v65
	v_cvt_pk_bf16_f32 v50, v67, v69
	v_cvt_pk_bf16_f32 v51, v71, v77
	v_lshl_add_u64 v[52:53], v[72:73], 0, v[52:53]
	global_store_dwordx4 v[52:53], v[48:51], off nt
	s_waitcnt lgkmcnt(0)
	s_branch .LBB0_558
